# c17 + duplicate s_waitcnt lgkmcnt(0) removed at the head of each GEMM MMA segment (one fewer issue slot between barrier release and first MFMA)
# speedup vs baseline: 1.0097x; 1.0063x over previous
.LBB0_42:
	s_add_u32 s82, s80, 0xfffc0080
	s_addc_u32 s83, s81, -1
	s_add_i32 s94, 0, 0x10000
	v_add_u32_e32 v0, s94, v189
	ds_read_b128 v[122:125], v0
	ds_read_b128 v[126:129], v0 offset:1024
	ds_read_b128 v[130:133], v0 offset:2048
	ds_read_b128 v[134:137], v0 offset:3072
	s_cmp_eq_u32 s93, 12
	s_cselect_b32 s85, s11, s83
	s_cselect_b32 s84, s89, s82
	s_cselect_b32 s83, s9, s92
	s_cselect_b32 s82, s90, s91
	v_lshl_add_u64 v[186:187], s[80:81], 0, v[184:185]
	s_add_i32 m0, s59, 0xc000
	ds_read_b128 v[146:149], v193
	ds_read_b128 v[150:153], v193 offset:1024
	ds_read_b128 v[154:157], v193 offset:2048
	ds_read_b128 v[158:161], v193 offset:3072
	ds_read_b128 v[162:165], v193 offset:4096
	ds_read_b128 v[166:169], v193 offset:5120
	ds_read_b128 v[170:173], v193 offset:6144
	ds_read_b128 v[174:177], v193 offset:7168
	global_load_lds_dwordx4 v[186:187], off
	v_lshl_add_u64 v[186:187], s[80:81], 0, v[182:183]
	s_add_i32 m0, s59, 0xe000
	s_nop 0
	global_load_lds_dwordx4 v[186:187], off
	s_waitcnt lgkmcnt(8)
	s_barrier
	s_waitcnt lgkmcnt(0)
	s_setprio 1
	v_mfma_f32_16x16x32_bf16 v[142:145], v[122:125], v[146:149], v[142:145]
	v_mfma_f32_16x16x32_bf16 v[138:141], v[130:133], v[146:149], v[138:141]
	v_mfma_f32_16x16x32_bf16 v[110:113], v[122:125], v[154:157], v[110:113]
	v_mfma_f32_16x16x32_bf16 v[106:109], v[130:133], v[154:157], v[106:109]
	v_mfma_f32_16x16x32_bf16 v[94:97], v[122:125], v[162:165], v[94:97]
	v_mfma_f32_16x16x32_bf16 v[90:93], v[130:133], v[162:165], v[90:93]
	v_mfma_f32_16x16x32_bf16 v[78:81], v[122:125], v[170:173], v[78:81]
	v_mfma_f32_16x16x32_bf16 v[74:77], v[130:133], v[170:173], v[74:77]
	v_mfma_f32_16x16x32_bf16 v[142:145], v[126:129], v[150:153], v[142:145]
	v_mfma_f32_16x16x32_bf16 v[138:141], v[134:137], v[150:153], v[138:141]
	v_mfma_f32_16x16x32_bf16 v[110:113], v[126:129], v[158:161], v[110:113]
	v_mfma_f32_16x16x32_bf16 v[106:109], v[134:137], v[158:161], v[106:109]
	v_mfma_f32_16x16x32_bf16 v[94:97], v[126:129], v[166:169], v[94:97]
	v_mfma_f32_16x16x32_bf16 v[90:93], v[134:137], v[166:169], v[90:93]
	v_mfma_f32_16x16x32_bf16 v[78:81], v[126:129], v[174:177], v[78:81]
	v_mfma_f32_16x16x32_bf16 v[74:77], v[134:137], v[174:177], v[74:77]
	s_setprio 0
	s_barrier
	s_add_i32 s96, 0, 0x14000
	s_add_i32 s94, s94, s46
	v_add_u32_e32 v0, s96, v189
	v_lshl_add_u64 v[186:187], s[82:83], 0, v[180:181]
	s_mov_b32 m0, s94
	ds_read_b128 v[194:197], v0
	ds_read_b128 v[198:201], v0 offset:1024
	ds_read_b128 v[202:205], v0 offset:2048
	ds_read_b128 v[206:209], v0 offset:3072
	global_load_lds_dwordx4 v[186:187], off
	v_lshl_add_u64 v[210:211], s[82:83], 0, v[178:179]
	s_add_i32 m0, s94, 0x2000
	s_nop 0
	global_load_lds_dwordx4 v[210:211], off
	s_barrier
	s_waitcnt lgkmcnt(0)
	s_setprio 1
	v_mfma_f32_16x16x32_bf16 v[118:121], v[194:197], v[146:149], v[118:121]
	v_mfma_f32_16x16x32_bf16 v[114:117], v[202:205], v[146:149], v[114:117]
	v_mfma_f32_16x16x32_bf16 v[102:105], v[194:197], v[154:157], v[102:105]
	v_mfma_f32_16x16x32_bf16 v[98:101], v[202:205], v[154:157], v[98:101]
	v_mfma_f32_16x16x32_bf16 v[86:89], v[194:197], v[162:165], v[86:89]
	v_mfma_f32_16x16x32_bf16 v[82:85], v[202:205], v[162:165], v[82:85]
	v_mfma_f32_16x16x32_bf16 v[70:73], v[194:197], v[170:173], v[70:73]
	v_mfma_f32_16x16x32_bf16 v[66:69], v[202:205], v[170:173], v[66:69]
	v_mfma_f32_16x16x32_bf16 v[118:121], v[198:201], v[150:153], v[118:121]
	v_mfma_f32_16x16x32_bf16 v[114:117], v[206:209], v[150:153], v[114:117]
	v_mfma_f32_16x16x32_bf16 v[102:105], v[198:201], v[158:161], v[102:105]
	v_mfma_f32_16x16x32_bf16 v[98:101], v[206:209], v[158:161], v[98:101]
	v_mfma_f32_16x16x32_bf16 v[86:89], v[198:201], v[166:169], v[86:89]
	v_mfma_f32_16x16x32_bf16 v[82:85], v[206:209], v[166:169], v[82:85]
	v_mfma_f32_16x16x32_bf16 v[70:73], v[198:201], v[174:177], v[70:73]
	v_mfma_f32_16x16x32_bf16 v[66:69], v[206:209], v[174:177], v[66:69]
	s_setprio 0
	s_mov_b32 m0, s59
	v_lshl_add_u64 v[212:213], s[84:85], 0, v[180:181]
	s_barrier
	ds_read_b128 v[146:149], v193 offset:16384
	ds_read_b128 v[150:153], v193 offset:17408
	ds_read_b128 v[154:157], v193 offset:18432
	ds_read_b128 v[158:161], v193 offset:19456
	ds_read_b128 v[162:165], v193 offset:20480
	ds_read_b128 v[166:169], v193 offset:21504
	ds_read_b128 v[170:173], v193 offset:22528
	ds_read_b128 v[174:177], v193 offset:23552
	global_load_lds_dwordx4 v[212:213], off
	v_lshl_add_u64 v[214:215], s[84:85], 0, v[178:179]
	s_mov_b32 m0, s60
	s_nop 0
	global_load_lds_dwordx4 v[214:215], off
	s_barrier
	s_waitcnt lgkmcnt(0)
	s_setprio 1
	v_mfma_f32_16x16x32_bf16 v[62:65], v[122:125], v[146:149], v[62:65]
	v_mfma_f32_16x16x32_bf16 v[58:61], v[130:133], v[146:149], v[58:61]
	v_mfma_f32_16x16x32_bf16 v[46:49], v[122:125], v[154:157], v[46:49]
	v_mfma_f32_16x16x32_bf16 v[42:45], v[130:133], v[154:157], v[42:45]
	v_mfma_f32_16x16x32_bf16 v[30:33], v[122:125], v[162:165], v[30:33]
	v_mfma_f32_16x16x32_bf16 v[26:29], v[130:133], v[162:165], v[26:29]
	v_mfma_f32_16x16x32_bf16 v[14:17], v[122:125], v[170:173], v[14:17]
	v_mfma_f32_16x16x32_bf16 v[10:13], v[130:133], v[170:173], v[10:13]
	v_mfma_f32_16x16x32_bf16 v[62:65], v[126:129], v[150:153], v[62:65]
	v_mfma_f32_16x16x32_bf16 v[58:61], v[134:137], v[150:153], v[58:61]
	v_mfma_f32_16x16x32_bf16 v[46:49], v[126:129], v[158:161], v[46:49]
	v_mfma_f32_16x16x32_bf16 v[42:45], v[134:137], v[158:161], v[42:45]
	v_mfma_f32_16x16x32_bf16 v[30:33], v[126:129], v[166:169], v[30:33]
	v_mfma_f32_16x16x32_bf16 v[26:29], v[134:137], v[166:169], v[26:29]
	v_mfma_f32_16x16x32_bf16 v[14:17], v[126:129], v[174:177], v[14:17]
	v_mfma_f32_16x16x32_bf16 v[10:13], v[134:137], v[174:177], v[10:13]
	s_setprio 0
	s_barrier
	s_add_u32 s94, s82, 0x40000
	s_addc_u32 s95, s83, 0
	s_add_i32 s96, s96, s46
	v_lshl_add_u64 v[122:123], s[94:95], 0, v[180:181]
	s_mov_b32 m0, s96
	s_nop 0
	global_load_lds_dwordx4 v[122:123], off
	v_lshl_add_u64 v[122:123], s[94:95], 0, v[178:179]
	s_add_i32 m0, s96, 0x2000
	s_nop 0
	global_load_lds_dwordx4 v[122:123], off
	s_waitcnt vmcnt(6)
	s_barrier
	s_setprio 1
	v_mfma_f32_16x16x32_bf16 v[54:57], v[194:197], v[146:149], v[54:57]
	v_mfma_f32_16x16x32_bf16 v[50:53], v[202:205], v[146:149], v[50:53]
	v_mfma_f32_16x16x32_bf16 v[38:41], v[194:197], v[154:157], v[38:41]
	v_mfma_f32_16x16x32_bf16 v[34:37], v[202:205], v[154:157], v[34:37]
	v_mfma_f32_16x16x32_bf16 v[22:25], v[194:197], v[162:165], v[22:25]
	v_mfma_f32_16x16x32_bf16 v[18:21], v[202:205], v[162:165], v[18:21]
	v_mfma_f32_16x16x32_bf16 v[6:9], v[194:197], v[170:173], v[6:9]
	v_mfma_f32_16x16x32_bf16 v[2:5], v[202:205], v[170:173], v[2:5]
	v_mfma_f32_16x16x32_bf16 v[54:57], v[198:201], v[150:153], v[54:57]
	v_mfma_f32_16x16x32_bf16 v[50:53], v[206:209], v[150:153], v[50:53]
	v_mfma_f32_16x16x32_bf16 v[38:41], v[198:201], v[158:161], v[38:41]
	v_mfma_f32_16x16x32_bf16 v[34:37], v[206:209], v[158:161], v[34:37]
	v_mfma_f32_16x16x32_bf16 v[22:25], v[198:201], v[166:169], v[22:25]
	v_mfma_f32_16x16x32_bf16 v[18:21], v[206:209], v[166:169], v[18:21]
	v_mfma_f32_16x16x32_bf16 v[6:9], v[198:201], v[174:177], v[6:9]
	v_mfma_f32_16x16x32_bf16 v[2:5], v[206:209], v[174:177], v[2:5]
	s_setprio 0
	s_add_i32 s94, 0, 0x18000
	v_add_u32_e32 v0, s94, v189
	s_barrier
	ds_read_b128 v[122:125], v0
	ds_read_b128 v[126:129], v0 offset:1024
	ds_read_b128 v[130:133], v0 offset:2048
	ds_read_b128 v[134:137], v0 offset:3072
	s_add_u32 s84, s84, 0x40000
	s_addc_u32 s85, s85, 0
	s_mov_b32 m0, s61
	v_lshl_add_u64 v[194:195], s[84:85], 0, v[180:181]
	ds_read_b128 v[146:149], v193 offset:32768
	ds_read_b128 v[150:153], v193 offset:33792
	ds_read_b128 v[154:157], v193 offset:34816
	ds_read_b128 v[158:161], v193 offset:35840
	ds_read_b128 v[162:165], v193 offset:36864
	ds_read_b128 v[166:169], v193 offset:37888
	ds_read_b128 v[170:173], v193 offset:38912
	ds_read_b128 v[174:177], v193 offset:39936
	global_load_lds_dwordx4 v[194:195], off
	v_lshl_add_u64 v[194:195], s[84:85], 0, v[178:179]
	s_mov_b32 m0, s76
	s_nop 0
	global_load_lds_dwordx4 v[194:195], off
	s_waitcnt lgkmcnt(8)
	s_barrier
	s_waitcnt lgkmcnt(0)
	s_setprio 1
	v_mfma_f32_16x16x32_bf16 v[142:145], v[122:125], v[146:149], v[142:145]
	v_mfma_f32_16x16x32_bf16 v[138:141], v[130:133], v[146:149], v[138:141]
	v_mfma_f32_16x16x32_bf16 v[110:113], v[122:125], v[154:157], v[110:113]
	v_mfma_f32_16x16x32_bf16 v[106:109], v[130:133], v[154:157], v[106:109]
	v_mfma_f32_16x16x32_bf16 v[94:97], v[122:125], v[162:165], v[94:97]
	v_mfma_f32_16x16x32_bf16 v[90:93], v[130:133], v[162:165], v[90:93]
	v_mfma_f32_16x16x32_bf16 v[78:81], v[122:125], v[170:173], v[78:81]
	v_mfma_f32_16x16x32_bf16 v[74:77], v[130:133], v[170:173], v[74:77]
	v_mfma_f32_16x16x32_bf16 v[142:145], v[126:129], v[150:153], v[142:145]
	v_mfma_f32_16x16x32_bf16 v[138:141], v[134:137], v[150:153], v[138:141]
	v_mfma_f32_16x16x32_bf16 v[110:113], v[126:129], v[158:161], v[110:113]
	v_mfma_f32_16x16x32_bf16 v[106:109], v[134:137], v[158:161], v[106:109]
	v_mfma_f32_16x16x32_bf16 v[94:97], v[126:129], v[166:169], v[94:97]
	v_mfma_f32_16x16x32_bf16 v[90:93], v[134:137], v[166:169], v[90:93]
	v_mfma_f32_16x16x32_bf16 v[78:81], v[126:129], v[174:177], v[78:81]
	v_mfma_f32_16x16x32_bf16 v[74:77], v[134:137], v[174:177], v[74:77]
	s_setprio 0
	s_barrier
	s_add_i32 s84, 0, 0x1c000
	s_add_i32 s85, s94, s46
	v_add_u32_e32 v0, s84, v189
	v_lshl_add_u64 v[186:187], v[186:187], 0, s[48:49]
	s_mov_b32 m0, s85
	ds_read_b128 v[194:197], v0
	ds_read_b128 v[198:201], v0 offset:1024
	ds_read_b128 v[202:205], v0 offset:2048
	ds_read_b128 v[206:209], v0 offset:3072
	global_load_lds_dwordx4 v[186:187], off
	v_lshl_add_u64 v[186:187], v[210:211], 0, s[48:49]
	s_add_i32 m0, s85, 0x2000
	s_nop 0
	global_load_lds_dwordx4 v[186:187], off
	s_barrier
	s_waitcnt lgkmcnt(0)
	s_setprio 1
	v_mfma_f32_16x16x32_bf16 v[118:121], v[194:197], v[146:149], v[118:121]
	v_mfma_f32_16x16x32_bf16 v[114:117], v[202:205], v[146:149], v[114:117]
	v_mfma_f32_16x16x32_bf16 v[102:105], v[194:197], v[154:157], v[102:105]
	v_mfma_f32_16x16x32_bf16 v[98:101], v[202:205], v[154:157], v[98:101]
	v_mfma_f32_16x16x32_bf16 v[86:89], v[194:197], v[162:165], v[86:89]
	v_mfma_f32_16x16x32_bf16 v[82:85], v[202:205], v[162:165], v[82:85]
	v_mfma_f32_16x16x32_bf16 v[70:73], v[194:197], v[170:173], v[70:73]
	v_mfma_f32_16x16x32_bf16 v[66:69], v[202:205], v[170:173], v[66:69]
	v_mfma_f32_16x16x32_bf16 v[118:121], v[198:201], v[150:153], v[118:121]
	v_mfma_f32_16x16x32_bf16 v[114:117], v[206:209], v[150:153], v[114:117]
	v_mfma_f32_16x16x32_bf16 v[102:105], v[198:201], v[158:161], v[102:105]
	v_mfma_f32_16x16x32_bf16 v[98:101], v[206:209], v[158:161], v[98:101]
	v_mfma_f32_16x16x32_bf16 v[86:89], v[198:201], v[166:169], v[86:89]
	v_mfma_f32_16x16x32_bf16 v[82:85], v[206:209], v[166:169], v[82:85]
	v_mfma_f32_16x16x32_bf16 v[70:73], v[198:201], v[174:177], v[70:73]
	v_mfma_f32_16x16x32_bf16 v[66:69], v[206:209], v[174:177], v[66:69]
	s_setprio 0
	s_mov_b32 m0, s79
	v_lshl_add_u64 v[186:187], v[212:213], 0, s[48:49]
	s_barrier
	ds_read_b128 v[146:149], v193 offset:49152
	ds_read_b128 v[150:153], v193 offset:50176
	ds_read_b128 v[154:157], v193 offset:51200
	ds_read_b128 v[158:161], v193 offset:52224
	ds_read_b128 v[162:165], v193 offset:53248
	ds_read_b128 v[166:169], v193 offset:54272
	ds_read_b128 v[170:173], v193 offset:55296
	ds_read_b128 v[174:177], v193 offset:56320
	global_load_lds_dwordx4 v[186:187], off
	v_lshl_add_u64 v[186:187], v[214:215], 0, s[48:49]
	s_mov_b32 m0, s86
	s_nop 0
	global_load_lds_dwordx4 v[186:187], off
	s_barrier
; template <int CTRL> DEVI float dpp(float x) { return __builtin_bit_cast(float, __builtin_amdgcn_mov_dpp(__builtin_bit_cast(int, x), CTRL, 0xf, 0xf, true)); }
;     DEVI void operator()(AccRef acc, const pg8::Unit& u, int wr, int wc, int fr, int fq) const {
;         unsigned o = (unsigned)((u.pm * 256 + wr * 64 + fr) * DM + u.pn * 256 + wc * 32 + 4 * fq) * 4u;
;         const bool lo = fr < 8;
;         unsigned os = (unsigned)((u.pm * 256 + wr * 64 + (fr & 7)) * DM + u.pn * 256 + wc * 32 + 4 * fq) * 4u + (lo ? 0u : 64u);
; #pragma unroll
;         for (int ai = 0; ai < 2; ++ai) {
;             asm volatile("" : "+v"(o), "+v"(os));
;             f32x4 b[4][2][2];
; #pragma unroll
;             for (int m = 0; m < 4; ++m)
; #pragma unroll
;                 for (int bj = 0; bj < 2; ++bj)
; #pragma unroll
;                     for (int n = 0; n < 2; ++n) b[m][bj][n] = *(const f32x4*)((const char*)base + o + (unsigned)(m * 16 * DM * 4 + bj * 512 + n * 64));
; #pragma unroll
;             for (int m = 0; m < 4; ++m)
; #pragma unroll
;                 for (int bj = 0; bj < 2; ++bj) { const f32x4 d0 = b[m][bj][0] + alpha * acc[ai][bj][m][0], d1 = b[m][bj][1] + alpha * acc[ai][bj][m][1];
;                     f32x4 t0, t1;
; #pragma unroll
;                     for (int i = 0; i < 4; ++i) { t0[i] = dpp<0x128>(d0[i]); t1[i] = dpp<0x128>(d1[i]); }
;                     const f32x4 sa = lo ? d0 : t1, sb = lo ? t0 : d1;
;                     const unsigned oo = os + (unsigned)(m * 16 * DM * 4 + bj * 512);
;                     *(f32x4*)((char*)out + oo) = sa; *(f32x4*)((char*)out + oo + 8u * DM * 4u) = sb; }
;             o += 128u * DM * 4u; os += 128u * DM * 4u; }
;     }
	s_waitcnt lgkmcnt(0)
	s_setprio 1
	v_mfma_f32_16x16x32_bf16 v[62:65], v[122:125], v[146:149], v[62:65]
	v_mfma_f32_16x16x32_bf16 v[58:61], v[130:133], v[146:149], v[58:61]
	v_mfma_f32_16x16x32_bf16 v[46:49], v[122:125], v[154:157], v[46:49]
	v_mfma_f32_16x16x32_bf16 v[42:45], v[130:133], v[154:157], v[42:45]
	v_mfma_f32_16x16x32_bf16 v[30:33], v[122:125], v[162:165], v[30:33]
	v_mfma_f32_16x16x32_bf16 v[26:29], v[130:133], v[162:165], v[26:29]
	v_mfma_f32_16x16x32_bf16 v[14:17], v[122:125], v[170:173], v[14:17]
	v_mfma_f32_16x16x32_bf16 v[10:13], v[130:133], v[170:173], v[10:13]
	v_mfma_f32_16x16x32_bf16 v[62:65], v[126:129], v[150:153], v[62:65]
	v_mfma_f32_16x16x32_bf16 v[58:61], v[134:137], v[150:153], v[58:61]
	v_mfma_f32_16x16x32_bf16 v[46:49], v[126:129], v[158:161], v[46:49]
	v_mfma_f32_16x16x32_bf16 v[42:45], v[134:137], v[158:161], v[42:45]
	v_mfma_f32_16x16x32_bf16 v[30:33], v[126:129], v[166:169], v[30:33]
	v_mfma_f32_16x16x32_bf16 v[26:29], v[134:137], v[166:169], v[26:29]
	v_mfma_f32_16x16x32_bf16 v[14:17], v[126:129], v[174:177], v[14:17]
	v_mfma_f32_16x16x32_bf16 v[10:13], v[134:137], v[174:177], v[10:13]
	s_setprio 0
	s_barrier
	s_add_u32 s82, s82, 0x40080
	s_addc_u32 s83, s83, 0
	s_add_i32 s84, s84, s46
	v_lshl_add_u64 v[122:123], s[82:83], 0, v[180:181]
	s_mov_b32 m0, s84
	s_nop 0
	global_load_lds_dwordx4 v[122:123], off
	v_lshl_add_u64 v[122:123], s[82:83], 0, v[178:179]
	s_add_i32 m0, s84, 0x2000
	s_nop 0
	global_load_lds_dwordx4 v[122:123], off
	s_waitcnt vmcnt(6)
	s_barrier
	s_setprio 1
	v_mfma_f32_16x16x32_bf16 v[54:57], v[194:197], v[146:149], v[54:57]
	v_mfma_f32_16x16x32_bf16 v[50:53], v[202:205], v[146:149], v[50:53]
	v_mfma_f32_16x16x32_bf16 v[38:41], v[194:197], v[154:157], v[38:41]
	v_mfma_f32_16x16x32_bf16 v[34:37], v[202:205], v[154:157], v[34:37]
	v_mfma_f32_16x16x32_bf16 v[22:25], v[194:197], v[162:165], v[22:25]
	v_mfma_f32_16x16x32_bf16 v[18:21], v[202:205], v[162:165], v[18:21]
	v_mfma_f32_16x16x32_bf16 v[6:9], v[194:197], v[170:173], v[6:9]
	v_mfma_f32_16x16x32_bf16 v[2:5], v[202:205], v[170:173], v[2:5]
	v_mfma_f32_16x16x32_bf16 v[54:57], v[198:201], v[150:153], v[54:57]
	v_mfma_f32_16x16x32_bf16 v[50:53], v[206:209], v[150:153], v[50:53]
	v_mfma_f32_16x16x32_bf16 v[38:41], v[198:201], v[158:161], v[38:41]
	v_mfma_f32_16x16x32_bf16 v[34:37], v[206:209], v[158:161], v[34:37]
	v_mfma_f32_16x16x32_bf16 v[22:25], v[198:201], v[166:169], v[22:25]
	v_mfma_f32_16x16x32_bf16 v[18:21], v[206:209], v[166:169], v[18:21]
	v_mfma_f32_16x16x32_bf16 v[6:9], v[198:201], v[174:177], v[6:9]
	v_mfma_f32_16x16x32_bf16 v[2:5], v[206:209], v[174:177], v[2:5]
	s_setprio 0
	s_add_i32 s93, s93, 2
	s_add_u32 s91, s91, 0x100
	s_addc_u32 s92, s92, 0
	s_add_u32 s80, s80, 0x100
	s_addc_u32 s81, s81, 0
	s_cmp_gt_u32 s93, 13
	s_barrier
	s_cbranch_scc0 .LBB0_42
	s_lshl_b32 s9, s78, 8
	s_add_i32 s9, s9, s77
	v_or_b32_e32 v0, s9, v188
	s_lshl_b32 s11, s88, 8
	v_or_b32_e32 v122, s9, v190
	v_lshl_add_u32 v0, v0, 10, s11
	v_lshl_add_u32 v122, v122, 10, s11
	v_or_b32_e32 v0, v0, v192
	v_or_b32_e32 v122, v122, v192
	v_lshlrev_b32_e32 v0, 2, v0
	v_lshl_or_b32 v186, v122, 2, v191
	s_mov_b32 s88, s8
	s_mov_b32 s78, s10
	s_mov_b64 s[80:81], s[24:25]
	s_mov_b64 s[82:83], s[22:23]
	v_add_u32_e32 v187, 0x8000, v186
	s_add_u32 s98, s28, 0x0
	s_addc_u32 s99, s29, 0
	global_load_dwordx4 v[194:197], v0, s[98:99]
	global_load_dwordx4 v[198:201], v0, s[98:99] offset:64
	global_load_dwordx4 v[202:205], v0, s[98:99] offset:512
	global_load_dwordx4 v[206:209], v0, s[98:99] offset:576
	s_add_u32 s98, s28, 0x10000
	s_addc_u32 s99, s29, 0
	global_load_dwordx4 v[174:177], v0, s[98:99]
	global_load_dwordx4 v[170:173], v0, s[98:99] offset:64
	global_load_dwordx4 v[166:169], v0, s[98:99] offset:512
	global_load_dwordx4 v[162:165], v0, s[98:99] offset:576
	s_add_u32 s98, s28, 0x20000
	s_addc_u32 s99, s29, 0
	global_load_dwordx4 v[158:161], v0, s[98:99]
	global_load_dwordx4 v[154:157], v0, s[98:99] offset:64
	global_load_dwordx4 v[150:153], v0, s[98:99] offset:512
	global_load_dwordx4 v[146:149], v0, s[98:99] offset:576
	s_add_u32 s98, s28, 0x30000
	s_addc_u32 s99, s29, 0
	global_load_dwordx4 v[134:137], v0, s[98:99]
	global_load_dwordx4 v[130:133], v0, s[98:99] offset:64
	global_load_dwordx4 v[126:129], v0, s[98:99] offset:512
	global_load_dwordx4 v[122:125], v0, s[98:99] offset:576
	s_waitcnt vmcnt(12)
	v_pk_add_f32 v[142:143], v[142:143], v[194:195]
	v_pk_add_f32 v[144:145], v[144:145], v[196:197]
	v_pk_add_f32 v[138:139], v[138:139], v[198:199]
	v_pk_add_f32 v[140:141], v[140:141], v[200:201]
	v_pk_add_f32 v[118:119], v[118:119], v[202:203]
	v_pk_add_f32 v[120:121], v[120:121], v[204:205]
	v_pk_add_f32 v[114:115], v[114:115], v[206:207]
	v_pk_add_f32 v[116:117], v[116:117], v[208:209]
	s_mov_b64 vcc, s[4:5]
	v_cndmask_b32_dpp v194, v138, v142, vcc row_ror:8 row_mask:0xf bank_mask:0xf bound_ctrl:1
	v_cndmask_b32_dpp v195, v139, v143, vcc row_ror:8 row_mask:0xf bank_mask:0xf bound_ctrl:1
	v_cndmask_b32_dpp v196, v140, v144, vcc row_ror:8 row_mask:0xf bank_mask:0xf bound_ctrl:1
	v_cndmask_b32_dpp v197, v141, v145, vcc row_ror:8 row_mask:0xf bank_mask:0xf bound_ctrl:1
	v_cndmask_b32_dpp v202, v114, v118, vcc row_ror:8 row_mask:0xf bank_mask:0xf bound_ctrl:1
	v_cndmask_b32_dpp v203, v115, v119, vcc row_ror:8 row_mask:0xf bank_mask:0xf bound_ctrl:1
	v_cndmask_b32_dpp v204, v116, v120, vcc row_ror:8 row_mask:0xf bank_mask:0xf bound_ctrl:1
	v_cndmask_b32_dpp v205, v117, v121, vcc row_ror:8 row_mask:0xf bank_mask:0xf bound_ctrl:1
	s_not_b64 vcc, s[4:5]
	v_cndmask_b32_dpp v198, v142, v138, vcc row_ror:8 row_mask:0xf bank_mask:0xf bound_ctrl:1
	v_cndmask_b32_dpp v199, v143, v139, vcc row_ror:8 row_mask:0xf bank_mask:0xf bound_ctrl:1
	v_cndmask_b32_dpp v200, v144, v140, vcc row_ror:8 row_mask:0xf bank_mask:0xf bound_ctrl:1
	v_cndmask_b32_dpp v201, v145, v141, vcc row_ror:8 row_mask:0xf bank_mask:0xf bound_ctrl:1
	v_cndmask_b32_dpp v206, v118, v114, vcc row_ror:8 row_mask:0xf bank_mask:0xf bound_ctrl:1
	v_cndmask_b32_dpp v207, v119, v115, vcc row_ror:8 row_mask:0xf bank_mask:0xf bound_ctrl:1
	v_cndmask_b32_dpp v208, v120, v116, vcc row_ror:8 row_mask:0xf bank_mask:0xf bound_ctrl:1
	v_cndmask_b32_dpp v209, v121, v117, vcc row_ror:8 row_mask:0xf bank_mask:0xf bound_ctrl:1
	s_add_u32 s100, s28, 0x0
	s_addc_u32 s101, s29, 0
	global_store_dwordx4 v186, v[194:197], s[100:101]
	global_store_dwordx4 v187, v[198:201], s[100:101]
	global_store_dwordx4 v186, v[202:205], s[100:101] offset:512
	global_store_dwordx4 v187, v[206:209], s[100:101] offset:512
	s_add_u32 s98, s28, 0x80000
	s_addc_u32 s99, s29, 0
	global_load_dwordx4 v[142:145], v0, s[98:99]
	global_load_dwordx4 v[138:141], v0, s[98:99] offset:64
	global_load_dwordx4 v[118:121], v0, s[98:99] offset:512
	global_load_dwordx4 v[114:117], v0, s[98:99] offset:576
	s_waitcnt vmcnt(16)
; template <int CTRL> DEVI float dpp(float x) { return __builtin_bit_cast(float, __builtin_amdgcn_mov_dpp(__builtin_bit_cast(int, x), CTRL, 0xf, 0xf, true)); }
;     DEVI void operator()(AccRef acc, const pg8::Unit& u, int wr, int wc, int fr, int fq) const {
;     ...
;                     for (int n = 0; n < 2; ++n) b[m][bj][n] = *(const f32x4*)((const char*)base + o + (unsigned)(m * 16 * DM * 4 + bj * 512 + n * 64));
; #pragma unroll
;             for (int m = 0; m < 4; ++m)
; #pragma unroll
;                 for (int bj = 0; bj < 2; ++bj) { const f32x4 d0 = b[m][bj][0] + alpha * acc[ai][bj][m][0], d1 = b[m][bj][1] + alpha * acc[ai][bj][m][1];
;                     f32x4 t0, t1;
; #pragma unroll
;                     for (int i = 0; i < 4; ++i) { t0[i] = dpp<0x128>(d0[i]); t1[i] = dpp<0x128>(d1[i]); }
;                     const f32x4 sa = lo ? d0 : t1, sb = lo ? t0 : d1;
;                     const unsigned oo = os + (unsigned)(m * 16 * DM * 4 + bj * 512);
;                     *(f32x4*)((char*)out + oo) = sa; *(f32x4*)((char*)out + oo + 8u * DM * 4u) = sb; }
;             o += 128u * DM * 4u; os += 128u * DM * 4u; }
	v_pk_add_f32 v[110:111], v[110:111], v[174:175]
	v_pk_add_f32 v[112:113], v[112:113], v[176:177]
	v_pk_add_f32 v[106:107], v[106:107], v[170:171]
	v_pk_add_f32 v[108:109], v[108:109], v[172:173]
	v_pk_add_f32 v[102:103], v[102:103], v[166:167]
	v_pk_add_f32 v[104:105], v[104:105], v[168:169]
	v_pk_add_f32 v[98:99], v[98:99], v[162:163]
	v_pk_add_f32 v[100:101], v[100:101], v[164:165]
	s_mov_b64 vcc, s[4:5]
	v_cndmask_b32_dpp v174, v106, v110, vcc row_ror:8 row_mask:0xf bank_mask:0xf bound_ctrl:1
	v_cndmask_b32_dpp v175, v107, v111, vcc row_ror:8 row_mask:0xf bank_mask:0xf bound_ctrl:1
	v_cndmask_b32_dpp v176, v108, v112, vcc row_ror:8 row_mask:0xf bank_mask:0xf bound_ctrl:1
	v_cndmask_b32_dpp v177, v109, v113, vcc row_ror:8 row_mask:0xf bank_mask:0xf bound_ctrl:1
	v_cndmask_b32_dpp v166, v98, v102, vcc row_ror:8 row_mask:0xf bank_mask:0xf bound_ctrl:1
	v_cndmask_b32_dpp v167, v99, v103, vcc row_ror:8 row_mask:0xf bank_mask:0xf bound_ctrl:1
	v_cndmask_b32_dpp v168, v100, v104, vcc row_ror:8 row_mask:0xf bank_mask:0xf bound_ctrl:1
	v_cndmask_b32_dpp v169, v101, v105, vcc row_ror:8 row_mask:0xf bank_mask:0xf bound_ctrl:1
	s_not_b64 vcc, s[4:5]
	v_cndmask_b32_dpp v170, v110, v106, vcc row_ror:8 row_mask:0xf bank_mask:0xf bound_ctrl:1
	v_cndmask_b32_dpp v171, v111, v107, vcc row_ror:8 row_mask:0xf bank_mask:0xf bound_ctrl:1
	v_cndmask_b32_dpp v172, v112, v108, vcc row_ror:8 row_mask:0xf bank_mask:0xf bound_ctrl:1
	v_cndmask_b32_dpp v173, v113, v109, vcc row_ror:8 row_mask:0xf bank_mask:0xf bound_ctrl:1
	v_cndmask_b32_dpp v162, v102, v98, vcc row_ror:8 row_mask:0xf bank_mask:0xf bound_ctrl:1
	v_cndmask_b32_dpp v163, v103, v99, vcc row_ror:8 row_mask:0xf bank_mask:0xf bound_ctrl:1
	v_cndmask_b32_dpp v164, v104, v100, vcc row_ror:8 row_mask:0xf bank_mask:0xf bound_ctrl:1
	v_cndmask_b32_dpp v165, v105, v101, vcc row_ror:8 row_mask:0xf bank_mask:0xf bound_ctrl:1
	s_add_u32 s100, s28, 0x10000
	s_addc_u32 s101, s29, 0
	global_store_dwordx4 v186, v[174:177], s[100:101]
	global_store_dwordx4 v187, v[170:173], s[100:101]
	global_store_dwordx4 v186, v[166:169], s[100:101] offset:512
	global_store_dwordx4 v187, v[162:165], s[100:101] offset:512
	s_add_u32 s98, s28, 0x90000
	s_addc_u32 s99, s29, 0
	global_load_dwordx4 v[110:113], v0, s[98:99]
	global_load_dwordx4 v[106:109], v0, s[98:99] offset:64
	global_load_dwordx4 v[102:105], v0, s[98:99] offset:512
	global_load_dwordx4 v[98:101], v0, s[98:99] offset:576
	s_waitcnt vmcnt(20)
	v_pk_add_f32 v[94:95], v[94:95], v[158:159]
	v_pk_add_f32 v[96:97], v[96:97], v[160:161]
	v_pk_add_f32 v[90:91], v[90:91], v[154:155]
	v_pk_add_f32 v[92:93], v[92:93], v[156:157]
	v_pk_add_f32 v[86:87], v[86:87], v[150:151]
	v_pk_add_f32 v[88:89], v[88:89], v[152:153]
	v_pk_add_f32 v[82:83], v[82:83], v[146:147]
	v_pk_add_f32 v[84:85], v[84:85], v[148:149]
	s_mov_b64 vcc, s[4:5]
	v_cndmask_b32_dpp v158, v90, v94, vcc row_ror:8 row_mask:0xf bank_mask:0xf bound_ctrl:1
	v_cndmask_b32_dpp v159, v91, v95, vcc row_ror:8 row_mask:0xf bank_mask:0xf bound_ctrl:1
	v_cndmask_b32_dpp v160, v92, v96, vcc row_ror:8 row_mask:0xf bank_mask:0xf bound_ctrl:1
	v_cndmask_b32_dpp v161, v93, v97, vcc row_ror:8 row_mask:0xf bank_mask:0xf bound_ctrl:1
	v_cndmask_b32_dpp v150, v82, v86, vcc row_ror:8 row_mask:0xf bank_mask:0xf bound_ctrl:1
	v_cndmask_b32_dpp v151, v83, v87, vcc row_ror:8 row_mask:0xf bank_mask:0xf bound_ctrl:1
	v_cndmask_b32_dpp v152, v84, v88, vcc row_ror:8 row_mask:0xf bank_mask:0xf bound_ctrl:1
	v_cndmask_b32_dpp v153, v85, v89, vcc row_ror:8 row_mask:0xf bank_mask:0xf bound_ctrl:1
	s_not_b64 vcc, s[4:5]
	v_cndmask_b32_dpp v154, v94, v90, vcc row_ror:8 row_mask:0xf bank_mask:0xf bound_ctrl:1
	v_cndmask_b32_dpp v155, v95, v91, vcc row_ror:8 row_mask:0xf bank_mask:0xf bound_ctrl:1
	v_cndmask_b32_dpp v156, v96, v92, vcc row_ror:8 row_mask:0xf bank_mask:0xf bound_ctrl:1
	v_cndmask_b32_dpp v157, v97, v93, vcc row_ror:8 row_mask:0xf bank_mask:0xf bound_ctrl:1
	v_cndmask_b32_dpp v146, v86, v82, vcc row_ror:8 row_mask:0xf bank_mask:0xf bound_ctrl:1
	v_cndmask_b32_dpp v147, v87, v83, vcc row_ror:8 row_mask:0xf bank_mask:0xf bound_ctrl:1
	v_cndmask_b32_dpp v148, v88, v84, vcc row_ror:8 row_mask:0xf bank_mask:0xf bound_ctrl:1
	v_cndmask_b32_dpp v149, v89, v85, vcc row_ror:8 row_mask:0xf bank_mask:0xf bound_ctrl:1
	s_add_u32 s100, s28, 0x20000
	s_addc_u32 s101, s29, 0
	global_store_dwordx4 v186, v[158:161], s[100:101]
	global_store_dwordx4 v187, v[154:157], s[100:101]
	global_store_dwordx4 v186, v[150:153], s[100:101] offset:512
	global_store_dwordx4 v187, v[146:149], s[100:101] offset:512
	s_add_u32 s98, s28, 0xa0000
	s_addc_u32 s99, s29, 0
	global_load_dwordx4 v[94:97], v0, s[98:99]
	global_load_dwordx4 v[90:93], v0, s[98:99] offset:64
	global_load_dwordx4 v[86:89], v0, s[98:99] offset:512
	global_load_dwordx4 v[82:85], v0, s[98:99] offset:576
	s_waitcnt vmcnt(24)
; template <int CTRL> DEVI float dpp(float x) { return __builtin_bit_cast(float, __builtin_amdgcn_mov_dpp(__builtin_bit_cast(int, x), CTRL, 0xf, 0xf, true)); }
;     DEVI void operator()(AccRef acc, const pg8::Unit& u, int wr, int wc, int fr, int fq) const {
;     ...
;                     for (int n = 0; n < 2; ++n) b[m][bj][n] = *(const f32x4*)((const char*)base + o + (unsigned)(m * 16 * DM * 4 + bj * 512 + n * 64));
; #pragma unroll
;             for (int m = 0; m < 4; ++m)
; #pragma unroll
;                 for (int bj = 0; bj < 2; ++bj) { const f32x4 d0 = b[m][bj][0] + alpha * acc[ai][bj][m][0], d1 = b[m][bj][1] + alpha * acc[ai][bj][m][1];
;                     f32x4 t0, t1;
; #pragma unroll
;                     for (int i = 0; i < 4; ++i) { t0[i] = dpp<0x128>(d0[i]); t1[i] = dpp<0x128>(d1[i]); }
;                     const f32x4 sa = lo ? d0 : t1, sb = lo ? t0 : d1;
;                     const unsigned oo = os + (unsigned)(m * 16 * DM * 4 + bj * 512);
;                     *(f32x4*)((char*)out + oo) = sa; *(f32x4*)((char*)out + oo + 8u * DM * 4u) = sb; }
;             o += 128u * DM * 4u; os += 128u * DM * 4u; }
	v_pk_add_f32 v[78:79], v[78:79], v[134:135]
	v_pk_add_f32 v[80:81], v[80:81], v[136:137]
	v_pk_add_f32 v[74:75], v[74:75], v[130:131]
	v_pk_add_f32 v[76:77], v[76:77], v[132:133]
	v_pk_add_f32 v[70:71], v[70:71], v[126:127]
	v_pk_add_f32 v[72:73], v[72:73], v[128:129]
	v_pk_add_f32 v[66:67], v[66:67], v[122:123]
	v_pk_add_f32 v[68:69], v[68:69], v[124:125]
	s_mov_b64 vcc, s[4:5]
	v_cndmask_b32_dpp v134, v74, v78, vcc row_ror:8 row_mask:0xf bank_mask:0xf bound_ctrl:1
	v_cndmask_b32_dpp v135, v75, v79, vcc row_ror:8 row_mask:0xf bank_mask:0xf bound_ctrl:1
	v_cndmask_b32_dpp v136, v76, v80, vcc row_ror:8 row_mask:0xf bank_mask:0xf bound_ctrl:1
	v_cndmask_b32_dpp v137, v77, v81, vcc row_ror:8 row_mask:0xf bank_mask:0xf bound_ctrl:1
	v_cndmask_b32_dpp v126, v66, v70, vcc row_ror:8 row_mask:0xf bank_mask:0xf bound_ctrl:1
	v_cndmask_b32_dpp v127, v67, v71, vcc row_ror:8 row_mask:0xf bank_mask:0xf bound_ctrl:1
	v_cndmask_b32_dpp v128, v68, v72, vcc row_ror:8 row_mask:0xf bank_mask:0xf bound_ctrl:1
	v_cndmask_b32_dpp v129, v69, v73, vcc row_ror:8 row_mask:0xf bank_mask:0xf bound_ctrl:1
	s_not_b64 vcc, s[4:5]
	v_cndmask_b32_dpp v130, v78, v74, vcc row_ror:8 row_mask:0xf bank_mask:0xf bound_ctrl:1
	v_cndmask_b32_dpp v131, v79, v75, vcc row_ror:8 row_mask:0xf bank_mask:0xf bound_ctrl:1
	v_cndmask_b32_dpp v132, v80, v76, vcc row_ror:8 row_mask:0xf bank_mask:0xf bound_ctrl:1
	v_cndmask_b32_dpp v133, v81, v77, vcc row_ror:8 row_mask:0xf bank_mask:0xf bound_ctrl:1
	v_cndmask_b32_dpp v122, v70, v66, vcc row_ror:8 row_mask:0xf bank_mask:0xf bound_ctrl:1
	v_cndmask_b32_dpp v123, v71, v67, vcc row_ror:8 row_mask:0xf bank_mask:0xf bound_ctrl:1
	v_cndmask_b32_dpp v124, v72, v68, vcc row_ror:8 row_mask:0xf bank_mask:0xf bound_ctrl:1
	v_cndmask_b32_dpp v125, v73, v69, vcc row_ror:8 row_mask:0xf bank_mask:0xf bound_ctrl:1
	s_add_u32 s100, s28, 0x30000
	s_addc_u32 s101, s29, 0
	global_store_dwordx4 v186, v[134:137], s[100:101]
	global_store_dwordx4 v187, v[130:133], s[100:101]
	global_store_dwordx4 v186, v[126:129], s[100:101] offset:512
	global_store_dwordx4 v187, v[122:125], s[100:101] offset:512
	s_add_u32 s98, s28, 0xb0000
	s_addc_u32 s99, s29, 0
	global_load_dwordx4 v[78:81], v0, s[98:99]
	global_load_dwordx4 v[74:77], v0, s[98:99] offset:64
	global_load_dwordx4 v[70:73], v0, s[98:99] offset:512
	global_load_dwordx4 v[66:69], v0, s[98:99] offset:576
	s_waitcnt vmcnt(24)
	v_pk_add_f32 v[62:63], v[62:63], v[142:143]
	v_pk_add_f32 v[64:65], v[64:65], v[144:145]
	v_pk_add_f32 v[58:59], v[58:59], v[138:139]
	v_pk_add_f32 v[60:61], v[60:61], v[140:141]
	v_pk_add_f32 v[54:55], v[54:55], v[118:119]
	v_pk_add_f32 v[56:57], v[56:57], v[120:121]
	v_pk_add_f32 v[50:51], v[50:51], v[114:115]
	v_pk_add_f32 v[52:53], v[52:53], v[116:117]
	s_mov_b64 vcc, s[4:5]
	v_cndmask_b32_dpp v142, v58, v62, vcc row_ror:8 row_mask:0xf bank_mask:0xf bound_ctrl:1
	v_cndmask_b32_dpp v143, v59, v63, vcc row_ror:8 row_mask:0xf bank_mask:0xf bound_ctrl:1
	v_cndmask_b32_dpp v144, v60, v64, vcc row_ror:8 row_mask:0xf bank_mask:0xf bound_ctrl:1
	v_cndmask_b32_dpp v145, v61, v65, vcc row_ror:8 row_mask:0xf bank_mask:0xf bound_ctrl:1
	v_cndmask_b32_dpp v118, v50, v54, vcc row_ror:8 row_mask:0xf bank_mask:0xf bound_ctrl:1
	v_cndmask_b32_dpp v119, v51, v55, vcc row_ror:8 row_mask:0xf bank_mask:0xf bound_ctrl:1
	v_cndmask_b32_dpp v120, v52, v56, vcc row_ror:8 row_mask:0xf bank_mask:0xf bound_ctrl:1
	v_cndmask_b32_dpp v121, v53, v57, vcc row_ror:8 row_mask:0xf bank_mask:0xf bound_ctrl:1
	s_not_b64 vcc, s[4:5]
	v_cndmask_b32_dpp v138, v62, v58, vcc row_ror:8 row_mask:0xf bank_mask:0xf bound_ctrl:1
	v_cndmask_b32_dpp v139, v63, v59, vcc row_ror:8 row_mask:0xf bank_mask:0xf bound_ctrl:1
	v_cndmask_b32_dpp v140, v64, v60, vcc row_ror:8 row_mask:0xf bank_mask:0xf bound_ctrl:1
	v_cndmask_b32_dpp v141, v65, v61, vcc row_ror:8 row_mask:0xf bank_mask:0xf bound_ctrl:1
	v_cndmask_b32_dpp v114, v54, v50, vcc row_ror:8 row_mask:0xf bank_mask:0xf bound_ctrl:1
	v_cndmask_b32_dpp v115, v55, v51, vcc row_ror:8 row_mask:0xf bank_mask:0xf bound_ctrl:1
	v_cndmask_b32_dpp v116, v56, v52, vcc row_ror:8 row_mask:0xf bank_mask:0xf bound_ctrl:1
	v_cndmask_b32_dpp v117, v57, v53, vcc row_ror:8 row_mask:0xf bank_mask:0xf bound_ctrl:1
	s_add_u32 s100, s28, 0x80000
	s_addc_u32 s101, s29, 0
	global_store_dwordx4 v186, v[142:145], s[100:101]
	global_store_dwordx4 v187, v[138:141], s[100:101]
	global_store_dwordx4 v186, v[118:121], s[100:101] offset:512
	global_store_dwordx4 v187, v[114:117], s[100:101] offset:512
	s_waitcnt vmcnt(20)
; template <int CTRL> DEVI float dpp(float x) { return __builtin_bit_cast(float, __builtin_amdgcn_mov_dpp(__builtin_bit_cast(int, x), CTRL, 0xf, 0xf, true)); }
; #define PG8_WAIT_V(n) asm volatile("s_waitcnt vmcnt(" #n ")" ::: "memory")
; #define PG8_BAR __builtin_amdgcn_s_barrier()
; template <class Epi, class Sched>
; __device__ __forceinline__ void gemm_phase(PG8_LAS unsigned char* lds, const Gemm g, const Sched& S, const Epi& E, int wv) {
;     ...
;         cur = nxt; cA = nA; cB = nB; ++ui;
;     }
;     PG8_WAIT_V(0);
;     if (wr == 0) PG8_BAR;
;     PG8_BAR;
;     DEVI void operator()(AccRef acc, const pg8::Unit& u, int wr, int wc, int fr, int fq) const {
;     ...
;                     for (int n = 0; n < 2; ++n) b[m][bj][n] = *(const f32x4*)((const char*)base + o + (unsigned)(m * 16 * DM * 4 + bj * 512 + n * 64));
; #pragma unroll
;             for (int m = 0; m < 4; ++m)
; #pragma unroll
;                 for (int bj = 0; bj < 2; ++bj) { const f32x4 d0 = b[m][bj][0] + alpha * acc[ai][bj][m][0], d1 = b[m][bj][1] + alpha * acc[ai][bj][m][1];
;                     f32x4 t0, t1;
; #pragma unroll
;                     for (int i = 0; i < 4; ++i) { t0[i] = dpp<0x128>(d0[i]); t1[i] = dpp<0x128>(d1[i]); }
;                     const f32x4 sa = lo ? d0 : t1, sb = lo ? t0 : d1;
;                     const unsigned oo = os + (unsigned)(m * 16 * DM * 4 + bj * 512);
;                     *(f32x4*)((char*)out + oo) = sa; *(f32x4*)((char*)out + oo + 8u * DM * 4u) = sb; }
;             o += 128u * DM * 4u; os += 128u * DM * 4u; }
;     }
	v_pk_add_f32 v[46:47], v[46:47], v[110:111]
	v_pk_add_f32 v[48:49], v[48:49], v[112:113]
	v_pk_add_f32 v[42:43], v[42:43], v[106:107]
	v_pk_add_f32 v[44:45], v[44:45], v[108:109]
	v_pk_add_f32 v[38:39], v[38:39], v[102:103]
	v_pk_add_f32 v[40:41], v[40:41], v[104:105]
	v_pk_add_f32 v[34:35], v[34:35], v[98:99]
	v_pk_add_f32 v[36:37], v[36:37], v[100:101]
	s_mov_b64 vcc, s[4:5]
	v_cndmask_b32_dpp v110, v42, v46, vcc row_ror:8 row_mask:0xf bank_mask:0xf bound_ctrl:1
	v_cndmask_b32_dpp v111, v43, v47, vcc row_ror:8 row_mask:0xf bank_mask:0xf bound_ctrl:1
	v_cndmask_b32_dpp v112, v44, v48, vcc row_ror:8 row_mask:0xf bank_mask:0xf bound_ctrl:1
	v_cndmask_b32_dpp v113, v45, v49, vcc row_ror:8 row_mask:0xf bank_mask:0xf bound_ctrl:1
	v_cndmask_b32_dpp v102, v34, v38, vcc row_ror:8 row_mask:0xf bank_mask:0xf bound_ctrl:1
	v_cndmask_b32_dpp v103, v35, v39, vcc row_ror:8 row_mask:0xf bank_mask:0xf bound_ctrl:1
	v_cndmask_b32_dpp v104, v36, v40, vcc row_ror:8 row_mask:0xf bank_mask:0xf bound_ctrl:1
	v_cndmask_b32_dpp v105, v37, v41, vcc row_ror:8 row_mask:0xf bank_mask:0xf bound_ctrl:1
	s_not_b64 vcc, s[4:5]
	v_cndmask_b32_dpp v106, v46, v42, vcc row_ror:8 row_mask:0xf bank_mask:0xf bound_ctrl:1
	v_cndmask_b32_dpp v107, v47, v43, vcc row_ror:8 row_mask:0xf bank_mask:0xf bound_ctrl:1
	v_cndmask_b32_dpp v108, v48, v44, vcc row_ror:8 row_mask:0xf bank_mask:0xf bound_ctrl:1
	v_cndmask_b32_dpp v109, v49, v45, vcc row_ror:8 row_mask:0xf bank_mask:0xf bound_ctrl:1
	v_cndmask_b32_dpp v98, v38, v34, vcc row_ror:8 row_mask:0xf bank_mask:0xf bound_ctrl:1
	v_cndmask_b32_dpp v99, v39, v35, vcc row_ror:8 row_mask:0xf bank_mask:0xf bound_ctrl:1
	v_cndmask_b32_dpp v100, v40, v36, vcc row_ror:8 row_mask:0xf bank_mask:0xf bound_ctrl:1
	v_cndmask_b32_dpp v101, v41, v37, vcc row_ror:8 row_mask:0xf bank_mask:0xf bound_ctrl:1
	s_add_u32 s100, s28, 0x90000
	s_addc_u32 s101, s29, 0
	global_store_dwordx4 v186, v[110:113], s[100:101]
	global_store_dwordx4 v187, v[106:109], s[100:101]
	global_store_dwordx4 v186, v[102:105], s[100:101] offset:512
	global_store_dwordx4 v187, v[98:101], s[100:101] offset:512
	s_waitcnt vmcnt(16)
	v_pk_add_f32 v[30:31], v[30:31], v[94:95]
	v_pk_add_f32 v[32:33], v[32:33], v[96:97]
	v_pk_add_f32 v[26:27], v[26:27], v[90:91]
	v_pk_add_f32 v[28:29], v[28:29], v[92:93]
	v_pk_add_f32 v[22:23], v[22:23], v[86:87]
	v_pk_add_f32 v[24:25], v[24:25], v[88:89]
	v_pk_add_f32 v[18:19], v[18:19], v[82:83]
	v_pk_add_f32 v[20:21], v[20:21], v[84:85]
	s_mov_b64 vcc, s[4:5]
	v_cndmask_b32_dpp v94, v26, v30, vcc row_ror:8 row_mask:0xf bank_mask:0xf bound_ctrl:1
	v_cndmask_b32_dpp v95, v27, v31, vcc row_ror:8 row_mask:0xf bank_mask:0xf bound_ctrl:1
	v_cndmask_b32_dpp v96, v28, v32, vcc row_ror:8 row_mask:0xf bank_mask:0xf bound_ctrl:1
	v_cndmask_b32_dpp v97, v29, v33, vcc row_ror:8 row_mask:0xf bank_mask:0xf bound_ctrl:1
	v_cndmask_b32_dpp v86, v18, v22, vcc row_ror:8 row_mask:0xf bank_mask:0xf bound_ctrl:1
	v_cndmask_b32_dpp v87, v19, v23, vcc row_ror:8 row_mask:0xf bank_mask:0xf bound_ctrl:1
	v_cndmask_b32_dpp v88, v20, v24, vcc row_ror:8 row_mask:0xf bank_mask:0xf bound_ctrl:1
	v_cndmask_b32_dpp v89, v21, v25, vcc row_ror:8 row_mask:0xf bank_mask:0xf bound_ctrl:1
	s_not_b64 vcc, s[4:5]
	v_cndmask_b32_dpp v90, v30, v26, vcc row_ror:8 row_mask:0xf bank_mask:0xf bound_ctrl:1
	v_cndmask_b32_dpp v91, v31, v27, vcc row_ror:8 row_mask:0xf bank_mask:0xf bound_ctrl:1
	v_cndmask_b32_dpp v92, v32, v28, vcc row_ror:8 row_mask:0xf bank_mask:0xf bound_ctrl:1
	v_cndmask_b32_dpp v93, v33, v29, vcc row_ror:8 row_mask:0xf bank_mask:0xf bound_ctrl:1
	v_cndmask_b32_dpp v82, v22, v18, vcc row_ror:8 row_mask:0xf bank_mask:0xf bound_ctrl:1
	v_cndmask_b32_dpp v83, v23, v19, vcc row_ror:8 row_mask:0xf bank_mask:0xf bound_ctrl:1
	v_cndmask_b32_dpp v84, v24, v20, vcc row_ror:8 row_mask:0xf bank_mask:0xf bound_ctrl:1
	v_cndmask_b32_dpp v85, v25, v21, vcc row_ror:8 row_mask:0xf bank_mask:0xf bound_ctrl:1
	s_add_u32 s100, s28, 0xa0000
	s_addc_u32 s101, s29, 0
	global_store_dwordx4 v186, v[94:97], s[100:101]
	global_store_dwordx4 v187, v[90:93], s[100:101]
	global_store_dwordx4 v186, v[86:89], s[100:101] offset:512
	global_store_dwordx4 v187, v[82:85], s[100:101] offset:512
	s_waitcnt vmcnt(12)
	v_pk_add_f32 v[14:15], v[14:15], v[78:79]
	v_pk_add_f32 v[16:17], v[16:17], v[80:81]
	v_pk_add_f32 v[10:11], v[10:11], v[74:75]
	v_pk_add_f32 v[12:13], v[12:13], v[76:77]
	v_pk_add_f32 v[6:7], v[6:7], v[70:71]
	v_pk_add_f32 v[8:9], v[8:9], v[72:73]
	v_pk_add_f32 v[2:3], v[2:3], v[66:67]
	v_pk_add_f32 v[4:5], v[4:5], v[68:69]
	s_mov_b64 vcc, s[4:5]
	v_cndmask_b32_dpp v78, v10, v14, vcc row_ror:8 row_mask:0xf bank_mask:0xf bound_ctrl:1
	v_cndmask_b32_dpp v79, v11, v15, vcc row_ror:8 row_mask:0xf bank_mask:0xf bound_ctrl:1
	v_cndmask_b32_dpp v80, v12, v16, vcc row_ror:8 row_mask:0xf bank_mask:0xf bound_ctrl:1
	v_cndmask_b32_dpp v81, v13, v17, vcc row_ror:8 row_mask:0xf bank_mask:0xf bound_ctrl:1
	v_cndmask_b32_dpp v70, v2, v6, vcc row_ror:8 row_mask:0xf bank_mask:0xf bound_ctrl:1
	v_cndmask_b32_dpp v71, v3, v7, vcc row_ror:8 row_mask:0xf bank_mask:0xf bound_ctrl:1
	v_cndmask_b32_dpp v72, v4, v8, vcc row_ror:8 row_mask:0xf bank_mask:0xf bound_ctrl:1
	v_cndmask_b32_dpp v73, v5, v9, vcc row_ror:8 row_mask:0xf bank_mask:0xf bound_ctrl:1
	s_not_b64 vcc, s[4:5]
	v_cndmask_b32_dpp v74, v14, v10, vcc row_ror:8 row_mask:0xf bank_mask:0xf bound_ctrl:1
	v_cndmask_b32_dpp v75, v15, v11, vcc row_ror:8 row_mask:0xf bank_mask:0xf bound_ctrl:1
	v_cndmask_b32_dpp v76, v16, v12, vcc row_ror:8 row_mask:0xf bank_mask:0xf bound_ctrl:1
	v_cndmask_b32_dpp v77, v17, v13, vcc row_ror:8 row_mask:0xf bank_mask:0xf bound_ctrl:1
	v_cndmask_b32_dpp v66, v6, v2, vcc row_ror:8 row_mask:0xf bank_mask:0xf bound_ctrl:1
	v_cndmask_b32_dpp v67, v7, v3, vcc row_ror:8 row_mask:0xf bank_mask:0xf bound_ctrl:1
	v_cndmask_b32_dpp v68, v8, v4, vcc row_ror:8 row_mask:0xf bank_mask:0xf bound_ctrl:1
	v_cndmask_b32_dpp v69, v9, v5, vcc row_ror:8 row_mask:0xf bank_mask:0xf bound_ctrl:1
	s_add_u32 s100, s28, 0xb0000
	s_addc_u32 s101, s29, 0
	global_store_dwordx4 v186, v[78:81], s[100:101]
	global_store_dwordx4 v187, v[74:77], s[100:101]
	global_store_dwordx4 v186, v[70:73], s[100:101] offset:512
	global_store_dwordx4 v187, v[66:69], s[100:101] offset:512
	s_and_b64 vcc, exec, s[6:7]
	s_cbranch_vccz .LBB0_35
	s_waitcnt vmcnt(0)
	s_cmpk_gt_u32 s13, 0xff
	s_cbranch_scc1 .LBB0_46
	s_barrier

.LBB0_63:
	s_add_i32 s96, s96, 2
	s_cmp_gt_u32 s96, 15
	s_cselect_b32 s97, 0x13fff800, 0
	s_cmp_gt_u32 s96, 13
	s_cselect_b32 s86, 0x13fff800, 0
	s_add_u32 s86, s86, s84
	s_addc_u32 s87, 0, s85
	s_add_u32 s86, s82, s86
	s_addc_u32 s87, s83, s87
	s_add_u32 s86, s86, 0x100
	s_addc_u32 s87, s87, 0
	s_add_u32 vcc_lo, s94, s84
	s_addc_u32 vcc_hi, s95, s85
	s_add_i32 s13, 0, 0x10000
	v_add_u32_e32 v0, s13, v202
	ds_read_b128 v[132:135], v0
	ds_read_b128 v[136:139], v0 offset:1024
	ds_read_b128 v[140:143], v0 offset:2048
	ds_read_b128 v[144:147], v0 offset:3072
	s_cmpk_eq_i32 s84, 0xf00
	s_cselect_b32 s89, s25, s87
	s_cselect_b32 s88, s92, s86
	s_cselect_b32 s87, s23, vcc_hi
	s_cselect_b32 s86, s93, vcc_lo
	s_add_u32 vcc_lo, s97, s84
	s_addc_u32 vcc_hi, 0, s85
	v_lshl_add_u64 v[2:3], v[200:201], 0, vcc
	s_add_i32 m0, s59, 0xc000
	ds_read_b128 v[148:151], v204
	ds_read_b128 v[152:155], v204 offset:1024
	ds_read_b128 v[156:159], v204 offset:2048
	ds_read_b128 v[160:163], v204 offset:3072
	ds_read_b128 v[164:167], v204 offset:4096
	ds_read_b128 v[168:171], v204 offset:5120
	ds_read_b128 v[172:175], v204 offset:6144
	ds_read_b128 v[176:179], v204 offset:7168
	global_load_lds_dwordx4 v[2:3], off
	v_lshl_add_u64 v[2:3], v[194:195], 0, vcc
	s_add_i32 m0, s59, 0xe000
	s_nop 0
	global_load_lds_dwordx4 v[2:3], off
	s_waitcnt lgkmcnt(8)
	s_barrier
	s_waitcnt lgkmcnt(0)
	s_setprio 1
	v_mfma_f32_16x16x32_bf16 v[128:131], v[132:135], v[148:151], v[128:131]
	v_mfma_f32_16x16x32_bf16 v[124:127], v[140:143], v[148:151], v[124:127]
	v_mfma_f32_16x16x32_bf16 v[112:115], v[132:135], v[156:159], v[112:115]
	v_mfma_f32_16x16x32_bf16 v[108:111], v[140:143], v[156:159], v[108:111]
	v_mfma_f32_16x16x32_bf16 v[96:99], v[132:135], v[164:167], v[96:99]
	v_mfma_f32_16x16x32_bf16 v[92:95], v[140:143], v[164:167], v[92:95]
	v_mfma_f32_16x16x32_bf16 v[80:83], v[132:135], v[172:175], v[80:83]
	v_mfma_f32_16x16x32_bf16 v[76:79], v[140:143], v[172:175], v[76:79]
	v_mfma_f32_16x16x32_bf16 v[128:131], v[136:139], v[152:155], v[128:131]
	v_mfma_f32_16x16x32_bf16 v[124:127], v[144:147], v[152:155], v[124:127]
	v_mfma_f32_16x16x32_bf16 v[112:115], v[136:139], v[160:163], v[112:115]
	v_mfma_f32_16x16x32_bf16 v[108:111], v[144:147], v[160:163], v[108:111]
	v_mfma_f32_16x16x32_bf16 v[96:99], v[136:139], v[168:171], v[96:99]
	v_mfma_f32_16x16x32_bf16 v[92:95], v[144:147], v[168:171], v[92:95]
	v_mfma_f32_16x16x32_bf16 v[80:83], v[136:139], v[176:179], v[80:83]
	v_mfma_f32_16x16x32_bf16 v[76:79], v[144:147], v[176:179], v[76:79]
	s_setprio 0
	s_barrier
	s_add_i32 s97, 0, 0x14000
	s_add_i32 s13, s13, s46
	v_add_u32_e32 v0, s97, v202
	v_lshl_add_u64 v[214:215], s[86:87], 0, v[184:185]
	s_mov_b32 m0, s13
	ds_read_b128 v[196:199], v0
	ds_read_b128 v[206:209], v0 offset:1024
	ds_read_b128 v[210:213], v0 offset:2048
	ds_read_b128 v[218:221], v0 offset:3072
	global_load_lds_dwordx4 v[214:215], off
	v_lshl_add_u64 v[222:223], s[86:87], 0, v[180:181]
	s_add_i32 m0, s13, 0x2000
	s_nop 0
	global_load_lds_dwordx4 v[222:223], off
	s_barrier
	s_waitcnt lgkmcnt(0)
	s_setprio 1
	v_mfma_f32_16x16x32_bf16 v[120:123], v[196:199], v[148:151], v[120:123]
	v_mfma_f32_16x16x32_bf16 v[116:119], v[210:213], v[148:151], v[116:119]
	v_mfma_f32_16x16x32_bf16 v[104:107], v[196:199], v[156:159], v[104:107]
	v_mfma_f32_16x16x32_bf16 v[100:103], v[210:213], v[156:159], v[100:103]
	v_mfma_f32_16x16x32_bf16 v[88:91], v[196:199], v[164:167], v[88:91]
	v_mfma_f32_16x16x32_bf16 v[84:87], v[210:213], v[164:167], v[84:87]
	v_mfma_f32_16x16x32_bf16 v[72:75], v[196:199], v[172:175], v[72:75]
	v_mfma_f32_16x16x32_bf16 v[68:71], v[210:213], v[172:175], v[68:71]
	v_mfma_f32_16x16x32_bf16 v[120:123], v[206:209], v[152:155], v[120:123]
	v_mfma_f32_16x16x32_bf16 v[116:119], v[218:221], v[152:155], v[116:119]
	v_mfma_f32_16x16x32_bf16 v[104:107], v[206:209], v[160:163], v[104:107]
	v_mfma_f32_16x16x32_bf16 v[100:103], v[218:221], v[160:163], v[100:103]
	v_mfma_f32_16x16x32_bf16 v[88:91], v[206:209], v[168:171], v[88:91]
	v_mfma_f32_16x16x32_bf16 v[84:87], v[218:221], v[168:171], v[84:87]
	v_mfma_f32_16x16x32_bf16 v[72:75], v[206:209], v[176:179], v[72:75]
	v_mfma_f32_16x16x32_bf16 v[68:71], v[218:221], v[176:179], v[68:71]
	s_setprio 0
	s_mov_b32 m0, s59
	v_lshl_add_u64 v[224:225], s[88:89], 0, v[186:187]
	s_barrier
	ds_read_b128 v[148:151], v204 offset:16384
	ds_read_b128 v[152:155], v204 offset:17408
	ds_read_b128 v[156:159], v204 offset:18432
	ds_read_b128 v[160:163], v204 offset:19456
	ds_read_b128 v[164:167], v204 offset:20480
	ds_read_b128 v[168:171], v204 offset:21504
	ds_read_b128 v[172:175], v204 offset:22528
	ds_read_b128 v[176:179], v204 offset:23552
	global_load_lds_dwordx4 v[224:225], off
	v_lshl_add_u64 v[226:227], s[88:89], 0, v[182:183]
	s_mov_b32 m0, s60
	s_nop 0
	global_load_lds_dwordx4 v[226:227], off
	s_barrier
	s_waitcnt lgkmcnt(0)
	s_setprio 1
	v_mfma_f32_16x16x32_bf16 v[64:67], v[132:135], v[148:151], v[64:67]
	v_mfma_f32_16x16x32_bf16 v[60:63], v[140:143], v[148:151], v[60:63]
	v_mfma_f32_16x16x32_bf16 v[48:51], v[132:135], v[156:159], v[48:51]
	v_mfma_f32_16x16x32_bf16 v[44:47], v[140:143], v[156:159], v[44:47]
	v_mfma_f32_16x16x32_bf16 v[32:35], v[132:135], v[164:167], v[32:35]
	v_mfma_f32_16x16x32_bf16 v[28:31], v[140:143], v[164:167], v[28:31]
	v_mfma_f32_16x16x32_bf16 v[16:19], v[132:135], v[172:175], v[16:19]
	v_mfma_f32_16x16x32_bf16 v[12:15], v[140:143], v[172:175], v[12:15]
	v_mfma_f32_16x16x32_bf16 v[64:67], v[136:139], v[152:155], v[64:67]
	v_mfma_f32_16x16x32_bf16 v[60:63], v[144:147], v[152:155], v[60:63]
	v_mfma_f32_16x16x32_bf16 v[48:51], v[136:139], v[160:163], v[48:51]
	v_mfma_f32_16x16x32_bf16 v[44:47], v[144:147], v[160:163], v[44:47]
	v_mfma_f32_16x16x32_bf16 v[32:35], v[136:139], v[168:171], v[32:35]
	v_mfma_f32_16x16x32_bf16 v[28:31], v[144:147], v[168:171], v[28:31]
	v_mfma_f32_16x16x32_bf16 v[16:19], v[136:139], v[176:179], v[16:19]
	v_mfma_f32_16x16x32_bf16 v[12:15], v[144:147], v[176:179], v[12:15]
	s_setprio 0
	s_barrier
	s_add_u32 vcc_lo, s86, 0x80000
	s_addc_u32 vcc_hi, s87, 0
	s_add_i32 s13, s97, s46
	v_lshl_add_u64 v[2:3], vcc, 0, v[184:185]
	s_mov_b32 m0, s13
	s_nop 0
	global_load_lds_dwordx4 v[2:3], off
	v_lshl_add_u64 v[2:3], vcc, 0, v[180:181]
	s_add_i32 m0, s13, 0x2000
	s_nop 0
	global_load_lds_dwordx4 v[2:3], off
	s_waitcnt vmcnt(6)
	s_barrier
	s_setprio 1
	v_mfma_f32_16x16x32_bf16 v[56:59], v[196:199], v[148:151], v[56:59]
	v_mfma_f32_16x16x32_bf16 v[52:55], v[210:213], v[148:151], v[52:55]
	v_mfma_f32_16x16x32_bf16 v[40:43], v[196:199], v[156:159], v[40:43]
	v_mfma_f32_16x16x32_bf16 v[36:39], v[210:213], v[156:159], v[36:39]
	v_mfma_f32_16x16x32_bf16 v[24:27], v[196:199], v[164:167], v[24:27]
	v_mfma_f32_16x16x32_bf16 v[20:23], v[210:213], v[164:167], v[20:23]
	v_mfma_f32_16x16x32_bf16 v[8:11], v[196:199], v[172:175], v[8:11]
	v_mfma_f32_16x16x32_bf16 v[2:5], v[210:213], v[172:175], v[4:7]
	v_mfma_f32_16x16x32_bf16 v[56:59], v[206:209], v[152:155], v[56:59]
	v_mfma_f32_16x16x32_bf16 v[52:55], v[218:221], v[152:155], v[52:55]
	v_mfma_f32_16x16x32_bf16 v[40:43], v[206:209], v[160:163], v[40:43]
	v_mfma_f32_16x16x32_bf16 v[36:39], v[218:221], v[160:163], v[36:39]
	v_mfma_f32_16x16x32_bf16 v[24:27], v[206:209], v[168:171], v[24:27]
	v_mfma_f32_16x16x32_bf16 v[20:23], v[218:221], v[168:171], v[20:23]
	v_mfma_f32_16x16x32_bf16 v[8:11], v[206:209], v[176:179], v[8:11]
	v_mfma_f32_16x16x32_bf16 v[2:5], v[218:221], v[176:179], v[2:5]
	s_setprio 0
	s_add_i32 s13, 0, 0x18000
	v_add_u32_e32 v0, s13, v202
	s_barrier
	ds_read_b128 v[132:135], v0
	ds_read_b128 v[136:139], v0 offset:1024
	ds_read_b128 v[140:143], v0 offset:2048
	ds_read_b128 v[144:147], v0 offset:3072
	s_add_u32 s88, s88, 0x40000
	s_addc_u32 s89, s89, 0
	s_mov_b32 m0, s61
	v_lshl_add_u64 v[6:7], s[88:89], 0, v[186:187]
	ds_read_b128 v[148:151], v204 offset:32768
	ds_read_b128 v[152:155], v204 offset:33792
	ds_read_b128 v[156:159], v204 offset:34816
	ds_read_b128 v[160:163], v204 offset:35840
	ds_read_b128 v[164:167], v204 offset:36864
	ds_read_b128 v[168:171], v204 offset:37888
	ds_read_b128 v[172:175], v204 offset:38912
	ds_read_b128 v[176:179], v204 offset:39936
	global_load_lds_dwordx4 v[6:7], off
	v_lshl_add_u64 v[6:7], s[88:89], 0, v[182:183]
	s_mov_b32 m0, s76
	s_nop 0
	global_load_lds_dwordx4 v[6:7], off
	s_waitcnt lgkmcnt(8)
	s_barrier
	s_waitcnt lgkmcnt(0)
	s_setprio 1
	v_mfma_f32_16x16x32_bf16 v[128:131], v[132:135], v[148:151], v[128:131]
	v_mfma_f32_16x16x32_bf16 v[124:127], v[140:143], v[148:151], v[124:127]
	v_mfma_f32_16x16x32_bf16 v[112:115], v[132:135], v[156:159], v[112:115]
	v_mfma_f32_16x16x32_bf16 v[108:111], v[140:143], v[156:159], v[108:111]
	v_mfma_f32_16x16x32_bf16 v[96:99], v[132:135], v[164:167], v[96:99]
	v_mfma_f32_16x16x32_bf16 v[92:95], v[140:143], v[164:167], v[92:95]
	v_mfma_f32_16x16x32_bf16 v[80:83], v[132:135], v[172:175], v[80:83]
	v_mfma_f32_16x16x32_bf16 v[76:79], v[140:143], v[172:175], v[76:79]
	v_mfma_f32_16x16x32_bf16 v[128:131], v[136:139], v[152:155], v[128:131]
	v_mfma_f32_16x16x32_bf16 v[124:127], v[144:147], v[152:155], v[124:127]
	v_mfma_f32_16x16x32_bf16 v[112:115], v[136:139], v[160:163], v[112:115]
	v_mfma_f32_16x16x32_bf16 v[108:111], v[144:147], v[160:163], v[108:111]
	v_mfma_f32_16x16x32_bf16 v[96:99], v[136:139], v[168:171], v[96:99]
	v_mfma_f32_16x16x32_bf16 v[92:95], v[144:147], v[168:171], v[92:95]
	v_mfma_f32_16x16x32_bf16 v[80:83], v[136:139], v[176:179], v[80:83]
	v_mfma_f32_16x16x32_bf16 v[76:79], v[144:147], v[176:179], v[76:79]
	s_setprio 0
	s_barrier
	s_add_i32 s88, 0, 0x1c000
	s_add_i32 s13, s13, s46
	v_add_u32_e32 v0, s88, v202
	v_lshl_add_u64 v[6:7], v[214:215], 0, s[48:49]
	s_mov_b32 m0, s13
	ds_read_b128 v[196:199], v0
	ds_read_b128 v[206:209], v0 offset:1024
	ds_read_b128 v[210:213], v0 offset:2048
	ds_read_b128 v[218:221], v0 offset:3072
	global_load_lds_dwordx4 v[6:7], off
	v_lshl_add_u64 v[6:7], v[222:223], 0, s[48:49]
	s_add_i32 m0, s13, 0x2000
	s_nop 0
	global_load_lds_dwordx4 v[6:7], off
	s_barrier
	s_waitcnt lgkmcnt(0)
	s_setprio 1
	v_mfma_f32_16x16x32_bf16 v[120:123], v[196:199], v[148:151], v[120:123]
	v_mfma_f32_16x16x32_bf16 v[116:119], v[210:213], v[148:151], v[116:119]
	v_mfma_f32_16x16x32_bf16 v[104:107], v[196:199], v[156:159], v[104:107]
	v_mfma_f32_16x16x32_bf16 v[100:103], v[210:213], v[156:159], v[100:103]
	v_mfma_f32_16x16x32_bf16 v[88:91], v[196:199], v[164:167], v[88:91]
	v_mfma_f32_16x16x32_bf16 v[84:87], v[210:213], v[164:167], v[84:87]
	v_mfma_f32_16x16x32_bf16 v[72:75], v[196:199], v[172:175], v[72:75]
	v_mfma_f32_16x16x32_bf16 v[68:71], v[210:213], v[172:175], v[68:71]
	v_mfma_f32_16x16x32_bf16 v[120:123], v[206:209], v[152:155], v[120:123]
	v_mfma_f32_16x16x32_bf16 v[116:119], v[218:221], v[152:155], v[116:119]
	v_mfma_f32_16x16x32_bf16 v[104:107], v[206:209], v[160:163], v[104:107]
	v_mfma_f32_16x16x32_bf16 v[100:103], v[218:221], v[160:163], v[100:103]
	v_mfma_f32_16x16x32_bf16 v[88:91], v[206:209], v[168:171], v[88:91]
	v_mfma_f32_16x16x32_bf16 v[84:87], v[218:221], v[168:171], v[84:87]
	v_mfma_f32_16x16x32_bf16 v[72:75], v[206:209], v[176:179], v[72:75]
	v_mfma_f32_16x16x32_bf16 v[68:71], v[218:221], v[176:179], v[68:71]
	s_setprio 0
	s_mov_b32 m0, s77
	v_lshl_add_u64 v[6:7], v[224:225], 0, s[48:49]
	s_barrier
	ds_read_b128 v[148:151], v204 offset:49152
	ds_read_b128 v[152:155], v204 offset:50176
	ds_read_b128 v[156:159], v204 offset:51200
	ds_read_b128 v[160:163], v204 offset:52224
	ds_read_b128 v[164:167], v204 offset:53248
	ds_read_b128 v[168:171], v204 offset:54272
	ds_read_b128 v[172:175], v204 offset:55296
	ds_read_b128 v[176:179], v204 offset:56320
	global_load_lds_dwordx4 v[6:7], off
	v_lshl_add_u64 v[6:7], v[226:227], 0, s[48:49]
	s_mov_b32 m0, s90
	s_nop 0
	global_load_lds_dwordx4 v[6:7], off
	s_barrier
	s_waitcnt lgkmcnt(0)
	s_setprio 1
	v_mfma_f32_16x16x32_bf16 v[64:67], v[132:135], v[148:151], v[64:67]
	v_mfma_f32_16x16x32_bf16 v[60:63], v[140:143], v[148:151], v[60:63]
	v_mfma_f32_16x16x32_bf16 v[48:51], v[132:135], v[156:159], v[48:51]
	v_mfma_f32_16x16x32_bf16 v[44:47], v[140:143], v[156:159], v[44:47]
	v_mfma_f32_16x16x32_bf16 v[32:35], v[132:135], v[164:167], v[32:35]
	v_mfma_f32_16x16x32_bf16 v[28:31], v[140:143], v[164:167], v[28:31]
	v_mfma_f32_16x16x32_bf16 v[16:19], v[132:135], v[172:175], v[16:19]
	v_mfma_f32_16x16x32_bf16 v[12:15], v[140:143], v[172:175], v[12:15]
	v_mfma_f32_16x16x32_bf16 v[64:67], v[136:139], v[152:155], v[64:67]
	v_mfma_f32_16x16x32_bf16 v[60:63], v[144:147], v[152:155], v[60:63]
	v_mfma_f32_16x16x32_bf16 v[48:51], v[136:139], v[160:163], v[48:51]
	v_mfma_f32_16x16x32_bf16 v[44:47], v[144:147], v[160:163], v[44:47]
	v_mfma_f32_16x16x32_bf16 v[32:35], v[136:139], v[168:171], v[32:35]
	v_mfma_f32_16x16x32_bf16 v[28:31], v[144:147], v[168:171], v[28:31]
	v_mfma_f32_16x16x32_bf16 v[16:19], v[136:139], v[176:179], v[16:19]
	v_mfma_f32_16x16x32_bf16 v[12:15], v[144:147], v[176:179], v[12:15]
	s_setprio 0
	s_barrier
	s_add_u32 s86, s86, 0x80080
	s_addc_u32 s87, s87, 0
	s_add_i32 s13, s88, s46
	v_lshl_add_u64 v[6:7], s[86:87], 0, v[184:185]
	s_mov_b32 m0, s13
	s_nop 0
	global_load_lds_dwordx4 v[6:7], off
	v_lshl_add_u64 v[6:7], s[86:87], 0, v[180:181]
	s_add_i32 m0, s13, 0x2000
	s_nop 0
	global_load_lds_dwordx4 v[6:7], off
	s_waitcnt vmcnt(6)
	s_barrier
	s_setprio 1
	v_mfma_f32_16x16x32_bf16 v[56:59], v[196:199], v[148:151], v[56:59]
	v_mfma_f32_16x16x32_bf16 v[52:55], v[210:213], v[148:151], v[52:55]
	v_mfma_f32_16x16x32_bf16 v[40:43], v[196:199], v[156:159], v[40:43]
	v_mfma_f32_16x16x32_bf16 v[36:39], v[210:213], v[156:159], v[36:39]
	v_mfma_f32_16x16x32_bf16 v[24:27], v[196:199], v[164:167], v[24:27]
	v_mfma_f32_16x16x32_bf16 v[20:23], v[210:213], v[164:167], v[20:23]
	v_mfma_f32_16x16x32_bf16 v[6:9], v[196:199], v[172:175], v[8:11]
	v_mfma_f32_16x16x32_bf16 v[2:5], v[210:213], v[172:175], v[2:5]
	v_mfma_f32_16x16x32_bf16 v[56:59], v[206:209], v[152:155], v[56:59]
	v_mfma_f32_16x16x32_bf16 v[52:55], v[218:221], v[152:155], v[52:55]
	v_mfma_f32_16x16x32_bf16 v[40:43], v[206:209], v[160:163], v[40:43]
	v_mfma_f32_16x16x32_bf16 v[36:39], v[218:221], v[160:163], v[36:39]
	v_mfma_f32_16x16x32_bf16 v[24:27], v[206:209], v[168:171], v[24:27]
	v_mfma_f32_16x16x32_bf16 v[20:23], v[218:221], v[168:171], v[20:23]
	v_mfma_f32_16x16x32_bf16 v[8:11], v[206:209], v[176:179], v[6:9]
	v_mfma_f32_16x16x32_bf16 v[4:7], v[218:221], v[176:179], v[2:5]
	s_setprio 0
	s_add_u32 s84, s84, 0x100
	s_addc_u32 s85, 0, s85
	s_cmp_gt_u32 s96, 29
	s_barrier
	s_cbranch_scc1 .LBB0_55

.LBB0_409:
	s_add_u32 s8, s84, 0xfffc0080
	s_addc_u32 s9, s85, -1
	s_add_i32 s10, 0, 0x10000
	v_add_u32_e32 v0, s10, v159
	ds_read_b128 v[142:145], v0
	ds_read_b128 v[146:149], v0 offset:1024
	ds_read_b128 v[150:153], v0 offset:2048
	ds_read_b128 v[154:157], v0 offset:3072
	s_cmp_eq_u32 s46, 12
	s_cselect_b32 s89, s23, s9
	s_cselect_b32 s88, s60, s8
	s_cselect_b32 s87, s21, vcc_hi
	s_cselect_b32 s86, s61, vcc_lo
	v_lshl_add_u64 v[196:197], s[84:85], 0, v[140:141]
	s_add_i32 m0, s25, 0xc000
	ds_read_b128 v[180:183], v177
	ds_read_b128 v[184:187], v177 offset:1024
	ds_read_b128 v[188:191], v177 offset:2048
	ds_read_b128 v[192:195], v177 offset:3072
	ds_read_b128 v[200:203], v177 offset:4096
	ds_read_b128 v[204:207], v177 offset:5120
	ds_read_b128 v[208:211], v177 offset:6144
	ds_read_b128 v[212:215], v177 offset:7168
	global_load_lds_dwordx4 v[196:197], off
	v_lshl_add_u64 v[196:197], s[84:85], 0, v[138:139]
	s_add_i32 m0, s25, 0xe000
	s_nop 0
	global_load_lds_dwordx4 v[196:197], off
	s_waitcnt lgkmcnt(8)
	s_barrier
	s_waitcnt lgkmcnt(0)
	s_setprio 1
	v_mfma_f32_16x16x32_bf16 v[126:129], v[142:145], v[180:183], v[126:129]
	v_mfma_f32_16x16x32_bf16 v[118:121], v[150:153], v[180:183], v[118:121]
	v_mfma_f32_16x16x32_bf16 v[122:125], v[142:145], v[188:191], v[122:125]
	v_mfma_f32_16x16x32_bf16 v[110:113], v[150:153], v[188:191], v[110:113]
	v_mfma_f32_16x16x32_bf16 v[114:117], v[142:145], v[200:203], v[114:117]
	v_mfma_f32_16x16x32_bf16 v[102:105], v[150:153], v[200:203], v[102:105]
	v_mfma_f32_16x16x32_bf16 v[106:109], v[142:145], v[208:211], v[106:109]
	v_mfma_f32_16x16x32_bf16 v[98:101], v[150:153], v[208:211], v[98:101]
	v_mfma_f32_16x16x32_bf16 v[126:129], v[146:149], v[184:187], v[126:129]
	v_mfma_f32_16x16x32_bf16 v[118:121], v[154:157], v[184:187], v[118:121]
	v_mfma_f32_16x16x32_bf16 v[122:125], v[146:149], v[192:195], v[122:125]
	v_mfma_f32_16x16x32_bf16 v[110:113], v[154:157], v[192:195], v[110:113]
	v_mfma_f32_16x16x32_bf16 v[114:117], v[146:149], v[204:207], v[114:117]
	v_mfma_f32_16x16x32_bf16 v[102:105], v[154:157], v[204:207], v[102:105]
	v_mfma_f32_16x16x32_bf16 v[106:109], v[146:149], v[212:215], v[106:109]
	v_mfma_f32_16x16x32_bf16 v[98:101], v[154:157], v[212:215], v[98:101]
	s_setprio 0
	s_barrier
	s_add_i32 s11, 0, 0x14000
	s_add_i32 s8, s10, s59
	v_add_u32_e32 v0, s11, v159
	v_lshl_add_u64 v[196:197], s[86:87], 0, v[132:133]
	s_mov_b32 m0, s8
	ds_read_b128 v[218:221], v0
	ds_read_b128 v[222:225], v0 offset:1024
	ds_read_b128 v[226:229], v0 offset:2048
	ds_read_b128 v[230:233], v0 offset:3072
	global_load_lds_dwordx4 v[196:197], off
	v_lshl_add_u64 v[198:199], s[86:87], 0, v[136:137]
	s_add_i32 m0, s8, 0x2000
	s_nop 0
	global_load_lds_dwordx4 v[198:199], off
	s_barrier
	s_waitcnt lgkmcnt(0)
	s_setprio 1
	v_mfma_f32_16x16x32_bf16 v[62:65], v[218:221], v[180:183], v[62:65]
	v_mfma_f32_16x16x32_bf16 v[54:57], v[226:229], v[180:183], v[54:57]
	v_mfma_f32_16x16x32_bf16 v[58:61], v[218:221], v[188:191], v[58:61]
	v_mfma_f32_16x16x32_bf16 v[46:49], v[226:229], v[188:191], v[46:49]
	v_mfma_f32_16x16x32_bf16 v[50:53], v[218:221], v[200:203], v[50:53]
	v_mfma_f32_16x16x32_bf16 v[38:41], v[226:229], v[200:203], v[38:41]
	v_mfma_f32_16x16x32_bf16 v[42:45], v[218:221], v[208:211], v[42:45]
	v_mfma_f32_16x16x32_bf16 v[34:37], v[226:229], v[208:211], v[34:37]
	v_mfma_f32_16x16x32_bf16 v[62:65], v[222:225], v[184:187], v[62:65]
	v_mfma_f32_16x16x32_bf16 v[54:57], v[230:233], v[184:187], v[54:57]
	v_mfma_f32_16x16x32_bf16 v[58:61], v[222:225], v[192:195], v[58:61]
	v_mfma_f32_16x16x32_bf16 v[46:49], v[230:233], v[192:195], v[46:49]
	v_mfma_f32_16x16x32_bf16 v[50:53], v[222:225], v[204:207], v[50:53]
	v_mfma_f32_16x16x32_bf16 v[38:41], v[230:233], v[204:207], v[38:41]
	v_mfma_f32_16x16x32_bf16 v[42:45], v[222:225], v[212:215], v[42:45]
	v_mfma_f32_16x16x32_bf16 v[34:37], v[230:233], v[212:215], v[34:37]
	s_setprio 0
	s_mov_b32 m0, s25
	v_lshl_add_u64 v[234:235], s[88:89], 0, v[130:131]
	s_barrier
	ds_read_b128 v[180:183], v177 offset:16384
	ds_read_b128 v[184:187], v177 offset:17408
	ds_read_b128 v[188:191], v177 offset:18432
	ds_read_b128 v[192:195], v177 offset:19456
	ds_read_b128 v[200:203], v177 offset:20480
	ds_read_b128 v[204:207], v177 offset:21504
	ds_read_b128 v[208:211], v177 offset:22528
	ds_read_b128 v[212:215], v177 offset:23552
	global_load_lds_dwordx4 v[234:235], off
	v_lshl_add_u64 v[236:237], s[88:89], 0, v[134:135]
	s_mov_b32 m0, s76
	s_nop 0
	global_load_lds_dwordx4 v[236:237], off
	s_barrier
	s_waitcnt lgkmcnt(0)
	s_setprio 1
	v_mfma_f32_16x16x32_bf16 v[94:97], v[142:145], v[180:183], v[94:97]
	v_mfma_f32_16x16x32_bf16 v[86:89], v[150:153], v[180:183], v[86:89]
	v_mfma_f32_16x16x32_bf16 v[90:93], v[142:145], v[188:191], v[90:93]
	v_mfma_f32_16x16x32_bf16 v[78:81], v[150:153], v[188:191], v[78:81]
	v_mfma_f32_16x16x32_bf16 v[82:85], v[142:145], v[200:203], v[82:85]
	v_mfma_f32_16x16x32_bf16 v[70:73], v[150:153], v[200:203], v[70:73]
	v_mfma_f32_16x16x32_bf16 v[74:77], v[142:145], v[208:211], v[74:77]
	v_mfma_f32_16x16x32_bf16 v[66:69], v[150:153], v[208:211], v[66:69]
	v_mfma_f32_16x16x32_bf16 v[94:97], v[146:149], v[184:187], v[94:97]
	v_mfma_f32_16x16x32_bf16 v[86:89], v[154:157], v[184:187], v[86:89]
	v_mfma_f32_16x16x32_bf16 v[90:93], v[146:149], v[192:195], v[90:93]
	v_mfma_f32_16x16x32_bf16 v[78:81], v[154:157], v[192:195], v[78:81]
	v_mfma_f32_16x16x32_bf16 v[82:85], v[146:149], v[204:207], v[82:85]
	v_mfma_f32_16x16x32_bf16 v[70:73], v[154:157], v[204:207], v[70:73]
	v_mfma_f32_16x16x32_bf16 v[74:77], v[146:149], v[212:215], v[74:77]
	v_mfma_f32_16x16x32_bf16 v[66:69], v[154:157], v[212:215], v[66:69]
	s_setprio 0
	s_barrier
	s_add_u32 s8, s86, 0x40000
	s_addc_u32 s9, s87, 0
	s_add_i32 s10, s11, s59
	v_lshl_add_u64 v[142:143], s[8:9], 0, v[132:133]
	s_mov_b32 m0, s10
	s_nop 0
	global_load_lds_dwordx4 v[142:143], off
	v_lshl_add_u64 v[142:143], s[8:9], 0, v[136:137]
	s_add_i32 m0, s10, 0x2000
	s_nop 0
	global_load_lds_dwordx4 v[142:143], off
	s_waitcnt vmcnt(6)
	s_barrier
	s_setprio 1
	v_mfma_f32_16x16x32_bf16 v[30:33], v[218:221], v[180:183], v[30:33]
	v_mfma_f32_16x16x32_bf16 v[22:25], v[226:229], v[180:183], v[22:25]
	v_mfma_f32_16x16x32_bf16 v[26:29], v[218:221], v[188:191], v[26:29]
	v_mfma_f32_16x16x32_bf16 v[14:17], v[226:229], v[188:191], v[14:17]
	v_mfma_f32_16x16x32_bf16 v[18:21], v[218:221], v[200:203], v[18:21]
	v_mfma_f32_16x16x32_bf16 v[6:9], v[226:229], v[200:203], v[6:9]
	v_mfma_f32_16x16x32_bf16 v[10:13], v[218:221], v[208:211], v[10:13]
	v_mfma_f32_16x16x32_bf16 v[2:5], v[226:229], v[208:211], v[2:5]
	v_mfma_f32_16x16x32_bf16 v[30:33], v[222:225], v[184:187], v[30:33]
	v_mfma_f32_16x16x32_bf16 v[22:25], v[230:233], v[184:187], v[22:25]
	v_mfma_f32_16x16x32_bf16 v[26:29], v[222:225], v[192:195], v[26:29]
	v_mfma_f32_16x16x32_bf16 v[14:17], v[230:233], v[192:195], v[14:17]
	v_mfma_f32_16x16x32_bf16 v[18:21], v[222:225], v[204:207], v[18:21]
	v_mfma_f32_16x16x32_bf16 v[6:9], v[230:233], v[204:207], v[6:9]
	v_mfma_f32_16x16x32_bf16 v[10:13], v[222:225], v[212:215], v[10:13]
	v_mfma_f32_16x16x32_bf16 v[2:5], v[230:233], v[212:215], v[2:5]
	s_setprio 0
	s_add_i32 s10, 0, 0x18000
	v_add_u32_e32 v0, s10, v159
	s_barrier
	ds_read_b128 v[142:145], v0
	ds_read_b128 v[146:149], v0 offset:1024
	ds_read_b128 v[150:153], v0 offset:2048
	ds_read_b128 v[154:157], v0 offset:3072
	s_add_u32 s8, s88, 0x40000
	s_addc_u32 s9, s89, 0
	s_mov_b32 m0, s79
	v_lshl_add_u64 v[218:219], s[8:9], 0, v[130:131]
	ds_read_b128 v[180:183], v177 offset:32768
	ds_read_b128 v[184:187], v177 offset:33792
	ds_read_b128 v[188:191], v177 offset:34816
	ds_read_b128 v[192:195], v177 offset:35840
	ds_read_b128 v[200:203], v177 offset:36864
	ds_read_b128 v[204:207], v177 offset:37888
	ds_read_b128 v[208:211], v177 offset:38912
	ds_read_b128 v[212:215], v177 offset:39936
	global_load_lds_dwordx4 v[218:219], off
	v_lshl_add_u64 v[218:219], s[8:9], 0, v[134:135]
	s_mov_b32 m0, s93
	s_nop 0
	global_load_lds_dwordx4 v[218:219], off
	s_waitcnt lgkmcnt(8)
	s_barrier
	s_waitcnt lgkmcnt(0)
	s_setprio 1
	v_mfma_f32_16x16x32_bf16 v[126:129], v[142:145], v[180:183], v[126:129]
	v_mfma_f32_16x16x32_bf16 v[118:121], v[150:153], v[180:183], v[118:121]
	v_mfma_f32_16x16x32_bf16 v[122:125], v[142:145], v[188:191], v[122:125]
	v_mfma_f32_16x16x32_bf16 v[110:113], v[150:153], v[188:191], v[110:113]
	v_mfma_f32_16x16x32_bf16 v[114:117], v[142:145], v[200:203], v[114:117]
	v_mfma_f32_16x16x32_bf16 v[102:105], v[150:153], v[200:203], v[102:105]
	v_mfma_f32_16x16x32_bf16 v[106:109], v[142:145], v[208:211], v[106:109]
	v_mfma_f32_16x16x32_bf16 v[98:101], v[150:153], v[208:211], v[98:101]
	v_mfma_f32_16x16x32_bf16 v[126:129], v[146:149], v[184:187], v[126:129]
	v_mfma_f32_16x16x32_bf16 v[118:121], v[154:157], v[184:187], v[118:121]
	v_mfma_f32_16x16x32_bf16 v[122:125], v[146:149], v[192:195], v[122:125]
	v_mfma_f32_16x16x32_bf16 v[110:113], v[154:157], v[192:195], v[110:113]
	v_mfma_f32_16x16x32_bf16 v[114:117], v[146:149], v[204:207], v[114:117]
	v_mfma_f32_16x16x32_bf16 v[102:105], v[154:157], v[204:207], v[102:105]
	v_mfma_f32_16x16x32_bf16 v[106:109], v[146:149], v[212:215], v[106:109]
	v_mfma_f32_16x16x32_bf16 v[98:101], v[154:157], v[212:215], v[98:101]
	s_setprio 0
	s_barrier
	s_add_i32 s11, 0, 0x1c000
	s_add_i32 s8, s10, s59
	v_add_u32_e32 v0, s11, v159
	v_lshl_add_u64 v[196:197], v[196:197], 0, s[48:49]
	s_mov_b32 m0, s8
	ds_read_b128 v[218:221], v0
	ds_read_b128 v[222:225], v0 offset:1024
	ds_read_b128 v[226:229], v0 offset:2048
	ds_read_b128 v[230:233], v0 offset:3072
	global_load_lds_dwordx4 v[196:197], off
	v_lshl_add_u64 v[196:197], v[198:199], 0, s[48:49]
	s_add_i32 m0, s8, 0x2000
	s_nop 0
	global_load_lds_dwordx4 v[196:197], off
	s_barrier
	s_waitcnt lgkmcnt(0)
	s_setprio 1
	v_mfma_f32_16x16x32_bf16 v[62:65], v[218:221], v[180:183], v[62:65]
	v_mfma_f32_16x16x32_bf16 v[54:57], v[226:229], v[180:183], v[54:57]
	v_mfma_f32_16x16x32_bf16 v[58:61], v[218:221], v[188:191], v[58:61]
	v_mfma_f32_16x16x32_bf16 v[46:49], v[226:229], v[188:191], v[46:49]
	v_mfma_f32_16x16x32_bf16 v[50:53], v[218:221], v[200:203], v[50:53]
	v_mfma_f32_16x16x32_bf16 v[38:41], v[226:229], v[200:203], v[38:41]
	v_mfma_f32_16x16x32_bf16 v[42:45], v[218:221], v[208:211], v[42:45]
	v_mfma_f32_16x16x32_bf16 v[34:37], v[226:229], v[208:211], v[34:37]
	v_mfma_f32_16x16x32_bf16 v[62:65], v[222:225], v[184:187], v[62:65]
	v_mfma_f32_16x16x32_bf16 v[54:57], v[230:233], v[184:187], v[54:57]
	v_mfma_f32_16x16x32_bf16 v[58:61], v[222:225], v[192:195], v[58:61]
	v_mfma_f32_16x16x32_bf16 v[46:49], v[230:233], v[192:195], v[46:49]
	v_mfma_f32_16x16x32_bf16 v[50:53], v[222:225], v[204:207], v[50:53]
	v_mfma_f32_16x16x32_bf16 v[38:41], v[230:233], v[204:207], v[38:41]
	v_mfma_f32_16x16x32_bf16 v[42:45], v[222:225], v[212:215], v[42:45]
	v_mfma_f32_16x16x32_bf16 v[34:37], v[230:233], v[212:215], v[34:37]
	s_setprio 0
	s_mov_b32 m0, s94
	v_lshl_add_u64 v[196:197], v[234:235], 0, s[48:49]
	s_barrier
	ds_read_b128 v[180:183], v177 offset:49152
	ds_read_b128 v[184:187], v177 offset:50176
	ds_read_b128 v[188:191], v177 offset:51200
	ds_read_b128 v[192:195], v177 offset:52224
	ds_read_b128 v[200:203], v177 offset:53248
	ds_read_b128 v[204:207], v177 offset:54272
	ds_read_b128 v[208:211], v177 offset:55296
	ds_read_b128 v[212:215], v177 offset:56320
	global_load_lds_dwordx4 v[196:197], off
	v_lshl_add_u64 v[196:197], v[236:237], 0, s[48:49]
	s_mov_b32 m0, s95
	s_nop 0
	global_load_lds_dwordx4 v[196:197], off
	s_barrier
;     DEVI void operator()(AccRef acc, const pg8::Unit& u, int wr, int wc, int fr, int fq) const {
;     ...
;             for (int n = 0; n < 2; ++n) { const f32x4 bv = *(const f32x4*)(bias + bcol0 + bj * 128 + n * 4);
; #pragma unroll
;                 for (int ai = 0; ai < 2; ++ai)
; #pragma unroll
;                     for (int m = 0; m < 4; ++m) acc[ai][bj][m][n] += bv; }
	s_waitcnt lgkmcnt(0)
	s_setprio 1
	v_mfma_f32_16x16x32_bf16 v[94:97], v[142:145], v[180:183], v[94:97]
	v_mfma_f32_16x16x32_bf16 v[86:89], v[150:153], v[180:183], v[86:89]
	v_mfma_f32_16x16x32_bf16 v[90:93], v[142:145], v[188:191], v[90:93]
	v_mfma_f32_16x16x32_bf16 v[78:81], v[150:153], v[188:191], v[78:81]
	v_mfma_f32_16x16x32_bf16 v[82:85], v[142:145], v[200:203], v[82:85]
	v_mfma_f32_16x16x32_bf16 v[70:73], v[150:153], v[200:203], v[70:73]
	v_mfma_f32_16x16x32_bf16 v[74:77], v[142:145], v[208:211], v[74:77]
	v_mfma_f32_16x16x32_bf16 v[66:69], v[150:153], v[208:211], v[66:69]
	v_mfma_f32_16x16x32_bf16 v[94:97], v[146:149], v[184:187], v[94:97]
	v_mfma_f32_16x16x32_bf16 v[86:89], v[154:157], v[184:187], v[86:89]
	v_mfma_f32_16x16x32_bf16 v[90:93], v[146:149], v[192:195], v[90:93]
	v_mfma_f32_16x16x32_bf16 v[78:81], v[154:157], v[192:195], v[78:81]
	v_mfma_f32_16x16x32_bf16 v[82:85], v[146:149], v[204:207], v[82:85]
	v_mfma_f32_16x16x32_bf16 v[70:73], v[154:157], v[204:207], v[70:73]
	v_mfma_f32_16x16x32_bf16 v[74:77], v[146:149], v[212:215], v[74:77]
	v_mfma_f32_16x16x32_bf16 v[66:69], v[154:157], v[212:215], v[66:69]
	s_setprio 0
	s_barrier
	s_add_u32 s8, s86, 0x40080
	s_addc_u32 s9, s87, 0
	s_add_i32 s10, s11, s59
	v_lshl_add_u64 v[142:143], s[8:9], 0, v[132:133]
	s_mov_b32 m0, s10
	s_nop 0
	global_load_lds_dwordx4 v[142:143], off
	v_lshl_add_u64 v[142:143], s[8:9], 0, v[136:137]
	s_add_i32 m0, s10, 0x2000
	s_nop 0
	global_load_lds_dwordx4 v[142:143], off
	s_waitcnt vmcnt(6)
	s_barrier
	s_setprio 1
	v_mfma_f32_16x16x32_bf16 v[30:33], v[218:221], v[180:183], v[30:33]
	v_mfma_f32_16x16x32_bf16 v[22:25], v[226:229], v[180:183], v[22:25]
	v_mfma_f32_16x16x32_bf16 v[26:29], v[218:221], v[188:191], v[26:29]
	v_mfma_f32_16x16x32_bf16 v[14:17], v[226:229], v[188:191], v[14:17]
	v_mfma_f32_16x16x32_bf16 v[18:21], v[218:221], v[200:203], v[18:21]
	v_mfma_f32_16x16x32_bf16 v[6:9], v[226:229], v[200:203], v[6:9]
	v_mfma_f32_16x16x32_bf16 v[10:13], v[218:221], v[208:211], v[10:13]
	v_mfma_f32_16x16x32_bf16 v[2:5], v[226:229], v[208:211], v[2:5]
	v_mfma_f32_16x16x32_bf16 v[30:33], v[222:225], v[184:187], v[30:33]
	v_mfma_f32_16x16x32_bf16 v[22:25], v[230:233], v[184:187], v[22:25]
	v_mfma_f32_16x16x32_bf16 v[26:29], v[222:225], v[192:195], v[26:29]
	v_mfma_f32_16x16x32_bf16 v[14:17], v[230:233], v[192:195], v[14:17]
	v_mfma_f32_16x16x32_bf16 v[18:21], v[222:225], v[204:207], v[18:21]
	v_mfma_f32_16x16x32_bf16 v[6:9], v[230:233], v[204:207], v[6:9]
	v_mfma_f32_16x16x32_bf16 v[10:13], v[222:225], v[212:215], v[10:13]
	v_mfma_f32_16x16x32_bf16 v[2:5], v[230:233], v[212:215], v[2:5]
	s_setprio 0
	s_add_i32 s46, s46, 2
	s_add_u32 vcc_lo, vcc_lo, 0x100
	s_addc_u32 vcc_hi, vcc_hi, 0
	s_add_u32 s84, s84, 0x100
	s_addc_u32 s85, s85, 0
	s_cmp_gt_u32 s46, 13
	s_barrier
	s_cbranch_scc0 .LBB0_409
	s_lshl_b32 s21, s24, 8
	s_cmp_gt_i32 s24, 11
	s_cselect_b32 s8, 8, 0
	v_or_b32_e32 v0, s21, v160
	v_add_u32_e32 v142, s8, v0
	v_ashrrev_i32_e32 v143, 31, v142
	v_lshl_add_u64 v[146:147], v[142:143], 2, s[16:17]
	global_load_dwordx4 v[148:151], v[146:147], off offset:16
	global_load_dwordx4 v[142:145], v[146:147], off
	global_load_dwordx4 v[238:241], v[146:147], off offset:528
	global_load_dwordx4 v[242:245], v[146:147], off offset:512
	s_cmp_gt_i32 s24, 7
	s_waitcnt vmcnt(0)
	v_pk_add_f32 v[128:129], v[128:129], v[144:145]
	v_pk_add_f32 v[126:127], v[126:127], v[142:143]
	v_pk_add_f32 v[124:125], v[124:125], v[144:145]
	v_pk_add_f32 v[122:123], v[122:123], v[142:143]
	v_pk_add_f32 v[116:117], v[116:117], v[144:145]
	v_pk_add_f32 v[114:115], v[114:115], v[142:143]
	v_pk_add_f32 v[108:109], v[108:109], v[144:145]
	v_pk_add_f32 v[106:107], v[106:107], v[142:143]
	v_pk_add_f32 v[96:97], v[96:97], v[144:145]
	v_pk_add_f32 v[94:95], v[94:95], v[142:143]
	v_pk_add_f32 v[92:93], v[92:93], v[144:145]
	v_pk_add_f32 v[90:91], v[90:91], v[142:143]
	v_pk_add_f32 v[84:85], v[84:85], v[144:145]
	v_pk_add_f32 v[82:83], v[82:83], v[142:143]
	v_pk_add_f32 v[76:77], v[76:77], v[144:145]
	v_pk_add_f32 v[74:75], v[74:75], v[142:143]
	v_pk_add_f32 v[142:143], v[120:121], v[150:151]
	v_pk_add_f32 v[144:145], v[118:119], v[148:149]
	v_pk_add_f32 v[118:119], v[112:113], v[150:151]
	v_pk_add_f32 v[120:121], v[110:111], v[148:149]
	v_pk_add_f32 v[110:111], v[104:105], v[150:151]
	v_pk_add_f32 v[112:113], v[102:103], v[148:149]
	v_pk_add_f32 v[102:103], v[100:101], v[150:151]
	v_pk_add_f32 v[104:105], v[98:99], v[148:149]
	v_pk_add_f32 v[98:99], v[88:89], v[150:151]
	v_pk_add_f32 v[100:101], v[86:87], v[148:149]
	v_pk_add_f32 v[86:87], v[80:81], v[150:151]
	v_pk_add_f32 v[88:89], v[78:79], v[148:149]
	v_pk_add_f32 v[78:79], v[72:73], v[150:151]
	v_pk_add_f32 v[80:81], v[70:71], v[148:149]
	v_pk_add_f32 v[70:71], v[68:69], v[150:151]
	v_pk_add_f32 v[72:73], v[66:67], v[148:149]
	v_pk_add_f32 v[154:155], v[56:57], v[240:241]
	v_pk_add_f32 v[150:151], v[64:65], v[244:245]
	v_pk_add_f32 v[152:153], v[62:63], v[242:243]
	v_pk_add_f32 v[62:63], v[60:61], v[244:245]
	v_pk_add_f32 v[64:65], v[58:59], v[242:243]
	v_pk_add_f32 v[58:59], v[52:53], v[244:245]
	v_pk_add_f32 v[60:61], v[50:51], v[242:243]
	v_pk_add_f32 v[50:51], v[44:45], v[244:245]
	v_pk_add_f32 v[52:53], v[42:43], v[242:243]
	v_pk_add_f32 v[42:43], v[32:33], v[244:245]
	v_pk_add_f32 v[44:45], v[30:31], v[242:243]
	v_pk_add_f32 v[30:31], v[28:29], v[244:245]
	v_pk_add_f32 v[32:33], v[26:27], v[242:243]
	v_pk_add_f32 v[26:27], v[20:21], v[244:245]
	v_pk_add_f32 v[28:29], v[18:19], v[242:243]
	v_pk_add_f32 v[18:19], v[12:13], v[244:245]
	v_pk_add_f32 v[20:21], v[10:11], v[242:243]
	v_pk_add_f32 v[156:157], v[54:55], v[238:239]
	v_pk_add_f32 v[146:147], v[48:49], v[240:241]
	v_pk_add_f32 v[148:149], v[46:47], v[238:239]
	v_pk_add_f32 v[54:55], v[40:41], v[240:241]
	v_pk_add_f32 v[56:57], v[38:39], v[238:239]
	v_pk_add_f32 v[46:47], v[36:37], v[240:241]
	v_pk_add_f32 v[48:49], v[34:35], v[238:239]
	v_pk_add_f32 v[38:39], v[24:25], v[240:241]
	v_pk_add_f32 v[40:41], v[22:23], v[238:239]
	v_pk_add_f32 v[34:35], v[16:17], v[240:241]
	v_pk_add_f32 v[36:37], v[14:15], v[238:239]
	v_pk_add_f32 v[22:23], v[8:9], v[240:241]
	v_pk_add_f32 v[24:25], v[6:7], v[238:239]
	v_pk_add_f32 v[14:15], v[4:5], v[240:241]
	v_pk_add_f32 v[16:17], v[2:3], v[238:239]
	s_cbranch_scc1 .LBB0_405
;     DEVI void operator()(AccRef acc, const pg8::Unit& u, int wr, int wc, int fr, int fq) const {
;     ...
;                     for (int bj = 0; bj < 2; ++bj) { const f32x4 a = acc[ai][bj][m][0], b = acc[ai][bj][m][1];
;                         float s = (a[0] * a[0] + a[1] * a[1]) + (a[2] * a[2] + a[3] * a[3]) + (b[0] * b[0] + b[1] * b[1]) + (b[2] * b[2] + b[3] * b[3]);
;                         s = xrow16_sum(s);
;                         if (fq == 0) Pt[((ai * 128 + wr * 64 + m * 16 + fr) * 2 + bj) * 4 + wc] = s; }
	v_mul_f32_e32 v0, v127, v127
	v_mul_f32_e32 v2, v129, v129
	v_fmac_f32_e32 v0, v126, v126
	v_fmac_f32_e32 v2, v128, v128
	v_add_f32_e32 v0, v0, v2
	v_mul_f32_e32 v2, v145, v145
	v_fmac_f32_e32 v2, v144, v144
	v_add_f32_e32 v0, v0, v2
	v_mul_f32_e32 v2, v143, v143
	v_fmac_f32_e32 v2, v142, v142
	v_add_f32_e32 v0, v2, v0
	v_mov_b32_e32 v2, v0
	s_nop 1
	v_permlane16_swap_b32_e32 v0, v2
	v_add_f32_e32 v0, v0, v2
	v_mov_b32_e32 v2, v0
	s_nop 1
	v_permlane32_swap_b32_e32 v0, v2
	s_and_saveexec_b64 s[60:61], s[4:5]
	v_add_f32_e32 v0, v0, v2
	ds_write_b32 v162, v0
	s_or_b64 exec, exec, s[60:61]
	v_mul_f32_e32 v0, v153, v153
	v_mul_f32_e32 v2, v151, v151
	v_fmac_f32_e32 v0, v152, v152
	v_fmac_f32_e32 v2, v150, v150
	v_add_f32_e32 v0, v0, v2
	v_mul_f32_e32 v2, v157, v157
	v_fmac_f32_e32 v2, v156, v156
	v_add_f32_e32 v0, v2, v0
	v_mul_f32_e32 v2, v155, v155
	v_fmac_f32_e32 v2, v154, v154
	v_add_f32_e32 v0, v2, v0
	v_mov_b32_e32 v2, v0
	s_nop 1
	v_permlane16_swap_b32_e32 v0, v2
	v_add_f32_e32 v0, v0, v2
	v_mov_b32_e32 v2, v0
	s_nop 1
	v_permlane32_swap_b32_e32 v0, v2
	s_and_saveexec_b64 s[60:61], s[4:5]
	v_add_f32_e32 v0, v0, v2
	ds_write_b32 v162, v0 offset:16
	s_or_b64 exec, exec, s[60:61]
	v_mul_f32_e32 v0, v123, v123
	v_mul_f32_e32 v2, v125, v125
	v_fmac_f32_e32 v0, v122, v122
	v_fmac_f32_e32 v2, v124, v124
	v_add_f32_e32 v0, v0, v2
	v_mul_f32_e32 v2, v121, v121
	v_fmac_f32_e32 v2, v120, v120
	v_add_f32_e32 v0, v0, v2
	v_mul_f32_e32 v2, v119, v119
	v_fmac_f32_e32 v2, v118, v118
	v_add_f32_e32 v0, v2, v0
	v_mov_b32_e32 v2, v0
	s_nop 1
	v_permlane16_swap_b32_e32 v0, v2
	v_add_f32_e32 v0, v0, v2
	v_mov_b32_e32 v2, v0
	s_nop 1
	v_permlane32_swap_b32_e32 v0, v2
	s_and_saveexec_b64 s[60:61], s[4:5]
	v_add_f32_e32 v0, v0, v2
	ds_write_b32 v163, v0
	s_or_b64 exec, exec, s[60:61]
	v_mul_f32_e32 v0, v65, v65
	v_mul_f32_e32 v2, v63, v63
	v_fmac_f32_e32 v0, v64, v64
	v_fmac_f32_e32 v2, v62, v62
	v_add_f32_e32 v0, v0, v2
	v_mul_f32_e32 v2, v149, v149
	v_fmac_f32_e32 v2, v148, v148
	v_add_f32_e32 v0, v0, v2
	v_mul_f32_e32 v2, v147, v147
	v_fmac_f32_e32 v2, v146, v146
	v_add_f32_e32 v0, v2, v0
	v_mov_b32_e32 v2, v0
	s_nop 1
	v_permlane16_swap_b32_e32 v0, v2
	v_add_f32_e32 v0, v0, v2
	v_mov_b32_e32 v2, v0
	s_nop 1
	v_permlane32_swap_b32_e32 v0, v2
	s_and_saveexec_b64 s[60:61], s[4:5]
	v_add_f32_e32 v0, v0, v2
	ds_write_b32 v163, v0 offset:16
	s_or_b64 exec, exec, s[60:61]
	v_mul_f32_e32 v0, v115, v115
	v_mul_f32_e32 v2, v117, v117
	v_fmac_f32_e32 v0, v114, v114
	v_fmac_f32_e32 v2, v116, v116
	v_add_f32_e32 v0, v0, v2
	v_mul_f32_e32 v2, v113, v113
	v_fmac_f32_e32 v2, v112, v112
	v_add_f32_e32 v0, v0, v2
	v_mul_f32_e32 v2, v111, v111
	v_fmac_f32_e32 v2, v110, v110
	v_add_f32_e32 v0, v2, v0
	v_mov_b32_e32 v2, v0
	s_nop 1
	v_permlane16_swap_b32_e32 v0, v2
	v_add_f32_e32 v0, v0, v2
	v_mov_b32_e32 v2, v0
	s_nop 1
	v_permlane32_swap_b32_e32 v0, v2
	s_and_saveexec_b64 s[60:61], s[4:5]
	v_add_f32_e32 v0, v0, v2
	ds_write_b32 v164, v0
	s_or_b64 exec, exec, s[60:61]
	v_mul_f32_e32 v0, v61, v61
	v_mul_f32_e32 v2, v59, v59
	v_fmac_f32_e32 v0, v60, v60
	v_fmac_f32_e32 v2, v58, v58
	v_add_f32_e32 v0, v0, v2
	v_mul_f32_e32 v2, v57, v57
	v_fmac_f32_e32 v2, v56, v56
	v_add_f32_e32 v0, v0, v2
	v_mul_f32_e32 v2, v55, v55
	v_fmac_f32_e32 v2, v54, v54
	v_add_f32_e32 v0, v2, v0
	v_mov_b32_e32 v2, v0
	s_nop 1
	v_permlane16_swap_b32_e32 v0, v2
	v_add_f32_e32 v0, v0, v2
	v_mov_b32_e32 v2, v0
	s_nop 1
	v_permlane32_swap_b32_e32 v0, v2
	s_and_saveexec_b64 s[60:61], s[4:5]
	v_add_f32_e32 v0, v0, v2
	ds_write_b32 v164, v0 offset:16
	s_or_b64 exec, exec, s[60:61]
	v_mul_f32_e32 v0, v107, v107
	v_mul_f32_e32 v2, v109, v109
	v_fmac_f32_e32 v0, v106, v106
	v_fmac_f32_e32 v2, v108, v108
	v_add_f32_e32 v0, v0, v2
	v_mul_f32_e32 v2, v105, v105
	v_fmac_f32_e32 v2, v104, v104
	v_add_f32_e32 v0, v0, v2
	v_mul_f32_e32 v2, v103, v103
	v_fmac_f32_e32 v2, v102, v102
	v_add_f32_e32 v0, v2, v0
	v_mov_b32_e32 v2, v0
	s_nop 1
	v_permlane16_swap_b32_e32 v0, v2
	v_add_f32_e32 v0, v0, v2
	v_mov_b32_e32 v2, v0
	s_nop 1
	v_permlane32_swap_b32_e32 v0, v2
	s_and_saveexec_b64 s[60:61], s[4:5]
	v_add_f32_e32 v0, v0, v2
	ds_write_b32 v165, v0
	s_or_b64 exec, exec, s[60:61]
	v_mul_f32_e32 v0, v53, v53
	v_mul_f32_e32 v2, v51, v51
	v_fmac_f32_e32 v0, v52, v52
	v_fmac_f32_e32 v2, v50, v50
	v_add_f32_e32 v0, v0, v2
	v_mul_f32_e32 v2, v49, v49
	v_fmac_f32_e32 v2, v48, v48
	v_add_f32_e32 v0, v0, v2
	v_mul_f32_e32 v2, v47, v47
	v_fmac_f32_e32 v2, v46, v46
	v_add_f32_e32 v0, v2, v0
	v_mov_b32_e32 v2, v0
	s_nop 1
	v_permlane16_swap_b32_e32 v0, v2
	v_add_f32_e32 v0, v0, v2
	v_mov_b32_e32 v2, v0
	s_nop 1
	v_permlane32_swap_b32_e32 v0, v2
	s_and_saveexec_b64 s[60:61], s[4:5]
	v_add_f32_e32 v0, v0, v2
	ds_write_b32 v165, v0 offset:16
;     DEVI void operator()(AccRef acc, const pg8::Unit& u, int wr, int wc, int fr, int fq) const {
;     ...
;                     for (int bj = 0; bj < 2; ++bj) { const f32x4 a = acc[ai][bj][m][0], b = acc[ai][bj][m][1];
;                         float s = (a[0] * a[0] + a[1] * a[1]) + (a[2] * a[2] + a[3] * a[3]) + (b[0] * b[0] + b[1] * b[1]) + (b[2] * b[2] + b[3] * b[3]);
;                         s = xrow16_sum(s);
;                         if (fq == 0) Pt[((ai * 128 + wr * 64 + m * 16 + fr) * 2 + bj) * 4 + wc] = s; }
	s_or_b64 exec, exec, s[60:61]
	v_mul_f32_e32 v0, v95, v95
	v_mul_f32_e32 v2, v97, v97
	v_fmac_f32_e32 v0, v94, v94
	v_fmac_f32_e32 v2, v96, v96
	v_add_f32_e32 v0, v0, v2
	v_mul_f32_e32 v2, v101, v101
	v_fmac_f32_e32 v2, v100, v100
	v_add_f32_e32 v0, v0, v2
	v_mul_f32_e32 v2, v99, v99
	v_fmac_f32_e32 v2, v98, v98
	v_add_f32_e32 v0, v2, v0
	v_mov_b32_e32 v2, v0
	s_nop 1
	v_permlane16_swap_b32_e32 v0, v2
	v_add_f32_e32 v0, v0, v2
	v_mov_b32_e32 v2, v0
	s_nop 1
	v_permlane32_swap_b32_e32 v0, v2
	s_and_saveexec_b64 s[60:61], s[4:5]
	v_add_f32_e32 v0, v0, v2
	ds_write_b32 v166, v0
	s_or_b64 exec, exec, s[60:61]
	v_mul_f32_e32 v0, v45, v45
	v_mul_f32_e32 v2, v43, v43
	v_fmac_f32_e32 v0, v44, v44
	v_fmac_f32_e32 v2, v42, v42
	v_add_f32_e32 v0, v0, v2
	v_mul_f32_e32 v2, v41, v41
	v_fmac_f32_e32 v2, v40, v40
	v_add_f32_e32 v0, v0, v2
	v_mul_f32_e32 v2, v39, v39
	v_fmac_f32_e32 v2, v38, v38
	v_add_f32_e32 v0, v2, v0
	v_mov_b32_e32 v2, v0
	s_nop 1
	v_permlane16_swap_b32_e32 v0, v2
	v_add_f32_e32 v0, v0, v2
	v_mov_b32_e32 v2, v0
	s_nop 1
	v_permlane32_swap_b32_e32 v0, v2
	s_and_saveexec_b64 s[60:61], s[4:5]
	v_add_f32_e32 v0, v0, v2
	ds_write_b32 v166, v0 offset:16
	s_or_b64 exec, exec, s[60:61]
	v_mul_f32_e32 v0, v91, v91
	v_mul_f32_e32 v2, v93, v93
	v_fmac_f32_e32 v0, v90, v90
	v_fmac_f32_e32 v2, v92, v92
	v_add_f32_e32 v0, v0, v2
	v_mul_f32_e32 v2, v89, v89
	v_fmac_f32_e32 v2, v88, v88
	v_add_f32_e32 v0, v0, v2
	v_mul_f32_e32 v2, v87, v87
	v_fmac_f32_e32 v2, v86, v86
	v_add_f32_e32 v0, v2, v0
	v_mov_b32_e32 v2, v0
	s_nop 1
	v_permlane16_swap_b32_e32 v0, v2
	v_add_f32_e32 v0, v0, v2
	v_mov_b32_e32 v2, v0
	s_nop 1
	v_permlane32_swap_b32_e32 v0, v2
	s_and_saveexec_b64 s[60:61], s[4:5]
	v_add_f32_e32 v0, v0, v2
	ds_write_b32 v167, v0
	s_or_b64 exec, exec, s[60:61]
	v_mul_f32_e32 v0, v33, v33
	v_mul_f32_e32 v2, v31, v31
	v_fmac_f32_e32 v0, v32, v32
	v_fmac_f32_e32 v2, v30, v30
	v_add_f32_e32 v0, v0, v2
	v_mul_f32_e32 v2, v37, v37
	v_fmac_f32_e32 v2, v36, v36
	v_add_f32_e32 v0, v0, v2
	v_mul_f32_e32 v2, v35, v35
	v_fmac_f32_e32 v2, v34, v34
	v_add_f32_e32 v0, v2, v0
	v_mov_b32_e32 v2, v0
	s_nop 1
	v_permlane16_swap_b32_e32 v0, v2
	v_add_f32_e32 v0, v0, v2
	v_mov_b32_e32 v2, v0
	s_nop 1
	v_permlane32_swap_b32_e32 v0, v2
	s_and_saveexec_b64 s[60:61], s[4:5]
	v_add_f32_e32 v0, v0, v2
	ds_write_b32 v167, v0 offset:16
	s_or_b64 exec, exec, s[60:61]
	v_mul_f32_e32 v0, v83, v83
	v_mul_f32_e32 v2, v85, v85
	v_fmac_f32_e32 v0, v82, v82
	v_fmac_f32_e32 v2, v84, v84
	v_add_f32_e32 v0, v0, v2
	v_mul_f32_e32 v2, v81, v81
	v_fmac_f32_e32 v2, v80, v80
	v_add_f32_e32 v0, v0, v2
	v_mul_f32_e32 v2, v79, v79
	v_fmac_f32_e32 v2, v78, v78
	v_add_f32_e32 v0, v2, v0
	v_mov_b32_e32 v2, v0
	s_nop 1
	v_permlane16_swap_b32_e32 v0, v2
	v_add_f32_e32 v0, v0, v2
	v_mov_b32_e32 v2, v0
	s_nop 1
	v_permlane32_swap_b32_e32 v0, v2
	s_and_saveexec_b64 s[60:61], s[4:5]
	v_add_f32_e32 v0, v0, v2
	ds_write_b32 v168, v0
	s_or_b64 exec, exec, s[60:61]
	v_mul_f32_e32 v0, v29, v29
	v_mul_f32_e32 v2, v27, v27
	v_fmac_f32_e32 v0, v28, v28
	v_fmac_f32_e32 v2, v26, v26
	v_add_f32_e32 v0, v0, v2
	v_mul_f32_e32 v2, v25, v25
	v_fmac_f32_e32 v2, v24, v24
	v_add_f32_e32 v0, v0, v2
	v_mul_f32_e32 v2, v23, v23
	v_fmac_f32_e32 v2, v22, v22
	v_add_f32_e32 v0, v2, v0
	v_mov_b32_e32 v2, v0
	s_nop 1
	v_permlane16_swap_b32_e32 v0, v2
	v_add_f32_e32 v0, v0, v2
	v_mov_b32_e32 v2, v0
	s_nop 1
	v_permlane32_swap_b32_e32 v0, v2
	s_and_saveexec_b64 s[60:61], s[4:5]
	v_add_f32_e32 v0, v0, v2
	ds_write_b32 v168, v0 offset:16
	s_or_b64 exec, exec, s[60:61]
	v_mul_f32_e32 v0, v75, v75
	v_mul_f32_e32 v2, v77, v77
	v_fmac_f32_e32 v0, v74, v74
	v_fmac_f32_e32 v2, v76, v76
	v_add_f32_e32 v0, v0, v2
	v_mul_f32_e32 v2, v73, v73
	v_fmac_f32_e32 v2, v72, v72
	v_add_f32_e32 v0, v0, v2
	v_mul_f32_e32 v2, v71, v71
	v_fmac_f32_e32 v2, v70, v70
	v_add_f32_e32 v0, v2, v0
	v_mov_b32_e32 v2, v0
	s_nop 1
	v_permlane16_swap_b32_e32 v0, v2
	v_add_f32_e32 v0, v0, v2
	v_mov_b32_e32 v2, v0
	s_nop 1
	v_permlane32_swap_b32_e32 v0, v2
	s_and_saveexec_b64 s[60:61], s[4:5]
	v_add_f32_e32 v0, v0, v2
	ds_write_b32 v169, v0
	s_or_b64 exec, exec, s[60:61]
	v_mul_f32_e32 v0, v21, v21
	v_mul_f32_e32 v2, v19, v19
	v_fmac_f32_e32 v0, v20, v20
	v_fmac_f32_e32 v2, v18, v18
	v_add_f32_e32 v0, v0, v2
	v_mul_f32_e32 v2, v17, v17
	v_fmac_f32_e32 v2, v16, v16
	v_add_f32_e32 v0, v0, v2
	v_mul_f32_e32 v2, v15, v15
	v_fmac_f32_e32 v2, v14, v14
	v_add_f32_e32 v0, v2, v0
	v_mov_b32_e32 v2, v0
	s_nop 1
	v_permlane16_swap_b32_e32 v0, v2
	v_add_f32_e32 v0, v0, v2
	v_mov_b32_e32 v2, v0
	s_nop 1
	v_permlane32_swap_b32_e32 v0, v2
	s_and_saveexec_b64 s[60:61], s[4:5]
	s_cbranch_execz .LBB0_404
	v_add_f32_e32 v0, v0, v2
	ds_write_b32 v169, v0 offset:16
	s_branch .LBB0_404

.LBB0_511:
	s_add_u32 s18, s14, 0x100
	s_addc_u32 s19, s15, 0
	s_add_i32 s84, 0, 0x10000
	v_add_u32_e32 v0, s84, v189
	ds_read_b128 v[122:125], v0
	ds_read_b128 v[126:129], v0 offset:1024
	ds_read_b128 v[130:133], v0 offset:2048
	ds_read_b128 v[134:137], v0 offset:3072
	s_cmp_eq_u32 s83, 40
	s_cselect_b32 s23, s9, s19
	s_cselect_b32 s22, s8, s18
	s_cselect_b32 s21, s11, s82
	s_cselect_b32 s20, s10, s81
	v_lshl_add_u64 v[186:187], s[14:15], 0, v[184:185]
	s_add_i32 m0, s46, 0xc000
	ds_read_b128 v[146:149], v193
	ds_read_b128 v[150:153], v193 offset:1024
	ds_read_b128 v[154:157], v193 offset:2048
	ds_read_b128 v[158:161], v193 offset:3072
	ds_read_b128 v[162:165], v193 offset:4096
	ds_read_b128 v[166:169], v193 offset:5120
	ds_read_b128 v[170:173], v193 offset:6144
	ds_read_b128 v[174:177], v193 offset:7168
	global_load_lds_dwordx4 v[186:187], off
	v_lshl_add_u64 v[186:187], s[14:15], 0, v[182:183]
	s_add_i32 m0, s46, 0xe000
	s_nop 0
	global_load_lds_dwordx4 v[186:187], off
	s_waitcnt lgkmcnt(8)
	s_barrier
	s_waitcnt lgkmcnt(0)
	s_setprio 1
	v_mfma_f32_16x16x32_bf16 v[142:145], v[122:125], v[146:149], v[142:145]
	v_mfma_f32_16x16x32_bf16 v[138:141], v[130:133], v[146:149], v[138:141]
	v_mfma_f32_16x16x32_bf16 v[110:113], v[122:125], v[154:157], v[110:113]
	v_mfma_f32_16x16x32_bf16 v[106:109], v[130:133], v[154:157], v[106:109]
	v_mfma_f32_16x16x32_bf16 v[94:97], v[122:125], v[162:165], v[94:97]
	v_mfma_f32_16x16x32_bf16 v[90:93], v[130:133], v[162:165], v[90:93]
	v_mfma_f32_16x16x32_bf16 v[78:81], v[122:125], v[170:173], v[78:81]
	v_mfma_f32_16x16x32_bf16 v[74:77], v[130:133], v[170:173], v[74:77]
	v_mfma_f32_16x16x32_bf16 v[142:145], v[126:129], v[150:153], v[142:145]
	v_mfma_f32_16x16x32_bf16 v[138:141], v[134:137], v[150:153], v[138:141]
	v_mfma_f32_16x16x32_bf16 v[110:113], v[126:129], v[158:161], v[110:113]
	v_mfma_f32_16x16x32_bf16 v[106:109], v[134:137], v[158:161], v[106:109]
	v_mfma_f32_16x16x32_bf16 v[94:97], v[126:129], v[166:169], v[94:97]
	v_mfma_f32_16x16x32_bf16 v[90:93], v[134:137], v[166:169], v[90:93]
	v_mfma_f32_16x16x32_bf16 v[78:81], v[126:129], v[174:177], v[78:81]
	v_mfma_f32_16x16x32_bf16 v[74:77], v[134:137], v[174:177], v[74:77]
	s_setprio 0
	s_barrier
	s_add_i32 s85, 0, 0x14000
	s_add_i32 s14, s84, s25
	v_add_u32_e32 v0, s85, v189
	v_lshl_add_u64 v[186:187], s[20:21], 0, v[180:181]
	s_mov_b32 m0, s14
	ds_read_b128 v[194:197], v0
	ds_read_b128 v[200:203], v0 offset:1024
	ds_read_b128 v[204:207], v0 offset:2048
	ds_read_b128 v[208:211], v0 offset:3072
	global_load_lds_dwordx4 v[186:187], off
	v_lshl_add_u64 v[198:199], s[20:21], 0, v[178:179]
	s_add_i32 m0, s14, 0x2000
	s_nop 0
	global_load_lds_dwordx4 v[198:199], off
	s_barrier
	s_waitcnt lgkmcnt(0)
	s_setprio 1
	v_mfma_f32_16x16x32_bf16 v[118:121], v[194:197], v[146:149], v[118:121]
	v_mfma_f32_16x16x32_bf16 v[114:117], v[204:207], v[146:149], v[114:117]
	v_mfma_f32_16x16x32_bf16 v[102:105], v[194:197], v[154:157], v[102:105]
	v_mfma_f32_16x16x32_bf16 v[98:101], v[204:207], v[154:157], v[98:101]
	v_mfma_f32_16x16x32_bf16 v[86:89], v[194:197], v[162:165], v[86:89]
	v_mfma_f32_16x16x32_bf16 v[82:85], v[204:207], v[162:165], v[82:85]
	v_mfma_f32_16x16x32_bf16 v[70:73], v[194:197], v[170:173], v[70:73]
	v_mfma_f32_16x16x32_bf16 v[66:69], v[204:207], v[170:173], v[66:69]
	v_mfma_f32_16x16x32_bf16 v[118:121], v[200:203], v[150:153], v[118:121]
	v_mfma_f32_16x16x32_bf16 v[114:117], v[208:211], v[150:153], v[114:117]
	v_mfma_f32_16x16x32_bf16 v[102:105], v[200:203], v[158:161], v[102:105]
	v_mfma_f32_16x16x32_bf16 v[98:101], v[208:211], v[158:161], v[98:101]
	v_mfma_f32_16x16x32_bf16 v[86:89], v[200:203], v[166:169], v[86:89]
	v_mfma_f32_16x16x32_bf16 v[82:85], v[208:211], v[166:169], v[82:85]
	v_mfma_f32_16x16x32_bf16 v[70:73], v[200:203], v[174:177], v[70:73]
	v_mfma_f32_16x16x32_bf16 v[66:69], v[208:211], v[174:177], v[66:69]
	s_setprio 0
	s_mov_b32 m0, s46
	v_lshl_add_u64 v[212:213], s[22:23], 0, v[180:181]
	s_barrier
	ds_read_b128 v[146:149], v193 offset:16384
	ds_read_b128 v[150:153], v193 offset:17408
	ds_read_b128 v[154:157], v193 offset:18432
	ds_read_b128 v[158:161], v193 offset:19456
	ds_read_b128 v[162:165], v193 offset:20480
	ds_read_b128 v[166:169], v193 offset:21504
	ds_read_b128 v[170:173], v193 offset:22528
	ds_read_b128 v[174:177], v193 offset:23552
	global_load_lds_dwordx4 v[212:213], off
	v_lshl_add_u64 v[214:215], s[22:23], 0, v[178:179]
	s_mov_b32 m0, s57
	s_nop 0
	global_load_lds_dwordx4 v[214:215], off
	s_barrier
	s_waitcnt lgkmcnt(0)
	s_setprio 1
	v_mfma_f32_16x16x32_bf16 v[62:65], v[122:125], v[146:149], v[62:65]
	v_mfma_f32_16x16x32_bf16 v[58:61], v[130:133], v[146:149], v[58:61]
	v_mfma_f32_16x16x32_bf16 v[46:49], v[122:125], v[154:157], v[46:49]
	v_mfma_f32_16x16x32_bf16 v[42:45], v[130:133], v[154:157], v[42:45]
	v_mfma_f32_16x16x32_bf16 v[30:33], v[122:125], v[162:165], v[30:33]
	v_mfma_f32_16x16x32_bf16 v[26:29], v[130:133], v[162:165], v[26:29]
	v_mfma_f32_16x16x32_bf16 v[14:17], v[122:125], v[170:173], v[14:17]
	v_mfma_f32_16x16x32_bf16 v[10:13], v[130:133], v[170:173], v[10:13]
	v_mfma_f32_16x16x32_bf16 v[62:65], v[126:129], v[150:153], v[62:65]
	v_mfma_f32_16x16x32_bf16 v[58:61], v[134:137], v[150:153], v[58:61]
	v_mfma_f32_16x16x32_bf16 v[46:49], v[126:129], v[158:161], v[46:49]
	v_mfma_f32_16x16x32_bf16 v[42:45], v[134:137], v[158:161], v[42:45]
	v_mfma_f32_16x16x32_bf16 v[30:33], v[126:129], v[166:169], v[30:33]
	v_mfma_f32_16x16x32_bf16 v[26:29], v[134:137], v[166:169], v[26:29]
	v_mfma_f32_16x16x32_bf16 v[14:17], v[126:129], v[174:177], v[14:17]
	v_mfma_f32_16x16x32_bf16 v[10:13], v[134:137], v[174:177], v[10:13]
	s_setprio 0
	s_barrier
	s_add_u32 s14, s20, 0xb0000
	s_addc_u32 s15, s21, 0
	s_add_i32 s84, s85, s25
	v_lshl_add_u64 v[122:123], s[14:15], 0, v[180:181]
	s_mov_b32 m0, s84
	s_nop 0
	global_load_lds_dwordx4 v[122:123], off
	v_lshl_add_u64 v[122:123], s[14:15], 0, v[178:179]
	s_add_i32 m0, s84, 0x2000
	s_nop 0
	global_load_lds_dwordx4 v[122:123], off
	s_waitcnt vmcnt(6)
	s_barrier
	s_setprio 1
	v_mfma_f32_16x16x32_bf16 v[54:57], v[194:197], v[146:149], v[54:57]
	v_mfma_f32_16x16x32_bf16 v[50:53], v[204:207], v[146:149], v[50:53]
	v_mfma_f32_16x16x32_bf16 v[38:41], v[194:197], v[154:157], v[38:41]
	v_mfma_f32_16x16x32_bf16 v[34:37], v[204:207], v[154:157], v[34:37]
	v_mfma_f32_16x16x32_bf16 v[22:25], v[194:197], v[162:165], v[22:25]
	v_mfma_f32_16x16x32_bf16 v[18:21], v[204:207], v[162:165], v[18:21]
	v_mfma_f32_16x16x32_bf16 v[6:9], v[194:197], v[170:173], v[6:9]
	v_mfma_f32_16x16x32_bf16 v[2:5], v[204:207], v[170:173], v[2:5]
	v_mfma_f32_16x16x32_bf16 v[54:57], v[200:203], v[150:153], v[54:57]
	v_mfma_f32_16x16x32_bf16 v[50:53], v[208:211], v[150:153], v[50:53]
	v_mfma_f32_16x16x32_bf16 v[38:41], v[200:203], v[158:161], v[38:41]
	v_mfma_f32_16x16x32_bf16 v[34:37], v[208:211], v[158:161], v[34:37]
	v_mfma_f32_16x16x32_bf16 v[22:25], v[200:203], v[166:169], v[22:25]
	v_mfma_f32_16x16x32_bf16 v[18:21], v[208:211], v[166:169], v[18:21]
	v_mfma_f32_16x16x32_bf16 v[6:9], v[200:203], v[174:177], v[6:9]
	v_mfma_f32_16x16x32_bf16 v[2:5], v[208:211], v[174:177], v[2:5]
	s_setprio 0
	s_add_i32 s84, 0, 0x18000
	v_add_u32_e32 v0, s84, v189
	s_barrier
	ds_read_b128 v[122:125], v0
	ds_read_b128 v[126:129], v0 offset:1024
	ds_read_b128 v[130:133], v0 offset:2048
	ds_read_b128 v[134:137], v0 offset:3072
	s_add_u32 s14, s22, 0xb0000
	s_addc_u32 s15, s23, 0
	s_mov_b32 m0, s59
	v_lshl_add_u64 v[194:195], s[14:15], 0, v[180:181]
	ds_read_b128 v[146:149], v193 offset:32768
	ds_read_b128 v[150:153], v193 offset:33792
	ds_read_b128 v[154:157], v193 offset:34816
	ds_read_b128 v[158:161], v193 offset:35840
	ds_read_b128 v[162:165], v193 offset:36864
	ds_read_b128 v[166:169], v193 offset:37888
	ds_read_b128 v[170:173], v193 offset:38912
	ds_read_b128 v[174:177], v193 offset:39936
	global_load_lds_dwordx4 v[194:195], off
	v_lshl_add_u64 v[194:195], s[14:15], 0, v[178:179]
	s_mov_b32 m0, s60
	s_nop 0
	global_load_lds_dwordx4 v[194:195], off
	s_waitcnt lgkmcnt(8)
	s_barrier
	s_waitcnt lgkmcnt(0)
	s_setprio 1
	v_mfma_f32_16x16x32_bf16 v[142:145], v[122:125], v[146:149], v[142:145]
	v_mfma_f32_16x16x32_bf16 v[138:141], v[130:133], v[146:149], v[138:141]
	v_mfma_f32_16x16x32_bf16 v[110:113], v[122:125], v[154:157], v[110:113]
	v_mfma_f32_16x16x32_bf16 v[106:109], v[130:133], v[154:157], v[106:109]
	v_mfma_f32_16x16x32_bf16 v[94:97], v[122:125], v[162:165], v[94:97]
	v_mfma_f32_16x16x32_bf16 v[90:93], v[130:133], v[162:165], v[90:93]
	v_mfma_f32_16x16x32_bf16 v[78:81], v[122:125], v[170:173], v[78:81]
	v_mfma_f32_16x16x32_bf16 v[74:77], v[130:133], v[170:173], v[74:77]
	v_mfma_f32_16x16x32_bf16 v[142:145], v[126:129], v[150:153], v[142:145]
	v_mfma_f32_16x16x32_bf16 v[138:141], v[134:137], v[150:153], v[138:141]
	v_mfma_f32_16x16x32_bf16 v[110:113], v[126:129], v[158:161], v[110:113]
	v_mfma_f32_16x16x32_bf16 v[106:109], v[134:137], v[158:161], v[106:109]
	v_mfma_f32_16x16x32_bf16 v[94:97], v[126:129], v[166:169], v[94:97]
	v_mfma_f32_16x16x32_bf16 v[90:93], v[134:137], v[166:169], v[90:93]
	v_mfma_f32_16x16x32_bf16 v[78:81], v[126:129], v[174:177], v[78:81]
	v_mfma_f32_16x16x32_bf16 v[74:77], v[134:137], v[174:177], v[74:77]
	s_setprio 0
	s_barrier
	s_add_i32 s22, 0, 0x1c000
	s_add_i32 s14, s84, s25
	v_add_u32_e32 v0, s22, v189
	v_lshl_add_u64 v[186:187], v[186:187], 0, s[48:49]
	s_mov_b32 m0, s14
	ds_read_b128 v[194:197], v0
	ds_read_b128 v[200:203], v0 offset:1024
	ds_read_b128 v[204:207], v0 offset:2048
	ds_read_b128 v[208:211], v0 offset:3072
	global_load_lds_dwordx4 v[186:187], off
	v_lshl_add_u64 v[186:187], v[198:199], 0, s[48:49]
	s_add_i32 m0, s14, 0x2000
	s_nop 0
	global_load_lds_dwordx4 v[186:187], off
	s_barrier
	s_waitcnt lgkmcnt(0)
	s_setprio 1
	v_mfma_f32_16x16x32_bf16 v[118:121], v[194:197], v[146:149], v[118:121]
	v_mfma_f32_16x16x32_bf16 v[114:117], v[204:207], v[146:149], v[114:117]
	v_mfma_f32_16x16x32_bf16 v[102:105], v[194:197], v[154:157], v[102:105]
	v_mfma_f32_16x16x32_bf16 v[98:101], v[204:207], v[154:157], v[98:101]
	v_mfma_f32_16x16x32_bf16 v[86:89], v[194:197], v[162:165], v[86:89]
	v_mfma_f32_16x16x32_bf16 v[82:85], v[204:207], v[162:165], v[82:85]
	v_mfma_f32_16x16x32_bf16 v[70:73], v[194:197], v[170:173], v[70:73]
	v_mfma_f32_16x16x32_bf16 v[66:69], v[204:207], v[170:173], v[66:69]
	v_mfma_f32_16x16x32_bf16 v[118:121], v[200:203], v[150:153], v[118:121]
	v_mfma_f32_16x16x32_bf16 v[114:117], v[208:211], v[150:153], v[114:117]
	v_mfma_f32_16x16x32_bf16 v[102:105], v[200:203], v[158:161], v[102:105]
	v_mfma_f32_16x16x32_bf16 v[98:101], v[208:211], v[158:161], v[98:101]
	v_mfma_f32_16x16x32_bf16 v[86:89], v[200:203], v[166:169], v[86:89]
	v_mfma_f32_16x16x32_bf16 v[82:85], v[208:211], v[166:169], v[82:85]
	v_mfma_f32_16x16x32_bf16 v[70:73], v[200:203], v[174:177], v[70:73]
	v_mfma_f32_16x16x32_bf16 v[66:69], v[208:211], v[174:177], v[66:69]
	s_setprio 0
	s_mov_b32 m0, s74
	v_lshl_add_u64 v[186:187], v[212:213], 0, s[48:49]
	s_barrier
	ds_read_b128 v[146:149], v193 offset:49152
	ds_read_b128 v[150:153], v193 offset:50176
	ds_read_b128 v[154:157], v193 offset:51200
	ds_read_b128 v[158:161], v193 offset:52224
	ds_read_b128 v[162:165], v193 offset:53248
	ds_read_b128 v[166:169], v193 offset:54272
	ds_read_b128 v[170:173], v193 offset:55296
	ds_read_b128 v[174:177], v193 offset:56320
	global_load_lds_dwordx4 v[186:187], off
	v_lshl_add_u64 v[186:187], v[214:215], 0, s[48:49]
	s_mov_b32 m0, s75
	s_nop 0
	global_load_lds_dwordx4 v[186:187], off
	s_barrier
;     DEVI void operator()(AccRef acc, const pg8::Unit& u, int wr, int wc, int fr, int fq) const {
;         unsigned o = (unsigned)((u.pm * 256 + wr * 64 + fr) * DM + u.pn * 256 + wc * 32 + 4 * fq) * 4u;
;         const bool lo = fr < 8;
;         unsigned os = (unsigned)((u.pm * 256 + wr * 64 + (fr & 7)) * DM + u.pn * 256 + wc * 32 + 4 * fq) * 4u + (lo ? 0u : 64u);
; #pragma unroll
;         for (int ai = 0; ai < 2; ++ai) {
;             asm volatile("" : "+v"(o), "+v"(os));
;             f32x4 b[4][2][2];
; #pragma unroll
;             for (int m = 0; m < 4; ++m)
; #pragma unroll
;                 for (int bj = 0; bj < 2; ++bj)
; #pragma unroll
;                     for (int n = 0; n < 2; ++n) b[m][bj][n] = *(const f32x4*)((const char*)base + o + (unsigned)(m * 16 * DM * 4 + bj * 512 + n * 64));
	s_waitcnt lgkmcnt(0)
	s_setprio 1
	v_mfma_f32_16x16x32_bf16 v[62:65], v[122:125], v[146:149], v[62:65]
	v_mfma_f32_16x16x32_bf16 v[58:61], v[130:133], v[146:149], v[58:61]
	v_mfma_f32_16x16x32_bf16 v[46:49], v[122:125], v[154:157], v[46:49]
	v_mfma_f32_16x16x32_bf16 v[42:45], v[130:133], v[154:157], v[42:45]
	v_mfma_f32_16x16x32_bf16 v[30:33], v[122:125], v[162:165], v[30:33]
	v_mfma_f32_16x16x32_bf16 v[26:29], v[130:133], v[162:165], v[26:29]
	v_mfma_f32_16x16x32_bf16 v[14:17], v[122:125], v[170:173], v[14:17]
	v_mfma_f32_16x16x32_bf16 v[10:13], v[130:133], v[170:173], v[10:13]
	v_mfma_f32_16x16x32_bf16 v[62:65], v[126:129], v[150:153], v[62:65]
	v_mfma_f32_16x16x32_bf16 v[58:61], v[134:137], v[150:153], v[58:61]
	v_mfma_f32_16x16x32_bf16 v[46:49], v[126:129], v[158:161], v[46:49]
	v_mfma_f32_16x16x32_bf16 v[42:45], v[134:137], v[158:161], v[42:45]
	v_mfma_f32_16x16x32_bf16 v[30:33], v[126:129], v[166:169], v[30:33]
	v_mfma_f32_16x16x32_bf16 v[26:29], v[134:137], v[166:169], v[26:29]
	v_mfma_f32_16x16x32_bf16 v[14:17], v[126:129], v[174:177], v[14:17]
	v_mfma_f32_16x16x32_bf16 v[10:13], v[134:137], v[174:177], v[10:13]
	s_setprio 0
	s_barrier
	s_add_u32 s14, s20, 0xb0080
	s_addc_u32 s15, s21, 0
	s_add_i32 s20, s22, s25
	v_lshl_add_u64 v[122:123], s[14:15], 0, v[180:181]
	s_mov_b32 m0, s20
	s_nop 0
	global_load_lds_dwordx4 v[122:123], off
	v_lshl_add_u64 v[122:123], s[14:15], 0, v[178:179]
	s_add_i32 m0, s20, 0x2000
	s_nop 0
	global_load_lds_dwordx4 v[122:123], off
	s_waitcnt vmcnt(6)
	s_barrier
	s_setprio 1
	v_mfma_f32_16x16x32_bf16 v[54:57], v[194:197], v[146:149], v[54:57]
	v_mfma_f32_16x16x32_bf16 v[50:53], v[204:207], v[146:149], v[50:53]
	v_mfma_f32_16x16x32_bf16 v[38:41], v[194:197], v[154:157], v[38:41]
	v_mfma_f32_16x16x32_bf16 v[34:37], v[204:207], v[154:157], v[34:37]
	v_mfma_f32_16x16x32_bf16 v[22:25], v[194:197], v[162:165], v[22:25]
	v_mfma_f32_16x16x32_bf16 v[18:21], v[204:207], v[162:165], v[18:21]
	v_mfma_f32_16x16x32_bf16 v[6:9], v[194:197], v[170:173], v[6:9]
	v_mfma_f32_16x16x32_bf16 v[2:5], v[204:207], v[170:173], v[2:5]
	v_mfma_f32_16x16x32_bf16 v[54:57], v[200:203], v[150:153], v[54:57]
	v_mfma_f32_16x16x32_bf16 v[50:53], v[208:211], v[150:153], v[50:53]
	v_mfma_f32_16x16x32_bf16 v[38:41], v[200:203], v[158:161], v[38:41]
	v_mfma_f32_16x16x32_bf16 v[34:37], v[208:211], v[158:161], v[34:37]
	v_mfma_f32_16x16x32_bf16 v[22:25], v[200:203], v[166:169], v[22:25]
	v_mfma_f32_16x16x32_bf16 v[18:21], v[208:211], v[166:169], v[18:21]
	v_mfma_f32_16x16x32_bf16 v[6:9], v[200:203], v[174:177], v[6:9]
	v_mfma_f32_16x16x32_bf16 v[2:5], v[208:211], v[174:177], v[2:5]
	s_setprio 0
	s_add_i32 s83, s83, 2
	s_add_u32 s81, s81, 0x100
	s_addc_u32 s82, s82, 0
	s_cmp_gt_u32 s83, 41
	s_mov_b64 s[14:15], s[18:19]
	s_barrier
	s_cbranch_scc0 .LBB0_511
	s_lshl_b32 s14, s79, 8
	s_add_i32 s14, s14, s61
	v_or_b32_e32 v0, s14, v188
	s_lshl_b32 s15, s80, 8
	v_or_b32_e32 v122, s14, v190
	v_lshl_add_u32 v0, v0, 10, s15
	v_lshl_add_u32 v122, v122, 10, s15
	v_or_b32_e32 v0, v0, v192
	v_or_b32_e32 v122, v122, v192
	v_lshlrev_b32_e32 v0, 2, v0
	v_lshl_or_b32 v186, v122, 2, v191
	s_mov_b32 s80, s77
	s_mov_b32 s79, s78
	s_mov_b64 s[18:19], s[10:11]
	s_mov_b64 s[14:15], s[8:9]
	v_add_u32_e32 v187, 0x8000, v186
	s_add_u32 s98, s12, 0x0
	s_addc_u32 s99, s13, 0
	global_load_dwordx4 v[194:197], v0, s[98:99]
	global_load_dwordx4 v[200:203], v0, s[98:99] offset:64
	global_load_dwordx4 v[204:207], v0, s[98:99] offset:512
	global_load_dwordx4 v[208:211], v0, s[98:99] offset:576
	s_add_u32 s98, s12, 0x10000
	s_addc_u32 s99, s13, 0
	global_load_dwordx4 v[174:177], v0, s[98:99]
	global_load_dwordx4 v[170:173], v0, s[98:99] offset:64
	global_load_dwordx4 v[166:169], v0, s[98:99] offset:512
	global_load_dwordx4 v[162:165], v0, s[98:99] offset:576
	s_add_u32 s98, s12, 0x20000
	s_addc_u32 s99, s13, 0
	global_load_dwordx4 v[158:161], v0, s[98:99]
	global_load_dwordx4 v[154:157], v0, s[98:99] offset:64
	global_load_dwordx4 v[150:153], v0, s[98:99] offset:512
	global_load_dwordx4 v[146:149], v0, s[98:99] offset:576
	s_add_u32 s98, s12, 0x30000
	s_addc_u32 s99, s13, 0
	global_load_dwordx4 v[134:137], v0, s[98:99]
	global_load_dwordx4 v[130:133], v0, s[98:99] offset:64
	global_load_dwordx4 v[126:129], v0, s[98:99] offset:512
	global_load_dwordx4 v[122:125], v0, s[98:99] offset:576
	s_waitcnt vmcnt(12)
; template <int CTRL> DEVI float dpp(float x) { return __builtin_bit_cast(float, __builtin_amdgcn_mov_dpp(__builtin_bit_cast(int, x), CTRL, 0xf, 0xf, true)); }
;     DEVI void operator()(AccRef acc, const pg8::Unit& u, int wr, int wc, int fr, int fq) const {
;     ...
;                     for (int n = 0; n < 2; ++n) b[m][bj][n] = *(const f32x4*)((const char*)base + o + (unsigned)(m * 16 * DM * 4 + bj * 512 + n * 64));
; #pragma unroll
;             for (int m = 0; m < 4; ++m)
; #pragma unroll
;                 for (int bj = 0; bj < 2; ++bj) { const f32x4 d0 = b[m][bj][0] + alpha * acc[ai][bj][m][0], d1 = b[m][bj][1] + alpha * acc[ai][bj][m][1];
;                     f32x4 t0, t1;
; #pragma unroll
;                     for (int i = 0; i < 4; ++i) { t0[i] = dpp<0x128>(d0[i]); t1[i] = dpp<0x128>(d1[i]); }
;                     const f32x4 sa = lo ? d0 : t1, sb = lo ? t0 : d1;
;                     const unsigned oo = os + (unsigned)(m * 16 * DM * 4 + bj * 512);
;                     *(f32x4*)((char*)out + oo) = sa; *(f32x4*)((char*)out + oo + 8u * DM * 4u) = sb; }
;             o += 128u * DM * 4u; os += 128u * DM * 4u; }
	v_pk_fma_f32 v[142:143], v[142:143], 0.5, v[194:195] op_sel_hi:[1,0,1]
	v_pk_fma_f32 v[144:145], v[144:145], 0.5, v[196:197] op_sel_hi:[1,0,1]
	v_pk_fma_f32 v[138:139], v[138:139], 0.5, v[200:201] op_sel_hi:[1,0,1]
	v_pk_fma_f32 v[140:141], v[140:141], 0.5, v[202:203] op_sel_hi:[1,0,1]
	v_pk_fma_f32 v[118:119], v[118:119], 0.5, v[204:205] op_sel_hi:[1,0,1]
	v_pk_fma_f32 v[120:121], v[120:121], 0.5, v[206:207] op_sel_hi:[1,0,1]
	v_pk_fma_f32 v[114:115], v[114:115], 0.5, v[208:209] op_sel_hi:[1,0,1]
	v_pk_fma_f32 v[116:117], v[116:117], 0.5, v[210:211] op_sel_hi:[1,0,1]
	s_mov_b64 vcc, s[4:5]
	v_cndmask_b32_dpp v194, v138, v142, vcc row_ror:8 row_mask:0xf bank_mask:0xf bound_ctrl:1
	v_cndmask_b32_dpp v195, v139, v143, vcc row_ror:8 row_mask:0xf bank_mask:0xf bound_ctrl:1
	v_cndmask_b32_dpp v196, v140, v144, vcc row_ror:8 row_mask:0xf bank_mask:0xf bound_ctrl:1
	v_cndmask_b32_dpp v197, v141, v145, vcc row_ror:8 row_mask:0xf bank_mask:0xf bound_ctrl:1
	v_cndmask_b32_dpp v204, v114, v118, vcc row_ror:8 row_mask:0xf bank_mask:0xf bound_ctrl:1
	v_cndmask_b32_dpp v205, v115, v119, vcc row_ror:8 row_mask:0xf bank_mask:0xf bound_ctrl:1
	v_cndmask_b32_dpp v206, v116, v120, vcc row_ror:8 row_mask:0xf bank_mask:0xf bound_ctrl:1
	v_cndmask_b32_dpp v207, v117, v121, vcc row_ror:8 row_mask:0xf bank_mask:0xf bound_ctrl:1
	s_not_b64 vcc, s[4:5]
	v_cndmask_b32_dpp v200, v142, v138, vcc row_ror:8 row_mask:0xf bank_mask:0xf bound_ctrl:1
	v_cndmask_b32_dpp v201, v143, v139, vcc row_ror:8 row_mask:0xf bank_mask:0xf bound_ctrl:1
	v_cndmask_b32_dpp v202, v144, v140, vcc row_ror:8 row_mask:0xf bank_mask:0xf bound_ctrl:1
	v_cndmask_b32_dpp v203, v145, v141, vcc row_ror:8 row_mask:0xf bank_mask:0xf bound_ctrl:1
	v_cndmask_b32_dpp v208, v118, v114, vcc row_ror:8 row_mask:0xf bank_mask:0xf bound_ctrl:1
	v_cndmask_b32_dpp v209, v119, v115, vcc row_ror:8 row_mask:0xf bank_mask:0xf bound_ctrl:1
	v_cndmask_b32_dpp v210, v120, v116, vcc row_ror:8 row_mask:0xf bank_mask:0xf bound_ctrl:1
	v_cndmask_b32_dpp v211, v121, v117, vcc row_ror:8 row_mask:0xf bank_mask:0xf bound_ctrl:1
	s_add_u32 s100, s28, 0x0
	s_addc_u32 s101, s29, 0
	global_store_dwordx4 v186, v[194:197], s[100:101]
	global_store_dwordx4 v187, v[200:203], s[100:101]
	global_store_dwordx4 v186, v[204:207], s[100:101] offset:512
	global_store_dwordx4 v187, v[208:211], s[100:101] offset:512
	s_add_u32 s98, s12, 0x80000
	s_addc_u32 s99, s13, 0
	global_load_dwordx4 v[142:145], v0, s[98:99]
	global_load_dwordx4 v[138:141], v0, s[98:99] offset:64
	global_load_dwordx4 v[118:121], v0, s[98:99] offset:512
	global_load_dwordx4 v[114:117], v0, s[98:99] offset:576
	s_waitcnt vmcnt(16)
	v_pk_fma_f32 v[110:111], v[110:111], 0.5, v[174:175] op_sel_hi:[1,0,1]
	v_pk_fma_f32 v[112:113], v[112:113], 0.5, v[176:177] op_sel_hi:[1,0,1]
	v_pk_fma_f32 v[106:107], v[106:107], 0.5, v[170:171] op_sel_hi:[1,0,1]
	v_pk_fma_f32 v[108:109], v[108:109], 0.5, v[172:173] op_sel_hi:[1,0,1]
	v_pk_fma_f32 v[102:103], v[102:103], 0.5, v[166:167] op_sel_hi:[1,0,1]
	v_pk_fma_f32 v[104:105], v[104:105], 0.5, v[168:169] op_sel_hi:[1,0,1]
	v_pk_fma_f32 v[98:99], v[98:99], 0.5, v[162:163] op_sel_hi:[1,0,1]
	v_pk_fma_f32 v[100:101], v[100:101], 0.5, v[164:165] op_sel_hi:[1,0,1]
	s_mov_b64 vcc, s[4:5]
	v_cndmask_b32_dpp v174, v106, v110, vcc row_ror:8 row_mask:0xf bank_mask:0xf bound_ctrl:1
	v_cndmask_b32_dpp v175, v107, v111, vcc row_ror:8 row_mask:0xf bank_mask:0xf bound_ctrl:1
	v_cndmask_b32_dpp v176, v108, v112, vcc row_ror:8 row_mask:0xf bank_mask:0xf bound_ctrl:1
	v_cndmask_b32_dpp v177, v109, v113, vcc row_ror:8 row_mask:0xf bank_mask:0xf bound_ctrl:1
	v_cndmask_b32_dpp v166, v98, v102, vcc row_ror:8 row_mask:0xf bank_mask:0xf bound_ctrl:1
	v_cndmask_b32_dpp v167, v99, v103, vcc row_ror:8 row_mask:0xf bank_mask:0xf bound_ctrl:1
	v_cndmask_b32_dpp v168, v100, v104, vcc row_ror:8 row_mask:0xf bank_mask:0xf bound_ctrl:1
	v_cndmask_b32_dpp v169, v101, v105, vcc row_ror:8 row_mask:0xf bank_mask:0xf bound_ctrl:1
	s_not_b64 vcc, s[4:5]
	v_cndmask_b32_dpp v170, v110, v106, vcc row_ror:8 row_mask:0xf bank_mask:0xf bound_ctrl:1
	v_cndmask_b32_dpp v171, v111, v107, vcc row_ror:8 row_mask:0xf bank_mask:0xf bound_ctrl:1
	v_cndmask_b32_dpp v172, v112, v108, vcc row_ror:8 row_mask:0xf bank_mask:0xf bound_ctrl:1
	v_cndmask_b32_dpp v173, v113, v109, vcc row_ror:8 row_mask:0xf bank_mask:0xf bound_ctrl:1
	v_cndmask_b32_dpp v162, v102, v98, vcc row_ror:8 row_mask:0xf bank_mask:0xf bound_ctrl:1
	v_cndmask_b32_dpp v163, v103, v99, vcc row_ror:8 row_mask:0xf bank_mask:0xf bound_ctrl:1
	v_cndmask_b32_dpp v164, v104, v100, vcc row_ror:8 row_mask:0xf bank_mask:0xf bound_ctrl:1
	v_cndmask_b32_dpp v165, v105, v101, vcc row_ror:8 row_mask:0xf bank_mask:0xf bound_ctrl:1
	s_add_u32 s100, s28, 0x10000
	s_addc_u32 s101, s29, 0
	global_store_dwordx4 v186, v[174:177], s[100:101]
	global_store_dwordx4 v187, v[170:173], s[100:101]
	global_store_dwordx4 v186, v[166:169], s[100:101] offset:512
	global_store_dwordx4 v187, v[162:165], s[100:101] offset:512
	s_add_u32 s98, s12, 0x90000
	s_addc_u32 s99, s13, 0
	global_load_dwordx4 v[110:113], v0, s[98:99]
	global_load_dwordx4 v[106:109], v0, s[98:99] offset:64
	global_load_dwordx4 v[102:105], v0, s[98:99] offset:512
	global_load_dwordx4 v[98:101], v0, s[98:99] offset:576
	s_waitcnt vmcnt(20)
; template <int CTRL> DEVI float dpp(float x) { return __builtin_bit_cast(float, __builtin_amdgcn_mov_dpp(__builtin_bit_cast(int, x), CTRL, 0xf, 0xf, true)); }
;     DEVI void operator()(AccRef acc, const pg8::Unit& u, int wr, int wc, int fr, int fq) const {
;     ...
;                     for (int n = 0; n < 2; ++n) b[m][bj][n] = *(const f32x4*)((const char*)base + o + (unsigned)(m * 16 * DM * 4 + bj * 512 + n * 64));
; #pragma unroll
;             for (int m = 0; m < 4; ++m)
; #pragma unroll
;                 for (int bj = 0; bj < 2; ++bj) { const f32x4 d0 = b[m][bj][0] + alpha * acc[ai][bj][m][0], d1 = b[m][bj][1] + alpha * acc[ai][bj][m][1];
;                     f32x4 t0, t1;
; #pragma unroll
;                     for (int i = 0; i < 4; ++i) { t0[i] = dpp<0x128>(d0[i]); t1[i] = dpp<0x128>(d1[i]); }
;                     const f32x4 sa = lo ? d0 : t1, sb = lo ? t0 : d1;
;                     const unsigned oo = os + (unsigned)(m * 16 * DM * 4 + bj * 512);
;                     *(f32x4*)((char*)out + oo) = sa; *(f32x4*)((char*)out + oo + 8u * DM * 4u) = sb; }
;             o += 128u * DM * 4u; os += 128u * DM * 4u; }
	v_pk_fma_f32 v[94:95], v[94:95], 0.5, v[158:159] op_sel_hi:[1,0,1]
	v_pk_fma_f32 v[96:97], v[96:97], 0.5, v[160:161] op_sel_hi:[1,0,1]
	v_pk_fma_f32 v[90:91], v[90:91], 0.5, v[154:155] op_sel_hi:[1,0,1]
	v_pk_fma_f32 v[92:93], v[92:93], 0.5, v[156:157] op_sel_hi:[1,0,1]
	v_pk_fma_f32 v[86:87], v[86:87], 0.5, v[150:151] op_sel_hi:[1,0,1]
	v_pk_fma_f32 v[88:89], v[88:89], 0.5, v[152:153] op_sel_hi:[1,0,1]
	v_pk_fma_f32 v[82:83], v[82:83], 0.5, v[146:147] op_sel_hi:[1,0,1]
	v_pk_fma_f32 v[84:85], v[84:85], 0.5, v[148:149] op_sel_hi:[1,0,1]
	s_mov_b64 vcc, s[4:5]
	v_cndmask_b32_dpp v158, v90, v94, vcc row_ror:8 row_mask:0xf bank_mask:0xf bound_ctrl:1
	v_cndmask_b32_dpp v159, v91, v95, vcc row_ror:8 row_mask:0xf bank_mask:0xf bound_ctrl:1
	v_cndmask_b32_dpp v160, v92, v96, vcc row_ror:8 row_mask:0xf bank_mask:0xf bound_ctrl:1
	v_cndmask_b32_dpp v161, v93, v97, vcc row_ror:8 row_mask:0xf bank_mask:0xf bound_ctrl:1
	v_cndmask_b32_dpp v150, v82, v86, vcc row_ror:8 row_mask:0xf bank_mask:0xf bound_ctrl:1
	v_cndmask_b32_dpp v151, v83, v87, vcc row_ror:8 row_mask:0xf bank_mask:0xf bound_ctrl:1
	v_cndmask_b32_dpp v152, v84, v88, vcc row_ror:8 row_mask:0xf bank_mask:0xf bound_ctrl:1
	v_cndmask_b32_dpp v153, v85, v89, vcc row_ror:8 row_mask:0xf bank_mask:0xf bound_ctrl:1
	s_not_b64 vcc, s[4:5]
	v_cndmask_b32_dpp v154, v94, v90, vcc row_ror:8 row_mask:0xf bank_mask:0xf bound_ctrl:1
	v_cndmask_b32_dpp v155, v95, v91, vcc row_ror:8 row_mask:0xf bank_mask:0xf bound_ctrl:1
	v_cndmask_b32_dpp v156, v96, v92, vcc row_ror:8 row_mask:0xf bank_mask:0xf bound_ctrl:1
	v_cndmask_b32_dpp v157, v97, v93, vcc row_ror:8 row_mask:0xf bank_mask:0xf bound_ctrl:1
	v_cndmask_b32_dpp v146, v86, v82, vcc row_ror:8 row_mask:0xf bank_mask:0xf bound_ctrl:1
	v_cndmask_b32_dpp v147, v87, v83, vcc row_ror:8 row_mask:0xf bank_mask:0xf bound_ctrl:1
	v_cndmask_b32_dpp v148, v88, v84, vcc row_ror:8 row_mask:0xf bank_mask:0xf bound_ctrl:1
	v_cndmask_b32_dpp v149, v89, v85, vcc row_ror:8 row_mask:0xf bank_mask:0xf bound_ctrl:1
	s_add_u32 s100, s28, 0x20000
	s_addc_u32 s101, s29, 0
	global_store_dwordx4 v186, v[158:161], s[100:101]
	global_store_dwordx4 v187, v[154:157], s[100:101]
	global_store_dwordx4 v186, v[150:153], s[100:101] offset:512
	global_store_dwordx4 v187, v[146:149], s[100:101] offset:512
	s_add_u32 s98, s12, 0xa0000
	s_addc_u32 s99, s13, 0
	global_load_dwordx4 v[94:97], v0, s[98:99]
	global_load_dwordx4 v[90:93], v0, s[98:99] offset:64
	global_load_dwordx4 v[86:89], v0, s[98:99] offset:512
	global_load_dwordx4 v[82:85], v0, s[98:99] offset:576
	s_waitcnt vmcnt(24)
	v_pk_fma_f32 v[78:79], v[78:79], 0.5, v[134:135] op_sel_hi:[1,0,1]
	v_pk_fma_f32 v[80:81], v[80:81], 0.5, v[136:137] op_sel_hi:[1,0,1]
	v_pk_fma_f32 v[74:75], v[74:75], 0.5, v[130:131] op_sel_hi:[1,0,1]
	v_pk_fma_f32 v[76:77], v[76:77], 0.5, v[132:133] op_sel_hi:[1,0,1]
	v_pk_fma_f32 v[70:71], v[70:71], 0.5, v[126:127] op_sel_hi:[1,0,1]
	v_pk_fma_f32 v[72:73], v[72:73], 0.5, v[128:129] op_sel_hi:[1,0,1]
	v_pk_fma_f32 v[66:67], v[66:67], 0.5, v[122:123] op_sel_hi:[1,0,1]
	v_pk_fma_f32 v[68:69], v[68:69], 0.5, v[124:125] op_sel_hi:[1,0,1]
	s_mov_b64 vcc, s[4:5]
	v_cndmask_b32_dpp v134, v74, v78, vcc row_ror:8 row_mask:0xf bank_mask:0xf bound_ctrl:1
	v_cndmask_b32_dpp v135, v75, v79, vcc row_ror:8 row_mask:0xf bank_mask:0xf bound_ctrl:1
	v_cndmask_b32_dpp v136, v76, v80, vcc row_ror:8 row_mask:0xf bank_mask:0xf bound_ctrl:1
	v_cndmask_b32_dpp v137, v77, v81, vcc row_ror:8 row_mask:0xf bank_mask:0xf bound_ctrl:1
	v_cndmask_b32_dpp v126, v66, v70, vcc row_ror:8 row_mask:0xf bank_mask:0xf bound_ctrl:1
	v_cndmask_b32_dpp v127, v67, v71, vcc row_ror:8 row_mask:0xf bank_mask:0xf bound_ctrl:1
	v_cndmask_b32_dpp v128, v68, v72, vcc row_ror:8 row_mask:0xf bank_mask:0xf bound_ctrl:1
	v_cndmask_b32_dpp v129, v69, v73, vcc row_ror:8 row_mask:0xf bank_mask:0xf bound_ctrl:1
	s_not_b64 vcc, s[4:5]
	v_cndmask_b32_dpp v130, v78, v74, vcc row_ror:8 row_mask:0xf bank_mask:0xf bound_ctrl:1
	v_cndmask_b32_dpp v131, v79, v75, vcc row_ror:8 row_mask:0xf bank_mask:0xf bound_ctrl:1
	v_cndmask_b32_dpp v132, v80, v76, vcc row_ror:8 row_mask:0xf bank_mask:0xf bound_ctrl:1
	v_cndmask_b32_dpp v133, v81, v77, vcc row_ror:8 row_mask:0xf bank_mask:0xf bound_ctrl:1
	v_cndmask_b32_dpp v122, v70, v66, vcc row_ror:8 row_mask:0xf bank_mask:0xf bound_ctrl:1
	v_cndmask_b32_dpp v123, v71, v67, vcc row_ror:8 row_mask:0xf bank_mask:0xf bound_ctrl:1
	v_cndmask_b32_dpp v124, v72, v68, vcc row_ror:8 row_mask:0xf bank_mask:0xf bound_ctrl:1
	v_cndmask_b32_dpp v125, v73, v69, vcc row_ror:8 row_mask:0xf bank_mask:0xf bound_ctrl:1
	s_add_u32 s100, s28, 0x30000
	s_addc_u32 s101, s29, 0
	global_store_dwordx4 v186, v[134:137], s[100:101]
	global_store_dwordx4 v187, v[130:133], s[100:101]
	global_store_dwordx4 v186, v[126:129], s[100:101] offset:512
	global_store_dwordx4 v187, v[122:125], s[100:101] offset:512
	s_add_u32 s98, s12, 0xb0000
	s_addc_u32 s99, s13, 0
	global_load_dwordx4 v[78:81], v0, s[98:99]
	global_load_dwordx4 v[74:77], v0, s[98:99] offset:64
	global_load_dwordx4 v[70:73], v0, s[98:99] offset:512
	global_load_dwordx4 v[66:69], v0, s[98:99] offset:576
	s_waitcnt vmcnt(24)
; template <int CTRL> DEVI float dpp(float x) { return __builtin_bit_cast(float, __builtin_amdgcn_mov_dpp(__builtin_bit_cast(int, x), CTRL, 0xf, 0xf, true)); }
;     DEVI void operator()(AccRef acc, const pg8::Unit& u, int wr, int wc, int fr, int fq) const {
;     ...
; #pragma unroll
;             for (int m = 0; m < 4; ++m)
; #pragma unroll
;                 for (int bj = 0; bj < 2; ++bj) { const f32x4 d0 = b[m][bj][0] + alpha * acc[ai][bj][m][0], d1 = b[m][bj][1] + alpha * acc[ai][bj][m][1];
;                     f32x4 t0, t1;
; #pragma unroll
;                     for (int i = 0; i < 4; ++i) { t0[i] = dpp<0x128>(d0[i]); t1[i] = dpp<0x128>(d1[i]); }
;                     const f32x4 sa = lo ? d0 : t1, sb = lo ? t0 : d1;
;                     const unsigned oo = os + (unsigned)(m * 16 * DM * 4 + bj * 512);
;                     *(f32x4*)((char*)out + oo) = sa; *(f32x4*)((char*)out + oo + 8u * DM * 4u) = sb; }
;             o += 128u * DM * 4u; os += 128u * DM * 4u; }
	v_pk_fma_f32 v[62:63], v[62:63], 0.5, v[142:143] op_sel_hi:[1,0,1]
	v_pk_fma_f32 v[64:65], v[64:65], 0.5, v[144:145] op_sel_hi:[1,0,1]
	v_pk_fma_f32 v[58:59], v[58:59], 0.5, v[138:139] op_sel_hi:[1,0,1]
	v_pk_fma_f32 v[60:61], v[60:61], 0.5, v[140:141] op_sel_hi:[1,0,1]
	v_pk_fma_f32 v[54:55], v[54:55], 0.5, v[118:119] op_sel_hi:[1,0,1]
	v_pk_fma_f32 v[56:57], v[56:57], 0.5, v[120:121] op_sel_hi:[1,0,1]
	v_pk_fma_f32 v[50:51], v[50:51], 0.5, v[114:115] op_sel_hi:[1,0,1]
	v_pk_fma_f32 v[52:53], v[52:53], 0.5, v[116:117] op_sel_hi:[1,0,1]
	s_mov_b64 vcc, s[4:5]
	v_cndmask_b32_dpp v142, v58, v62, vcc row_ror:8 row_mask:0xf bank_mask:0xf bound_ctrl:1
	v_cndmask_b32_dpp v143, v59, v63, vcc row_ror:8 row_mask:0xf bank_mask:0xf bound_ctrl:1
	v_cndmask_b32_dpp v144, v60, v64, vcc row_ror:8 row_mask:0xf bank_mask:0xf bound_ctrl:1
	v_cndmask_b32_dpp v145, v61, v65, vcc row_ror:8 row_mask:0xf bank_mask:0xf bound_ctrl:1
	v_cndmask_b32_dpp v118, v50, v54, vcc row_ror:8 row_mask:0xf bank_mask:0xf bound_ctrl:1
	v_cndmask_b32_dpp v119, v51, v55, vcc row_ror:8 row_mask:0xf bank_mask:0xf bound_ctrl:1
	v_cndmask_b32_dpp v120, v52, v56, vcc row_ror:8 row_mask:0xf bank_mask:0xf bound_ctrl:1
	v_cndmask_b32_dpp v121, v53, v57, vcc row_ror:8 row_mask:0xf bank_mask:0xf bound_ctrl:1
	s_not_b64 vcc, s[4:5]
	v_cndmask_b32_dpp v138, v62, v58, vcc row_ror:8 row_mask:0xf bank_mask:0xf bound_ctrl:1
	v_cndmask_b32_dpp v139, v63, v59, vcc row_ror:8 row_mask:0xf bank_mask:0xf bound_ctrl:1
	v_cndmask_b32_dpp v140, v64, v60, vcc row_ror:8 row_mask:0xf bank_mask:0xf bound_ctrl:1
	v_cndmask_b32_dpp v141, v65, v61, vcc row_ror:8 row_mask:0xf bank_mask:0xf bound_ctrl:1
	v_cndmask_b32_dpp v114, v54, v50, vcc row_ror:8 row_mask:0xf bank_mask:0xf bound_ctrl:1
	v_cndmask_b32_dpp v115, v55, v51, vcc row_ror:8 row_mask:0xf bank_mask:0xf bound_ctrl:1
	v_cndmask_b32_dpp v116, v56, v52, vcc row_ror:8 row_mask:0xf bank_mask:0xf bound_ctrl:1
	v_cndmask_b32_dpp v117, v57, v53, vcc row_ror:8 row_mask:0xf bank_mask:0xf bound_ctrl:1
	s_add_u32 s100, s28, 0x80000
	s_addc_u32 s101, s29, 0
	global_store_dwordx4 v186, v[142:145], s[100:101]
	global_store_dwordx4 v187, v[138:141], s[100:101]
	global_store_dwordx4 v186, v[118:121], s[100:101] offset:512
	global_store_dwordx4 v187, v[114:117], s[100:101] offset:512
	s_waitcnt vmcnt(20)
	v_pk_fma_f32 v[46:47], v[46:47], 0.5, v[110:111] op_sel_hi:[1,0,1]
	v_pk_fma_f32 v[48:49], v[48:49], 0.5, v[112:113] op_sel_hi:[1,0,1]
	v_pk_fma_f32 v[42:43], v[42:43], 0.5, v[106:107] op_sel_hi:[1,0,1]
	v_pk_fma_f32 v[44:45], v[44:45], 0.5, v[108:109] op_sel_hi:[1,0,1]
	v_pk_fma_f32 v[38:39], v[38:39], 0.5, v[102:103] op_sel_hi:[1,0,1]
	v_pk_fma_f32 v[40:41], v[40:41], 0.5, v[104:105] op_sel_hi:[1,0,1]
	v_pk_fma_f32 v[34:35], v[34:35], 0.5, v[98:99] op_sel_hi:[1,0,1]
	v_pk_fma_f32 v[36:37], v[36:37], 0.5, v[100:101] op_sel_hi:[1,0,1]
	s_mov_b64 vcc, s[4:5]
	v_cndmask_b32_dpp v110, v42, v46, vcc row_ror:8 row_mask:0xf bank_mask:0xf bound_ctrl:1
	v_cndmask_b32_dpp v111, v43, v47, vcc row_ror:8 row_mask:0xf bank_mask:0xf bound_ctrl:1
	v_cndmask_b32_dpp v112, v44, v48, vcc row_ror:8 row_mask:0xf bank_mask:0xf bound_ctrl:1
	v_cndmask_b32_dpp v113, v45, v49, vcc row_ror:8 row_mask:0xf bank_mask:0xf bound_ctrl:1
	v_cndmask_b32_dpp v102, v34, v38, vcc row_ror:8 row_mask:0xf bank_mask:0xf bound_ctrl:1
	v_cndmask_b32_dpp v103, v35, v39, vcc row_ror:8 row_mask:0xf bank_mask:0xf bound_ctrl:1
	v_cndmask_b32_dpp v104, v36, v40, vcc row_ror:8 row_mask:0xf bank_mask:0xf bound_ctrl:1
	v_cndmask_b32_dpp v105, v37, v41, vcc row_ror:8 row_mask:0xf bank_mask:0xf bound_ctrl:1
	s_not_b64 vcc, s[4:5]
	v_cndmask_b32_dpp v106, v46, v42, vcc row_ror:8 row_mask:0xf bank_mask:0xf bound_ctrl:1
	v_cndmask_b32_dpp v107, v47, v43, vcc row_ror:8 row_mask:0xf bank_mask:0xf bound_ctrl:1
	v_cndmask_b32_dpp v108, v48, v44, vcc row_ror:8 row_mask:0xf bank_mask:0xf bound_ctrl:1
	v_cndmask_b32_dpp v109, v49, v45, vcc row_ror:8 row_mask:0xf bank_mask:0xf bound_ctrl:1
	v_cndmask_b32_dpp v98, v38, v34, vcc row_ror:8 row_mask:0xf bank_mask:0xf bound_ctrl:1
	v_cndmask_b32_dpp v99, v39, v35, vcc row_ror:8 row_mask:0xf bank_mask:0xf bound_ctrl:1
	v_cndmask_b32_dpp v100, v40, v36, vcc row_ror:8 row_mask:0xf bank_mask:0xf bound_ctrl:1
	v_cndmask_b32_dpp v101, v41, v37, vcc row_ror:8 row_mask:0xf bank_mask:0xf bound_ctrl:1
	s_add_u32 s100, s28, 0x90000
	s_addc_u32 s101, s29, 0
	global_store_dwordx4 v186, v[110:113], s[100:101]
	global_store_dwordx4 v187, v[106:109], s[100:101]
	global_store_dwordx4 v186, v[102:105], s[100:101] offset:512
	global_store_dwordx4 v187, v[98:101], s[100:101] offset:512
	s_waitcnt vmcnt(16)
; template <int CTRL> DEVI float dpp(float x) { return __builtin_bit_cast(float, __builtin_amdgcn_mov_dpp(__builtin_bit_cast(int, x), CTRL, 0xf, 0xf, true)); }
; #define PG8_WAIT_V(n) asm volatile("s_waitcnt vmcnt(" #n ")" ::: "memory")
; #define PG8_BAR __builtin_amdgcn_s_barrier()
; template <class Epi, class Sched>
; __device__ __forceinline__ void gemm_phase(PG8_LAS unsigned char* lds, const Gemm g, const Sched& S, const Epi& E, int wv) {
;     ...
;         if (!has_next) break;
; #pragma unroll
;         for (int a = 0; a < 2; ++a)
; #pragma unroll
;             for (int b = 0; b < 2; ++b)
; #pragma unroll
;                 for (int m = 0; m < 4; ++m)
; #pragma unroll
;                     for (int n = 0; n < 2; ++n) acc[a][b][m][n] = (f32x4){0.f, 0.f, 0.f, 0.f};
;         cur = nxt; cA = nA; cB = nB; ++ui;
;     }
;     PG8_WAIT_V(0);
;     if (wr == 0) PG8_BAR;
;     PG8_BAR;
;     DEVI void operator()(AccRef acc, const pg8::Unit& u, int wr, int wc, int fr, int fq) const {
;     ...
; #pragma unroll
;             for (int m = 0; m < 4; ++m)
; #pragma unroll
;                 for (int bj = 0; bj < 2; ++bj) { const f32x4 d0 = b[m][bj][0] + alpha * acc[ai][bj][m][0], d1 = b[m][bj][1] + alpha * acc[ai][bj][m][1];
;                     f32x4 t0, t1;
; #pragma unroll
;                     for (int i = 0; i < 4; ++i) { t0[i] = dpp<0x128>(d0[i]); t1[i] = dpp<0x128>(d1[i]); }
;                     const f32x4 sa = lo ? d0 : t1, sb = lo ? t0 : d1;
;                     const unsigned oo = os + (unsigned)(m * 16 * DM * 4 + bj * 512);
;                     *(f32x4*)((char*)out + oo) = sa; *(f32x4*)((char*)out + oo + 8u * DM * 4u) = sb; }
;             o += 128u * DM * 4u; os += 128u * DM * 4u; }
	v_pk_fma_f32 v[30:31], v[30:31], 0.5, v[94:95] op_sel_hi:[1,0,1]
	v_pk_fma_f32 v[32:33], v[32:33], 0.5, v[96:97] op_sel_hi:[1,0,1]
	v_pk_fma_f32 v[26:27], v[26:27], 0.5, v[90:91] op_sel_hi:[1,0,1]
	v_pk_fma_f32 v[28:29], v[28:29], 0.5, v[92:93] op_sel_hi:[1,0,1]
	v_pk_fma_f32 v[22:23], v[22:23], 0.5, v[86:87] op_sel_hi:[1,0,1]
	v_pk_fma_f32 v[24:25], v[24:25], 0.5, v[88:89] op_sel_hi:[1,0,1]
	v_pk_fma_f32 v[18:19], v[18:19], 0.5, v[82:83] op_sel_hi:[1,0,1]
	v_pk_fma_f32 v[20:21], v[20:21], 0.5, v[84:85] op_sel_hi:[1,0,1]
	s_mov_b64 vcc, s[4:5]
	v_cndmask_b32_dpp v94, v26, v30, vcc row_ror:8 row_mask:0xf bank_mask:0xf bound_ctrl:1
	v_cndmask_b32_dpp v95, v27, v31, vcc row_ror:8 row_mask:0xf bank_mask:0xf bound_ctrl:1
	v_cndmask_b32_dpp v96, v28, v32, vcc row_ror:8 row_mask:0xf bank_mask:0xf bound_ctrl:1
	v_cndmask_b32_dpp v97, v29, v33, vcc row_ror:8 row_mask:0xf bank_mask:0xf bound_ctrl:1
	v_cndmask_b32_dpp v86, v18, v22, vcc row_ror:8 row_mask:0xf bank_mask:0xf bound_ctrl:1
	v_cndmask_b32_dpp v87, v19, v23, vcc row_ror:8 row_mask:0xf bank_mask:0xf bound_ctrl:1
	v_cndmask_b32_dpp v88, v20, v24, vcc row_ror:8 row_mask:0xf bank_mask:0xf bound_ctrl:1
	v_cndmask_b32_dpp v89, v21, v25, vcc row_ror:8 row_mask:0xf bank_mask:0xf bound_ctrl:1
	s_not_b64 vcc, s[4:5]
	v_cndmask_b32_dpp v90, v30, v26, vcc row_ror:8 row_mask:0xf bank_mask:0xf bound_ctrl:1
	v_cndmask_b32_dpp v91, v31, v27, vcc row_ror:8 row_mask:0xf bank_mask:0xf bound_ctrl:1
	v_cndmask_b32_dpp v92, v32, v28, vcc row_ror:8 row_mask:0xf bank_mask:0xf bound_ctrl:1
	v_cndmask_b32_dpp v93, v33, v29, vcc row_ror:8 row_mask:0xf bank_mask:0xf bound_ctrl:1
	v_cndmask_b32_dpp v82, v22, v18, vcc row_ror:8 row_mask:0xf bank_mask:0xf bound_ctrl:1
	v_cndmask_b32_dpp v83, v23, v19, vcc row_ror:8 row_mask:0xf bank_mask:0xf bound_ctrl:1
	v_cndmask_b32_dpp v84, v24, v20, vcc row_ror:8 row_mask:0xf bank_mask:0xf bound_ctrl:1
	v_cndmask_b32_dpp v85, v25, v21, vcc row_ror:8 row_mask:0xf bank_mask:0xf bound_ctrl:1
	s_add_u32 s100, s28, 0xa0000
	s_addc_u32 s101, s29, 0
	global_store_dwordx4 v186, v[94:97], s[100:101]
	global_store_dwordx4 v187, v[90:93], s[100:101]
	global_store_dwordx4 v186, v[86:89], s[100:101] offset:512
	global_store_dwordx4 v187, v[82:85], s[100:101] offset:512
	s_waitcnt vmcnt(12)
	v_pk_fma_f32 v[14:15], v[14:15], 0.5, v[78:79] op_sel_hi:[1,0,1]
	v_pk_fma_f32 v[16:17], v[16:17], 0.5, v[80:81] op_sel_hi:[1,0,1]
	v_pk_fma_f32 v[10:11], v[10:11], 0.5, v[74:75] op_sel_hi:[1,0,1]
	v_pk_fma_f32 v[12:13], v[12:13], 0.5, v[76:77] op_sel_hi:[1,0,1]
	v_pk_fma_f32 v[6:7], v[6:7], 0.5, v[70:71] op_sel_hi:[1,0,1]
	v_pk_fma_f32 v[8:9], v[8:9], 0.5, v[72:73] op_sel_hi:[1,0,1]
	v_pk_fma_f32 v[2:3], v[2:3], 0.5, v[66:67] op_sel_hi:[1,0,1]
	v_pk_fma_f32 v[4:5], v[4:5], 0.5, v[68:69] op_sel_hi:[1,0,1]
	s_mov_b64 vcc, s[4:5]
	v_cndmask_b32_dpp v78, v10, v14, vcc row_ror:8 row_mask:0xf bank_mask:0xf bound_ctrl:1
	v_cndmask_b32_dpp v79, v11, v15, vcc row_ror:8 row_mask:0xf bank_mask:0xf bound_ctrl:1
	v_cndmask_b32_dpp v80, v12, v16, vcc row_ror:8 row_mask:0xf bank_mask:0xf bound_ctrl:1
	v_cndmask_b32_dpp v81, v13, v17, vcc row_ror:8 row_mask:0xf bank_mask:0xf bound_ctrl:1
	v_cndmask_b32_dpp v70, v2, v6, vcc row_ror:8 row_mask:0xf bank_mask:0xf bound_ctrl:1
	v_cndmask_b32_dpp v71, v3, v7, vcc row_ror:8 row_mask:0xf bank_mask:0xf bound_ctrl:1
	v_cndmask_b32_dpp v72, v4, v8, vcc row_ror:8 row_mask:0xf bank_mask:0xf bound_ctrl:1
	v_cndmask_b32_dpp v73, v5, v9, vcc row_ror:8 row_mask:0xf bank_mask:0xf bound_ctrl:1
	s_not_b64 vcc, s[4:5]
	v_cndmask_b32_dpp v74, v14, v10, vcc row_ror:8 row_mask:0xf bank_mask:0xf bound_ctrl:1
	v_cndmask_b32_dpp v75, v15, v11, vcc row_ror:8 row_mask:0xf bank_mask:0xf bound_ctrl:1
	v_cndmask_b32_dpp v76, v16, v12, vcc row_ror:8 row_mask:0xf bank_mask:0xf bound_ctrl:1
	v_cndmask_b32_dpp v77, v17, v13, vcc row_ror:8 row_mask:0xf bank_mask:0xf bound_ctrl:1
	v_cndmask_b32_dpp v66, v6, v2, vcc row_ror:8 row_mask:0xf bank_mask:0xf bound_ctrl:1
	v_cndmask_b32_dpp v67, v7, v3, vcc row_ror:8 row_mask:0xf bank_mask:0xf bound_ctrl:1
	v_cndmask_b32_dpp v68, v8, v4, vcc row_ror:8 row_mask:0xf bank_mask:0xf bound_ctrl:1
	v_cndmask_b32_dpp v69, v9, v5, vcc row_ror:8 row_mask:0xf bank_mask:0xf bound_ctrl:1
	s_add_u32 s100, s28, 0xb0000
	s_addc_u32 s101, s29, 0
	global_store_dwordx4 v186, v[78:81], s[100:101]
	global_store_dwordx4 v187, v[74:77], s[100:101]
	global_store_dwordx4 v186, v[70:73], s[100:101] offset:512
	global_store_dwordx4 v187, v[66:69], s[100:101] offset:512
	s_and_b64 vcc, exec, s[6:7]
	s_cbranch_vccz .LBB0_500
	s_waitcnt vmcnt(0)
	s_cmpk_gt_u32 s24, 0xff
	s_cbranch_scc1 .LBB0_515
	s_barrier

.LBB0_524:
	s_and_b64 vcc, exec, s[22:23]
	s_cbranch_vccz .LBB0_526
	s_add_i32 s7, 0, 0x10000
	v_add_u32_e32 v0, s7, v147
	ds_read_b128 v[2:5], v0
	ds_read_b128 v[6:9], v0 offset:1024
	ds_read_b128 v[10:13], v0 offset:2048
	ds_read_b128 v[14:17], v0 offset:3072
	ds_read_b128 v[18:21], v149
	ds_read_b128 v[22:25], v149 offset:1024
	ds_read_b128 v[26:29], v149 offset:2048
	ds_read_b128 v[30:33], v149 offset:3072
	ds_read_b128 v[34:37], v149 offset:4096
	ds_read_b128 v[38:41], v149 offset:5120
	ds_read_b128 v[42:45], v149 offset:6144
	ds_read_b128 v[46:49], v149 offset:7168
	s_waitcnt lgkmcnt(8)
	s_barrier
	s_waitcnt lgkmcnt(0)
	s_setprio 1
	v_mfma_f32_16x16x32_bf16 v[50:53], v[2:5], v[18:21], 0
	v_mfma_f32_16x16x32_bf16 v[62:65], v[10:13], v[26:29], 0
	v_mfma_f32_16x16x32_bf16 v[66:69], v[2:5], v[34:37], 0
	v_mfma_f32_16x16x32_bf16 v[70:73], v[10:13], v[34:37], 0
	v_mfma_f32_16x16x32_bf16 v[74:77], v[2:5], v[42:45], 0
	v_mfma_f32_16x16x32_bf16 v[78:81], v[10:13], v[42:45], 0
	v_mfma_f32_16x16x32_bf16 v[50:53], v[6:9], v[22:25], v[50:53]
	v_mfma_f32_16x16x32_bf16 v[54:57], v[10:13], v[18:21], 0
	v_mfma_f32_16x16x32_bf16 v[58:61], v[2:5], v[26:29], 0
	v_mfma_f32_16x16x32_bf16 v[62:65], v[14:17], v[30:33], v[62:65]
	v_mfma_f32_16x16x32_bf16 v[66:69], v[6:9], v[38:41], v[66:69]
	v_mfma_f32_16x16x32_bf16 v[70:73], v[14:17], v[38:41], v[70:73]
	v_mfma_f32_16x16x32_bf16 v[74:77], v[6:9], v[46:49], v[74:77]
	v_mfma_f32_16x16x32_bf16 v[80:83], v[14:17], v[46:49], v[78:81]
	v_mfma_f32_16x16x32_bf16 v[194:197], v[14:17], v[22:25], v[54:57]
	v_mfma_f32_16x16x32_bf16 v[212:215], v[6:9], v[30:33], v[58:61]
	s_setprio 0
	s_barrier
	s_add_i32 s9, 0, 0x14000
	v_lshl_add_u64 v[144:145], s[18:19], 0, v[136:137]
	s_add_i32 s7, s7, s25
	v_add_u32_e32 v0, s9, v147
	v_lshl_add_u64 v[78:79], v[144:145], 0, s[50:51]
	s_mov_b32 m0, s7
	v_lshl_add_u64 v[198:199], s[18:19], 0, v[132:133]
	ds_read_b128 v[84:87], v0
	ds_read_b128 v[88:91], v0 offset:1024
	ds_read_b128 v[92:95], v0 offset:2048
	ds_read_b128 v[96:99], v0 offset:3072
	global_load_lds_dwordx4 v[78:79], off
	v_lshl_add_u64 v[78:79], v[198:199], 0, s[50:51]
	s_add_i32 m0, s7, 0x2000
	s_nop 0
	global_load_lds_dwordx4 v[78:79], off
	s_barrier
	s_waitcnt lgkmcnt(0)
	s_setprio 1
	v_mfma_f32_16x16x32_bf16 v[100:103], v[84:87], v[18:21], 0
	v_mfma_f32_16x16x32_bf16 v[18:21], v[92:95], v[18:21], 0
	v_mfma_f32_16x16x32_bf16 v[104:107], v[88:91], v[22:25], v[100:103]
	v_mfma_f32_16x16x32_bf16 v[18:21], v[96:99], v[22:25], v[18:21]
	v_mfma_f32_16x16x32_bf16 v[22:25], v[84:87], v[26:29], 0
	v_mfma_f32_16x16x32_bf16 v[26:29], v[92:95], v[26:29], 0
	v_mfma_f32_16x16x32_bf16 v[22:25], v[88:91], v[30:33], v[22:25]
	v_mfma_f32_16x16x32_bf16 v[26:29], v[96:99], v[30:33], v[26:29]
	v_mfma_f32_16x16x32_bf16 v[30:33], v[84:87], v[34:37], 0
	v_mfma_f32_16x16x32_bf16 v[34:37], v[92:95], v[34:37], 0
	v_mfma_f32_16x16x32_bf16 v[30:33], v[88:91], v[38:41], v[30:33]
	v_mfma_f32_16x16x32_bf16 v[34:37], v[96:99], v[38:41], v[34:37]
	v_mfma_f32_16x16x32_bf16 v[38:41], v[84:87], v[42:45], 0
	v_mfma_f32_16x16x32_bf16 v[42:45], v[92:95], v[42:45], 0
	v_mfma_f32_16x16x32_bf16 v[38:41], v[88:91], v[46:49], v[38:41]
	v_mfma_f32_16x16x32_bf16 v[42:45], v[96:99], v[46:49], v[42:45]
	s_setprio 0
	v_lshl_add_u64 v[140:141], s[20:21], 0, v[138:139]
	s_mov_b32 m0, s11
	v_lshl_add_u64 v[78:79], v[140:141], 0, s[50:51]
	v_lshl_add_u64 v[142:143], s[20:21], 0, v[134:135]
	s_barrier
	ds_read_b128 v[46:49], v149 offset:16384
	ds_read_b128 v[100:103], v149 offset:17408
	ds_read_b128 v[108:111], v149 offset:18432
	ds_read_b128 v[112:115], v149 offset:19456
	ds_read_b128 v[116:119], v149 offset:20480
	ds_read_b128 v[120:123], v149 offset:21504
	ds_read_b128 v[124:127], v149 offset:22528
	ds_read_b128 v[128:131], v149 offset:23552
	global_load_lds_dwordx4 v[78:79], off
	v_lshl_add_u64 v[78:79], v[142:143], 0, s[50:51]
	s_mov_b32 m0, s57
	s_nop 0
	global_load_lds_dwordx4 v[78:79], off
	s_barrier
	s_waitcnt lgkmcnt(0)
	s_setprio 1
	v_mfma_f32_16x16x32_bf16 v[150:153], v[2:5], v[46:49], 0
	v_mfma_f32_16x16x32_bf16 v[154:157], v[10:13], v[46:49], 0
	v_mfma_f32_16x16x32_bf16 v[158:161], v[2:5], v[108:111], 0
	v_mfma_f32_16x16x32_bf16 v[166:169], v[2:5], v[116:119], 0
	v_mfma_f32_16x16x32_bf16 v[2:5], v[2:5], v[124:127], 0
	v_mfma_f32_16x16x32_bf16 v[54:57], v[6:9], v[100:103], v[150:153]
	v_mfma_f32_16x16x32_bf16 v[152:155], v[14:17], v[100:103], v[154:157]
	v_mfma_f32_16x16x32_bf16 v[156:159], v[6:9], v[112:115], v[158:161]
	v_mfma_f32_16x16x32_bf16 v[166:169], v[6:9], v[120:123], v[166:169]
	v_mfma_f32_16x16x32_bf16 v[2:5], v[6:9], v[128:131], v[2:5]
	v_mfma_f32_16x16x32_bf16 v[6:9], v[10:13], v[124:127], 0
	v_mfma_f32_16x16x32_bf16 v[162:165], v[10:13], v[108:111], 0
	v_mfma_f32_16x16x32_bf16 v[170:173], v[10:13], v[116:119], 0
	v_mfma_f32_16x16x32_bf16 v[6:9], v[14:17], v[128:131], v[6:9]
	v_mfma_f32_16x16x32_bf16 v[160:163], v[14:17], v[112:115], v[162:165]
	v_mfma_f32_16x16x32_bf16 v[170:173], v[14:17], v[120:123], v[170:173]
	s_setprio 0
	s_barrier
	s_add_u32 s14, s18, 0x40100
	s_addc_u32 s15, s19, 0
	s_add_i32 s7, s9, s25
	v_lshl_add_u64 v[10:11], s[14:15], 0, v[136:137]
	s_mov_b32 m0, s7
	s_nop 0
	global_load_lds_dwordx4 v[10:11], off
	v_lshl_add_u64 v[10:11], s[14:15], 0, v[132:133]
	s_add_i32 m0, s7, 0x2000
	s_nop 0
	global_load_lds_dwordx4 v[10:11], off
	s_barrier
	s_setprio 1
	v_mfma_f32_16x16x32_bf16 v[10:13], v[84:87], v[46:49], 0
	v_mfma_f32_16x16x32_bf16 v[174:177], v[88:91], v[100:103], v[10:13]
	v_mfma_f32_16x16x32_bf16 v[10:13], v[92:95], v[46:49], 0
	v_mfma_f32_16x16x32_bf16 v[178:181], v[96:99], v[100:103], v[10:13]
	v_mfma_f32_16x16x32_bf16 v[10:13], v[84:87], v[108:111], 0
	v_mfma_f32_16x16x32_bf16 v[182:185], v[88:91], v[112:115], v[10:13]
	v_mfma_f32_16x16x32_bf16 v[10:13], v[92:95], v[108:111], 0
	v_mfma_f32_16x16x32_bf16 v[186:189], v[96:99], v[112:115], v[10:13]
	v_mfma_f32_16x16x32_bf16 v[10:13], v[84:87], v[116:119], 0
	v_mfma_f32_16x16x32_bf16 v[190:193], v[88:91], v[120:123], v[10:13]
	v_mfma_f32_16x16x32_bf16 v[10:13], v[92:95], v[116:119], 0
	v_mfma_f32_16x16x32_bf16 v[200:203], v[96:99], v[120:123], v[10:13]
	v_mfma_f32_16x16x32_bf16 v[10:13], v[84:87], v[124:127], 0
	v_mfma_f32_16x16x32_bf16 v[204:207], v[88:91], v[128:131], v[10:13]
	v_mfma_f32_16x16x32_bf16 v[10:13], v[92:95], v[124:127], 0
	v_mfma_f32_16x16x32_bf16 v[208:211], v[96:99], v[128:131], v[10:13]
	s_setprio 0
	s_add_i32 s7, 0, 0x18000
	v_add_u32_e32 v0, s7, v147
	s_barrier
	s_nop 2
	ds_read_b128 v[10:13], v0
	ds_read_b128 v[14:17], v0 offset:1024
	v_mov_b64_e32 v[164:165], v[220:221]
	ds_read_b128 v[218:221], v0 offset:2048
	v_mov_b64_e32 v[58:59], v[222:223]
	ds_read_b128 v[222:225], v0 offset:3072
	s_add_u32 s14, s20, 0x40100
	s_addc_u32 s15, s21, 0
	s_mov_b32 m0, s58
	v_lshl_add_u64 v[78:79], s[14:15], 0, v[138:139]
	ds_read_b128 v[46:49], v149 offset:32768
	ds_read_b128 v[88:91], v149 offset:33792
	ds_read_b128 v[96:99], v149 offset:34816
	ds_read_b128 v[226:229], v149 offset:35840
	ds_read_b128 v[230:233], v149 offset:36864
	ds_read_b128 v[234:237], v149 offset:37888
	ds_read_b128 v[238:241], v149 offset:38912
	ds_read_b128 v[242:245], v149 offset:39936
	global_load_lds_dwordx4 v[78:79], off
	v_lshl_add_u64 v[78:79], s[14:15], 0, v[134:135]
	s_mov_b32 m0, s59
	v_mov_b32_e32 v151, v1
	global_load_lds_dwordx4 v[78:79], off
	s_waitcnt lgkmcnt(8)
	s_barrier
	s_waitcnt lgkmcnt(0)
	s_setprio 1
	v_mfma_f32_16x16x32_bf16 v[50:53], v[10:13], v[46:49], v[50:53]
	v_mfma_f32_16x16x32_bf16 v[124:127], v[14:17], v[88:91], v[50:53]
	v_mfma_f32_16x16x32_bf16 v[50:53], v[218:221], v[46:49], v[194:197]
	v_mfma_f32_16x16x32_bf16 v[116:119], v[222:225], v[88:91], v[50:53]
	v_mfma_f32_16x16x32_bf16 v[50:53], v[10:13], v[96:99], v[212:215]
	v_mfma_f32_16x16x32_bf16 v[108:111], v[14:17], v[226:229], v[50:53]
	v_mfma_f32_16x16x32_bf16 v[50:53], v[218:221], v[96:99], v[62:65]
	v_mfma_f32_16x16x32_bf16 v[100:103], v[222:225], v[226:229], v[50:53]
	v_mfma_f32_16x16x32_bf16 v[50:53], v[10:13], v[230:233], v[66:69]
	v_mfma_f32_16x16x32_bf16 v[92:95], v[14:17], v[234:237], v[50:53]
	v_mfma_f32_16x16x32_bf16 v[50:53], v[218:221], v[230:233], v[70:73]
	v_mfma_f32_16x16x32_bf16 v[84:87], v[222:225], v[234:237], v[50:53]
	v_mfma_f32_16x16x32_bf16 v[50:53], v[10:13], v[238:241], v[74:77]
	v_mfma_f32_16x16x32_bf16 v[76:79], v[14:17], v[242:245], v[50:53]
	v_mfma_f32_16x16x32_bf16 v[50:53], v[218:221], v[238:241], v[80:83]
	v_mfma_f32_16x16x32_bf16 v[64:67], v[222:225], v[242:245], v[50:53]
	s_setprio 0
	s_barrier
	s_add_i32 s9, 0, 0x1c000
	s_add_i32 s7, s7, s25
	v_add_u32_e32 v0, s9, v147
	s_nop 1
	v_lshl_add_u64 v[50:51], v[144:145], 0, s[62:63]
	s_mov_b32 m0, s7
	ds_read_b128 v[246:249], v0
	v_mov_b32_e32 v150, v148
	v_mov_b32_e32 v148, v254
	v_mov_b32_e32 v254, v216
	v_mov_b32_e32 v1, v217
	v_mov_b64_e32 v[216:217], v[252:253]
	ds_read_b128 v[250:253], v0 offset:1024
	ds_read_b128 v[194:197], v0 offset:2048
	ds_read_b128 v[212:215], v0 offset:3072
	global_load_lds_dwordx4 v[50:51], off
	v_lshl_add_u64 v[50:51], v[198:199], 0, s[62:63]
	s_add_i32 m0, s7, 0x2000
	s_nop 0
	global_load_lds_dwordx4 v[50:51], off
	s_barrier
	s_waitcnt lgkmcnt(0)
	s_setprio 1
	v_mfma_f32_16x16x32_bf16 v[18:21], v[194:197], v[46:49], v[18:21]
	v_mfma_f32_16x16x32_bf16 v[120:123], v[212:215], v[88:91], v[18:21]
	v_mfma_f32_16x16x32_bf16 v[18:21], v[246:249], v[96:99], v[22:25]
	v_mfma_f32_16x16x32_bf16 v[112:115], v[250:253], v[226:229], v[18:21]
	v_mfma_f32_16x16x32_bf16 v[18:21], v[194:197], v[96:99], v[26:29]
	v_mfma_f32_16x16x32_bf16 v[50:53], v[246:249], v[46:49], v[104:107]
	v_mfma_f32_16x16x32_bf16 v[104:107], v[212:215], v[226:229], v[18:21]
	v_mfma_f32_16x16x32_bf16 v[18:21], v[246:249], v[230:233], v[30:33]
	v_mfma_f32_16x16x32_bf16 v[96:99], v[250:253], v[234:237], v[18:21]
	v_mfma_f32_16x16x32_bf16 v[18:21], v[194:197], v[230:233], v[34:37]
	v_mfma_f32_16x16x32_bf16 v[128:131], v[250:253], v[88:91], v[50:53]
	v_mfma_f32_16x16x32_bf16 v[88:91], v[212:215], v[234:237], v[18:21]
	v_mfma_f32_16x16x32_bf16 v[18:21], v[246:249], v[238:241], v[38:41]
	v_mfma_f32_16x16x32_bf16 v[80:83], v[250:253], v[242:245], v[18:21]
	v_mfma_f32_16x16x32_bf16 v[18:21], v[194:197], v[238:241], v[42:45]
	v_mfma_f32_16x16x32_bf16 v[72:75], v[212:215], v[242:245], v[18:21]
	s_setprio 0
	s_mov_b32 m0, s60
	s_nop 4
	v_lshl_add_u64 v[18:19], v[140:141], 0, s[62:63]
	s_barrier
	ds_read_b128 v[24:27], v149 offset:49152
	ds_read_b128 v[32:35], v149 offset:50176
	ds_read_b128 v[40:43], v149 offset:51200
	ds_read_b128 v[226:229], v149 offset:52224
	ds_read_b128 v[230:233], v149 offset:53248
	ds_read_b128 v[234:237], v149 offset:54272
	ds_read_b128 v[238:241], v149 offset:55296
	ds_read_b128 v[242:245], v149 offset:56320
	global_load_lds_dwordx4 v[18:19], off
	v_lshl_add_u64 v[18:19], v[142:143], 0, s[62:63]
	s_mov_b32 m0, s61
	s_nop 0
	global_load_lds_dwordx4 v[18:19], off
	s_barrier
	s_waitcnt lgkmcnt(0)
	s_setprio 1
	v_mfma_f32_16x16x32_bf16 v[18:21], v[10:13], v[24:27], v[54:57]
	v_mfma_f32_16x16x32_bf16 v[60:63], v[14:17], v[32:35], v[18:21]
	v_mfma_f32_16x16x32_bf16 v[18:21], v[218:221], v[24:27], v[152:155]
	v_mfma_f32_16x16x32_bf16 v[52:55], v[222:225], v[32:35], v[18:21]
	v_mfma_f32_16x16x32_bf16 v[18:21], v[10:13], v[40:43], v[156:159]
	v_mfma_f32_16x16x32_bf16 v[44:47], v[14:17], v[226:229], v[18:21]
	v_mfma_f32_16x16x32_bf16 v[18:21], v[218:221], v[40:43], v[160:163]
	v_mfma_f32_16x16x32_bf16 v[36:39], v[222:225], v[226:229], v[18:21]
	v_mfma_f32_16x16x32_bf16 v[18:21], v[10:13], v[230:233], v[166:169]
	v_mfma_f32_16x16x32_bf16 v[2:5], v[10:13], v[238:241], v[2:5]
	v_mfma_f32_16x16x32_bf16 v[28:31], v[14:17], v[234:237], v[18:21]
	v_mfma_f32_16x16x32_bf16 v[18:21], v[218:221], v[230:233], v[170:173]
	v_mfma_f32_16x16x32_bf16 v[12:15], v[14:17], v[242:245], v[2:5]
	v_mfma_f32_16x16x32_bf16 v[2:5], v[218:221], v[238:241], v[6:9]
	v_mov_b64_e32 v[220:221], v[164:165]
	v_mfma_f32_16x16x32_bf16 v[20:23], v[222:225], v[234:237], v[18:21]
	v_mfma_f32_16x16x32_bf16 v[4:7], v[222:225], v[242:245], v[2:5]
	v_mov_b64_e32 v[222:223], v[58:59]
	s_setprio 0
	s_barrier
	s_add_u32 s14, s18, 0x40180
	s_addc_u32 s15, s19, 0
	s_add_i32 s7, s9, s25
	v_lshl_add_u64 v[2:3], s[14:15], 0, v[136:137]
	s_mov_b32 m0, s7
	s_nop 0
	global_load_lds_dwordx4 v[2:3], off
	v_lshl_add_u64 v[2:3], s[14:15], 0, v[132:133]
	s_add_i32 m0, s7, 0x2000
	s_nop 0
	global_load_lds_dwordx4 v[2:3], off
	s_waitcnt vmcnt(6)
	s_barrier
	s_setprio 1
	v_mfma_f32_16x16x32_bf16 v[8:11], v[246:249], v[24:27], v[174:177]
	v_mfma_f32_16x16x32_bf16 v[68:71], v[250:253], v[32:35], v[8:11]
	v_mfma_f32_16x16x32_bf16 v[8:11], v[194:197], v[24:27], v[178:181]
	v_mfma_f32_16x16x32_bf16 v[56:59], v[212:215], v[32:35], v[8:11]
	v_mfma_f32_16x16x32_bf16 v[8:11], v[246:249], v[40:43], v[182:185]
	v_mfma_f32_16x16x32_bf16 v[48:51], v[250:253], v[226:229], v[8:11]
	v_mfma_f32_16x16x32_bf16 v[8:11], v[194:197], v[40:43], v[186:189]
	v_mfma_f32_16x16x32_bf16 v[40:43], v[212:215], v[226:229], v[8:11]
	v_mfma_f32_16x16x32_bf16 v[8:11], v[246:249], v[230:233], v[190:193]
	v_mfma_f32_16x16x32_bf16 v[32:35], v[250:253], v[234:237], v[8:11]
	v_mfma_f32_16x16x32_bf16 v[8:11], v[194:197], v[230:233], v[200:203]
	v_mfma_f32_16x16x32_bf16 v[24:27], v[212:215], v[234:237], v[8:11]
	v_mfma_f32_16x16x32_bf16 v[8:11], v[246:249], v[238:241], v[204:207]
	v_mfma_f32_16x16x32_bf16 v[16:19], v[250:253], v[242:245], v[8:11]
	v_mov_b64_e32 v[252:253], v[216:217]
	v_mov_b32_e32 v217, v1
	v_mov_b32_e32 v216, v254
	v_mfma_f32_16x16x32_bf16 v[8:11], v[194:197], v[238:241], v[208:211]
	v_mov_b32_e32 v254, v148
	v_mov_b32_e32 v148, v150
	v_mov_b32_e32 v1, v151
	v_mfma_f32_16x16x32_bf16 v[8:11], v[212:215], v[242:245], v[8:11]
	s_setprio 0
	s_barrier
	s_mov_b32 s22, 2
	s_branch .LBB0_527

.LBB0_528:
	s_add_u32 s20, s81, s46
	s_addc_u32 s21, s82, 0
	s_add_u32 s83, s79, s46
	s_addc_u32 s84, s80, 0
	s_add_i32 s85, 0, 0x10000
	v_add_u32_e32 v0, s85, v147
	ds_read_b128 v[150:153], v0
	ds_read_b128 v[154:157], v0 offset:1024
	ds_read_b128 v[158:161], v0 offset:2048
	ds_read_b128 v[162:165], v0 offset:3072
	s_cmp_eq_u32 s46, s18
	s_cselect_b32 s23, s9, s21
	s_cselect_b32 s22, s76, s20
	s_cselect_b32 s21, s7, s84
	s_cselect_b32 s20, s77, s83
	s_add_i32 s84, s11, 0xc000
	v_lshl_add_u64 v[140:141], v[144:145], 0, s[46:47]
	s_mov_b32 m0, s84
	s_add_i32 s83, s11, 0xe000
	ds_read_b128 v[166:169], v149
	ds_read_b128 v[170:173], v149 offset:1024
	ds_read_b128 v[174:177], v149 offset:2048
	ds_read_b128 v[178:181], v149 offset:3072
	ds_read_b128 v[182:185], v149 offset:4096
	ds_read_b128 v[186:189], v149 offset:5120
	ds_read_b128 v[190:193], v149 offset:6144
	ds_read_b128 v[194:197], v149 offset:7168
	global_load_lds_dwordx4 v[140:141], off
	v_lshl_add_u64 v[140:141], v[2:3], 0, s[46:47]
	s_mov_b32 m0, s83
	s_nop 0
	global_load_lds_dwordx4 v[140:141], off
	s_waitcnt lgkmcnt(8)
	s_barrier
	s_waitcnt lgkmcnt(0)
	s_setprio 1
	v_mfma_f32_16x16x32_bf16 v[124:127], v[150:153], v[166:169], v[124:127]
	v_mfma_f32_16x16x32_bf16 v[116:119], v[158:161], v[166:169], v[116:119]
	v_mfma_f32_16x16x32_bf16 v[108:111], v[150:153], v[174:177], v[108:111]
	v_mfma_f32_16x16x32_bf16 v[100:103], v[158:161], v[174:177], v[100:103]
	v_mfma_f32_16x16x32_bf16 v[92:95], v[150:153], v[182:185], v[92:95]
	v_mfma_f32_16x16x32_bf16 v[84:87], v[158:161], v[182:185], v[84:87]
	v_mfma_f32_16x16x32_bf16 v[76:79], v[150:153], v[190:193], v[76:79]
	v_mfma_f32_16x16x32_bf16 v[64:67], v[158:161], v[190:193], v[64:67]
	v_mfma_f32_16x16x32_bf16 v[124:127], v[154:157], v[170:173], v[124:127]
	v_mfma_f32_16x16x32_bf16 v[116:119], v[162:165], v[170:173], v[116:119]
	v_mfma_f32_16x16x32_bf16 v[108:111], v[154:157], v[178:181], v[108:111]
	v_mfma_f32_16x16x32_bf16 v[100:103], v[162:165], v[178:181], v[100:103]
	v_mfma_f32_16x16x32_bf16 v[92:95], v[154:157], v[186:189], v[92:95]
	v_mfma_f32_16x16x32_bf16 v[84:87], v[162:165], v[186:189], v[84:87]
	v_mfma_f32_16x16x32_bf16 v[76:79], v[154:157], v[194:197], v[76:79]
	v_mfma_f32_16x16x32_bf16 v[64:67], v[162:165], v[194:197], v[64:67]
	s_setprio 0
	s_barrier
	s_add_i32 s88, 0, 0x14000
	s_add_i32 s85, s85, s25
	v_add_u32_e32 v0, s88, v147
	v_lshl_add_u64 v[140:141], s[20:21], 0, v[136:137]
	s_mov_b32 m0, s85
	ds_read_b128 v[200:203], v0
	ds_read_b128 v[204:207], v0 offset:1024
	ds_read_b128 v[208:211], v0 offset:2048
	ds_read_b128 v[212:215], v0 offset:3072
	global_load_lds_dwordx4 v[140:141], off
	v_lshl_add_u64 v[142:143], s[20:21], 0, v[132:133]
	s_add_i32 m0, s85, 0x2000
	s_nop 0
	global_load_lds_dwordx4 v[142:143], off
	s_barrier
	s_waitcnt lgkmcnt(0)
	s_setprio 1
	v_mfma_f32_16x16x32_bf16 v[128:131], v[200:203], v[166:169], v[128:131]
	v_mfma_f32_16x16x32_bf16 v[120:123], v[208:211], v[166:169], v[120:123]
	v_mfma_f32_16x16x32_bf16 v[112:115], v[200:203], v[174:177], v[112:115]
	v_mfma_f32_16x16x32_bf16 v[104:107], v[208:211], v[174:177], v[104:107]
	v_mfma_f32_16x16x32_bf16 v[96:99], v[200:203], v[182:185], v[96:99]
	v_mfma_f32_16x16x32_bf16 v[88:91], v[208:211], v[182:185], v[88:91]
	v_mfma_f32_16x16x32_bf16 v[80:83], v[200:203], v[190:193], v[80:83]
	v_mfma_f32_16x16x32_bf16 v[72:75], v[208:211], v[190:193], v[72:75]
	v_mfma_f32_16x16x32_bf16 v[128:131], v[204:207], v[170:173], v[128:131]
	v_mfma_f32_16x16x32_bf16 v[120:123], v[212:215], v[170:173], v[120:123]
	v_mfma_f32_16x16x32_bf16 v[112:115], v[204:207], v[178:181], v[112:115]
	v_mfma_f32_16x16x32_bf16 v[104:107], v[212:215], v[178:181], v[104:107]
	v_mfma_f32_16x16x32_bf16 v[96:99], v[204:207], v[186:189], v[96:99]
	v_mfma_f32_16x16x32_bf16 v[88:91], v[212:215], v[186:189], v[88:91]
	v_mfma_f32_16x16x32_bf16 v[80:83], v[204:207], v[194:197], v[80:83]
	v_mfma_f32_16x16x32_bf16 v[72:75], v[212:215], v[194:197], v[72:75]
	s_setprio 0
	s_mov_b32 m0, s11
	v_lshl_add_u64 v[198:199], s[22:23], 0, v[138:139]
	s_barrier
	ds_read_b128 v[166:169], v149 offset:16384
	ds_read_b128 v[170:173], v149 offset:17408
	ds_read_b128 v[174:177], v149 offset:18432
	ds_read_b128 v[178:181], v149 offset:19456
	ds_read_b128 v[182:185], v149 offset:20480
	ds_read_b128 v[186:189], v149 offset:21504
	ds_read_b128 v[190:193], v149 offset:22528
	ds_read_b128 v[194:197], v149 offset:23552
	global_load_lds_dwordx4 v[198:199], off
	v_lshl_add_u64 v[218:219], s[22:23], 0, v[134:135]
	s_mov_b32 m0, s57
	s_nop 0
	global_load_lds_dwordx4 v[218:219], off
	s_barrier
	s_waitcnt lgkmcnt(0)
	s_setprio 1
	v_mfma_f32_16x16x32_bf16 v[60:63], v[150:153], v[166:169], v[60:63]
	v_mfma_f32_16x16x32_bf16 v[52:55], v[158:161], v[166:169], v[52:55]
	v_mfma_f32_16x16x32_bf16 v[44:47], v[150:153], v[174:177], v[44:47]
	v_mfma_f32_16x16x32_bf16 v[36:39], v[158:161], v[174:177], v[36:39]
	v_mfma_f32_16x16x32_bf16 v[28:31], v[150:153], v[182:185], v[28:31]
	v_mfma_f32_16x16x32_bf16 v[20:23], v[158:161], v[182:185], v[20:23]
	v_mfma_f32_16x16x32_bf16 v[12:15], v[150:153], v[190:193], v[12:15]
	v_mfma_f32_16x16x32_bf16 v[4:7], v[158:161], v[190:193], v[4:7]
	v_mfma_f32_16x16x32_bf16 v[60:63], v[154:157], v[170:173], v[60:63]
	v_mfma_f32_16x16x32_bf16 v[52:55], v[162:165], v[170:173], v[52:55]
	v_mfma_f32_16x16x32_bf16 v[44:47], v[154:157], v[178:181], v[44:47]
	v_mfma_f32_16x16x32_bf16 v[36:39], v[162:165], v[178:181], v[36:39]
	v_mfma_f32_16x16x32_bf16 v[28:31], v[154:157], v[186:189], v[28:31]
	v_mfma_f32_16x16x32_bf16 v[20:23], v[162:165], v[186:189], v[20:23]
	v_mfma_f32_16x16x32_bf16 v[12:15], v[154:157], v[194:197], v[12:15]
	v_mfma_f32_16x16x32_bf16 v[4:7], v[162:165], v[194:197], v[4:7]
	s_setprio 0
	s_barrier
	s_add_u32 s86, s20, 0x40000
	s_addc_u32 s87, s21, 0
	s_add_i32 s85, s88, s25
	v_lshl_add_u64 v[150:151], s[86:87], 0, v[136:137]
	s_mov_b32 m0, s85
	s_nop 0
	global_load_lds_dwordx4 v[150:151], off
	v_lshl_add_u64 v[150:151], s[86:87], 0, v[132:133]
	s_add_i32 m0, s85, 0x2000
	s_nop 0
	global_load_lds_dwordx4 v[150:151], off
	s_waitcnt vmcnt(6)
	s_barrier
	s_setprio 1
	v_mfma_f32_16x16x32_bf16 v[68:71], v[200:203], v[166:169], v[68:71]
	v_mfma_f32_16x16x32_bf16 v[56:59], v[208:211], v[166:169], v[56:59]
	v_mfma_f32_16x16x32_bf16 v[48:51], v[200:203], v[174:177], v[48:51]
	v_mfma_f32_16x16x32_bf16 v[40:43], v[208:211], v[174:177], v[40:43]
	v_mfma_f32_16x16x32_bf16 v[32:35], v[200:203], v[182:185], v[32:35]
	v_mfma_f32_16x16x32_bf16 v[24:27], v[208:211], v[182:185], v[24:27]
	v_mfma_f32_16x16x32_bf16 v[16:19], v[200:203], v[190:193], v[16:19]
	v_mfma_f32_16x16x32_bf16 v[8:11], v[208:211], v[190:193], v[8:11]
	v_mfma_f32_16x16x32_bf16 v[68:71], v[204:207], v[170:173], v[68:71]
	v_mfma_f32_16x16x32_bf16 v[56:59], v[212:215], v[170:173], v[56:59]
	v_mfma_f32_16x16x32_bf16 v[48:51], v[204:207], v[178:181], v[48:51]
	v_mfma_f32_16x16x32_bf16 v[40:43], v[212:215], v[178:181], v[40:43]
	v_mfma_f32_16x16x32_bf16 v[32:35], v[204:207], v[186:189], v[32:35]
	v_mfma_f32_16x16x32_bf16 v[24:27], v[212:215], v[186:189], v[24:27]
	v_mfma_f32_16x16x32_bf16 v[16:19], v[204:207], v[194:197], v[16:19]
	v_mfma_f32_16x16x32_bf16 v[8:11], v[212:215], v[194:197], v[8:11]
	s_setprio 0
	s_add_i32 s85, 0, 0x18000
	v_add_u32_e32 v0, s85, v147
	s_barrier
	ds_read_b128 v[150:153], v0
	ds_read_b128 v[154:157], v0 offset:1024
	ds_read_b128 v[158:161], v0 offset:2048
	ds_read_b128 v[162:165], v0 offset:3072
	s_add_u32 s22, s22, 0x40000
	s_addc_u32 s23, s23, 0
	s_mov_b32 m0, s58
	v_lshl_add_u64 v[200:201], s[22:23], 0, v[138:139]
	ds_read_b128 v[166:169], v149 offset:32768
	ds_read_b128 v[170:173], v149 offset:33792
	ds_read_b128 v[174:177], v149 offset:34816
	ds_read_b128 v[178:181], v149 offset:35840
	ds_read_b128 v[182:185], v149 offset:36864
	ds_read_b128 v[186:189], v149 offset:37888
	ds_read_b128 v[190:193], v149 offset:38912
	ds_read_b128 v[194:197], v149 offset:39936
	global_load_lds_dwordx4 v[200:201], off
	v_lshl_add_u64 v[200:201], s[22:23], 0, v[134:135]
	s_mov_b32 m0, s59
	s_nop 0
	global_load_lds_dwordx4 v[200:201], off
	s_waitcnt lgkmcnt(8)
	s_barrier
	s_waitcnt lgkmcnt(0)
	s_setprio 1
	v_mfma_f32_16x16x32_bf16 v[124:127], v[150:153], v[166:169], v[124:127]
	v_mfma_f32_16x16x32_bf16 v[116:119], v[158:161], v[166:169], v[116:119]
	v_mfma_f32_16x16x32_bf16 v[108:111], v[150:153], v[174:177], v[108:111]
	v_mfma_f32_16x16x32_bf16 v[100:103], v[158:161], v[174:177], v[100:103]
	v_mfma_f32_16x16x32_bf16 v[92:95], v[150:153], v[182:185], v[92:95]
	v_mfma_f32_16x16x32_bf16 v[84:87], v[158:161], v[182:185], v[84:87]
	v_mfma_f32_16x16x32_bf16 v[76:79], v[150:153], v[190:193], v[76:79]
	v_mfma_f32_16x16x32_bf16 v[64:67], v[158:161], v[190:193], v[64:67]
	v_mfma_f32_16x16x32_bf16 v[124:127], v[154:157], v[170:173], v[124:127]
	v_mfma_f32_16x16x32_bf16 v[116:119], v[162:165], v[170:173], v[116:119]
	v_mfma_f32_16x16x32_bf16 v[108:111], v[154:157], v[178:181], v[108:111]
	v_mfma_f32_16x16x32_bf16 v[100:103], v[162:165], v[178:181], v[100:103]
	v_mfma_f32_16x16x32_bf16 v[92:95], v[154:157], v[186:189], v[92:95]
	v_mfma_f32_16x16x32_bf16 v[84:87], v[162:165], v[186:189], v[84:87]
	v_mfma_f32_16x16x32_bf16 v[76:79], v[154:157], v[194:197], v[76:79]
	v_mfma_f32_16x16x32_bf16 v[64:67], v[162:165], v[194:197], v[64:67]
	s_setprio 0
	s_barrier
	s_add_i32 s22, 0, 0x1c000
	s_add_i32 s23, s85, s25
	v_add_u32_e32 v0, s22, v147
	v_lshl_add_u64 v[140:141], v[140:141], 0, s[48:49]
	s_mov_b32 m0, s23
	ds_read_b128 v[200:203], v0
	ds_read_b128 v[204:207], v0 offset:1024
	ds_read_b128 v[208:211], v0 offset:2048
	ds_read_b128 v[212:215], v0 offset:3072
	global_load_lds_dwordx4 v[140:141], off
	v_lshl_add_u64 v[140:141], v[142:143], 0, s[48:49]
	s_add_i32 m0, s23, 0x2000
	s_nop 0
	global_load_lds_dwordx4 v[140:141], off
	s_barrier
	s_waitcnt lgkmcnt(0)
	s_setprio 1
	v_mfma_f32_16x16x32_bf16 v[128:131], v[200:203], v[166:169], v[128:131]
	v_mfma_f32_16x16x32_bf16 v[120:123], v[208:211], v[166:169], v[120:123]
	v_mfma_f32_16x16x32_bf16 v[112:115], v[200:203], v[174:177], v[112:115]
	v_mfma_f32_16x16x32_bf16 v[104:107], v[208:211], v[174:177], v[104:107]
	v_mfma_f32_16x16x32_bf16 v[96:99], v[200:203], v[182:185], v[96:99]
	v_mfma_f32_16x16x32_bf16 v[88:91], v[208:211], v[182:185], v[88:91]
	v_mfma_f32_16x16x32_bf16 v[80:83], v[200:203], v[190:193], v[80:83]
	v_mfma_f32_16x16x32_bf16 v[72:75], v[208:211], v[190:193], v[72:75]
	v_mfma_f32_16x16x32_bf16 v[128:131], v[204:207], v[170:173], v[128:131]
	v_mfma_f32_16x16x32_bf16 v[120:123], v[212:215], v[170:173], v[120:123]
	v_mfma_f32_16x16x32_bf16 v[112:115], v[204:207], v[178:181], v[112:115]
	v_mfma_f32_16x16x32_bf16 v[104:107], v[212:215], v[178:181], v[104:107]
	v_mfma_f32_16x16x32_bf16 v[96:99], v[204:207], v[186:189], v[96:99]
	v_mfma_f32_16x16x32_bf16 v[88:91], v[212:215], v[186:189], v[88:91]
	v_mfma_f32_16x16x32_bf16 v[80:83], v[204:207], v[194:197], v[80:83]
	v_mfma_f32_16x16x32_bf16 v[72:75], v[212:215], v[194:197], v[72:75]
	s_setprio 0
	s_mov_b32 m0, s60
	v_lshl_add_u64 v[140:141], v[198:199], 0, s[48:49]
	s_barrier
	ds_read_b128 v[166:169], v149 offset:49152
	ds_read_b128 v[170:173], v149 offset:50176
	ds_read_b128 v[174:177], v149 offset:51200
	ds_read_b128 v[178:181], v149 offset:52224
	ds_read_b128 v[182:185], v149 offset:53248
	ds_read_b128 v[186:189], v149 offset:54272
	ds_read_b128 v[190:193], v149 offset:55296
	ds_read_b128 v[194:197], v149 offset:56320
	global_load_lds_dwordx4 v[140:141], off
	v_lshl_add_u64 v[140:141], v[218:219], 0, s[48:49]
	s_mov_b32 m0, s61
	s_nop 0
	global_load_lds_dwordx4 v[140:141], off
	s_barrier
; DEVI unsigned cvtpk(float lo, float hi) { unsigned r; asm volatile("v_cvt_pk_bf16_f32 %0, %1, %2" : "=v"(r) : "v"(lo), "v"(hi)); return r; }
; DEVI float sigmoidf_(float x) { return __builtin_amdgcn_rcpf(1.f + __expf(-x)); }
;     DEVI void operator()(AccRef acc, const pg8::Unit& u, int wr, int wc, int fr, int fq) const {
;         const int row0 = u.pm * 256 + wr * 64 + fr, col = u.pn * 128 + wc * 32 + 8 * fq;
; #pragma unroll
;         for (int ai = 0; ai < 2; ++ai)
; #pragma unroll
;             for (int m = 0; m < 4; ++m) { bf16_t* rowp = Hm + (size_t)(row0 + ai * 128 + m * 16) * DFF + col; float h[8];
; #pragma unroll
;                 for (int j = 0; j < 8; ++j) { const float gt = acc[ai][0][m][j >> 2][j & 3], up = acc[ai][1][m][j >> 2][j & 3]; h[j] = gt * sigmoidf_(gt) * up; }
;                 u32x4 w; w.x = cvtpk(h[0], h[1]); w.y = cvtpk(h[2], h[3]); w.z = cvtpk(h[4], h[5]); w.w = cvtpk(h[6], h[7]);
;                 if (ai == 0 && m == 0) asm volatile("s_waitcnt vmcnt(0)" ::: "memory");
;                 __builtin_nontemporal_store(w, (u32x4*)rowp); }
	s_waitcnt lgkmcnt(0)
	s_setprio 1
	v_mfma_f32_16x16x32_bf16 v[60:63], v[150:153], v[166:169], v[60:63]
	v_mfma_f32_16x16x32_bf16 v[52:55], v[158:161], v[166:169], v[52:55]
	v_mfma_f32_16x16x32_bf16 v[44:47], v[150:153], v[174:177], v[44:47]
	v_mfma_f32_16x16x32_bf16 v[36:39], v[158:161], v[174:177], v[36:39]
	v_mfma_f32_16x16x32_bf16 v[28:31], v[150:153], v[182:185], v[28:31]
	v_mfma_f32_16x16x32_bf16 v[20:23], v[158:161], v[182:185], v[20:23]
	v_mfma_f32_16x16x32_bf16 v[12:15], v[150:153], v[190:193], v[12:15]
	v_mfma_f32_16x16x32_bf16 v[4:7], v[158:161], v[190:193], v[4:7]
	v_mfma_f32_16x16x32_bf16 v[60:63], v[154:157], v[170:173], v[60:63]
	v_mfma_f32_16x16x32_bf16 v[52:55], v[162:165], v[170:173], v[52:55]
	v_mfma_f32_16x16x32_bf16 v[44:47], v[154:157], v[178:181], v[44:47]
	v_mfma_f32_16x16x32_bf16 v[36:39], v[162:165], v[178:181], v[36:39]
	v_mfma_f32_16x16x32_bf16 v[28:31], v[154:157], v[186:189], v[28:31]
	v_mfma_f32_16x16x32_bf16 v[20:23], v[162:165], v[186:189], v[20:23]
	v_mfma_f32_16x16x32_bf16 v[12:15], v[154:157], v[194:197], v[12:15]
	v_mfma_f32_16x16x32_bf16 v[4:7], v[162:165], v[194:197], v[4:7]
	s_setprio 0
	s_barrier
	s_add_u32 s20, s20, 0x40080
	s_addc_u32 s21, s21, 0
	s_add_i32 s22, s22, s25
	v_lshl_add_u64 v[140:141], s[20:21], 0, v[136:137]
	s_mov_b32 m0, s22
	s_nop 0
	global_load_lds_dwordx4 v[140:141], off
	v_lshl_add_u64 v[140:141], s[20:21], 0, v[132:133]
	s_add_i32 m0, s22, 0x2000
	s_nop 0
	global_load_lds_dwordx4 v[140:141], off
	s_waitcnt vmcnt(6)
	s_barrier
	s_setprio 1
	v_mfma_f32_16x16x32_bf16 v[68:71], v[200:203], v[166:169], v[68:71]
	v_mfma_f32_16x16x32_bf16 v[56:59], v[208:211], v[166:169], v[56:59]
	v_mfma_f32_16x16x32_bf16 v[48:51], v[200:203], v[174:177], v[48:51]
	v_mfma_f32_16x16x32_bf16 v[40:43], v[208:211], v[174:177], v[40:43]
	v_mfma_f32_16x16x32_bf16 v[32:35], v[200:203], v[182:185], v[32:35]
	v_mfma_f32_16x16x32_bf16 v[24:27], v[208:211], v[182:185], v[24:27]
	v_mfma_f32_16x16x32_bf16 v[16:19], v[200:203], v[190:193], v[16:19]
	v_mfma_f32_16x16x32_bf16 v[8:11], v[208:211], v[190:193], v[8:11]
	v_mfma_f32_16x16x32_bf16 v[68:71], v[204:207], v[170:173], v[68:71]
	v_mfma_f32_16x16x32_bf16 v[56:59], v[212:215], v[170:173], v[56:59]
	v_mfma_f32_16x16x32_bf16 v[48:51], v[204:207], v[178:181], v[48:51]
	v_mfma_f32_16x16x32_bf16 v[40:43], v[212:215], v[178:181], v[40:43]
	v_mfma_f32_16x16x32_bf16 v[32:35], v[204:207], v[186:189], v[32:35]
	v_mfma_f32_16x16x32_bf16 v[24:27], v[212:215], v[186:189], v[24:27]
	v_mfma_f32_16x16x32_bf16 v[16:19], v[204:207], v[194:197], v[16:19]
	v_mfma_f32_16x16x32_bf16 v[8:11], v[212:215], v[194:197], v[8:11]
	s_setprio 0
	s_add_i32 s78, s78, 2
	s_add_u32 s79, s79, 0x100
	s_addc_u32 s80, s80, 0
	s_add_u32 s81, s81, 0x100
	s_addc_u32 s82, s82, 0
	s_add_u32 s18, s18, 0xffffff00
	s_addc_u32 s19, s19, -1
	v_lshl_add_u64 v[2:3], v[2:3], 0, s[50:51]
	s_cmp_gt_u32 s78, 13
	v_lshl_add_u64 v[144:145], v[144:145], 0, s[50:51]
	s_barrier
	s_cbranch_scc0 .LBB0_528
	s_add_u32 s18, s76, 0x40080
	s_addc_u32 s19, s9, 0
	s_mov_b32 m0, s84
	v_lshl_add_u64 v[2:3], s[18:19], 0, v[138:139]
	global_load_lds_dwordx4 v[2:3], off
	v_lshl_add_u64 v[2:3], s[18:19], 0, v[134:135]
	s_mov_b32 m0, s83
	v_lshl_or_b32 v140, s75, 7, v148
	global_load_lds_dwordx4 v[2:3], off
	v_mul_f32_e32 v2, 0xbfb8aa3b, v124
	v_exp_f32_e32 v142, v2
	v_mul_f32_e32 v2, 0xbfb8aa3b, v125
	v_exp_f32_e32 v143, v2
	v_lshl_add_u32 v0, s10, 8, v146
	v_add_f32_e32 v142, 1.0, v142
	v_rcp_f32_e32 v144, v142
	v_add_f32_e32 v142, 1.0, v143
	v_rcp_f32_e32 v145, v142
	v_ashrrev_i32_e32 v141, 31, v140
	v_mul_f32_e32 v124, v124, v144
	v_mul_f32_e32 v124, v124, v128
	v_mul_f32_e32 v128, 0xbfb8aa3b, v126
	v_mul_f32_e32 v144, 0xbfb8aa3b, v127
	v_exp_f32_e32 v128, v128
	v_exp_f32_e32 v144, v144
	v_mul_f32_e32 v125, v125, v145
	v_mul_f32_e32 v125, v125, v129
	v_add_f32_e32 v128, 1.0, v128
	v_add_f32_e32 v129, 1.0, v144
	v_mul_f32_e32 v144, 0xbfb8aa3b, v116
	v_rcp_f32_e32 v128, v128
	v_exp_f32_e32 v144, v144
	v_rcp_f32_e32 v129, v129
	v_mov_b64_e32 v[2:3], s[68:69]
	v_mul_f32_e32 v126, v126, v128
	v_add_f32_e32 v128, 1.0, v144
	v_mul_f32_e32 v127, v127, v129
	v_rcp_f32_e32 v128, v128
	v_mul_f32_e32 v129, 0xbfb8aa3b, v117
	v_exp_f32_e32 v129, v129
	v_mad_i64_i32 v[142:143], s[18:19], v0, s3, v[2:3]
	v_mul_f32_e32 v116, v116, v128
	v_mul_f32_e32 v120, v116, v120
	v_add_f32_e32 v116, 1.0, v129
	v_mul_f32_e32 v128, 0xbfb8aa3b, v118
	v_rcp_f32_e32 v116, v116
	v_exp_f32_e32 v128, v128
	v_mul_f32_e32 v129, 0xbfb8aa3b, v119
	v_exp_f32_e32 v129, v129
	v_mul_f32_e32 v116, v117, v116
	v_add_f32_e32 v117, 1.0, v128
	v_rcp_f32_e32 v117, v117
	v_mul_f32_e32 v121, v116, v121
	v_add_f32_e32 v128, 1.0, v129
	v_rcp_f32_e32 v128, v128
	v_mul_f32_e32 v116, v118, v117
	v_cvt_pk_bf16_f32 v118, v124, v125
	v_mul_f32_e32 v124, 0xbfb8aa3b, v108
	v_exp_f32_e32 v124, v124
	v_mul_f32_e32 v125, 0xbfb8aa3b, v109
	v_exp_f32_e32 v125, v125
	v_mul_f32_e32 v129, v116, v122
	v_add_f32_e32 v124, 1.0, v124
	v_rcp_f32_e32 v124, v124
	v_mul_f32_e32 v116, v119, v128
	v_mul_f32_e32 v128, v116, v123
	v_lshlrev_b64 v[116:117], 1, v[140:141]
	v_lshl_add_u64 v[122:123], v[142:143], 0, v[116:117]
	v_add_f32_e32 v125, 1.0, v125
	v_mul_f32_e32 v108, v108, v124
	v_mul_f32_e32 v126, v126, v130
	v_mul_f32_e32 v127, v127, v131
	v_cvt_pk_bf16_f32 v119, v126, v127
	v_cvt_pk_bf16_f32 v120, v120, v121
	v_cvt_pk_bf16_f32 v121, v129, v128
	s_waitcnt vmcnt(0)
; DEVI unsigned cvtpk(float lo, float hi) { unsigned r; asm volatile("v_cvt_pk_bf16_f32 %0, %1, %2" : "=v"(r) : "v"(lo), "v"(hi)); return r; }
; DEVI float sigmoidf_(float x) { return __builtin_amdgcn_rcpf(1.f + __expf(-x)); }
;     DEVI void operator()(AccRef acc, const pg8::Unit& u, int wr, int wc, int fr, int fq) const {
;     ...
;         for (int ai = 0; ai < 2; ++ai)
; #pragma unroll
;             for (int m = 0; m < 4; ++m) { bf16_t* rowp = Hm + (size_t)(row0 + ai * 128 + m * 16) * DFF + col; float h[8];
; #pragma unroll
;                 for (int j = 0; j < 8; ++j) { const float gt = acc[ai][0][m][j >> 2][j & 3], up = acc[ai][1][m][j >> 2][j & 3]; h[j] = gt * sigmoidf_(gt) * up; }
;                 u32x4 w; w.x = cvtpk(h[0], h[1]); w.y = cvtpk(h[2], h[3]); w.z = cvtpk(h[4], h[5]); w.w = cvtpk(h[6], h[7]);
;                 if (ai == 0 && m == 0) asm volatile("s_waitcnt vmcnt(0)" ::: "memory");
;                 __builtin_nontemporal_store(w, (u32x4*)rowp); }
	v_rcp_f32_e32 v125, v125
	flat_store_dwordx4 v[122:123], v[118:121]
	v_mul_f32_e32 v108, v108, v112
	v_mul_f32_e32 v112, 0xbfb8aa3b, v110
	v_mul_f32_e32 v118, 0xbfb8aa3b, v111
	v_exp_f32_e32 v112, v112
	v_exp_f32_e32 v118, v118
	v_mul_f32_e32 v109, v109, v125
	v_mul_f32_e32 v109, v109, v113
	v_add_f32_e32 v112, 1.0, v112
	v_add_f32_e32 v113, 1.0, v118
	v_mul_f32_e32 v118, 0xbfb8aa3b, v100
	v_rcp_f32_e32 v112, v112
	v_exp_f32_e32 v118, v118
	v_rcp_f32_e32 v113, v113
	s_mov_b64 s[22:23], -1
	v_mul_f32_e32 v110, v110, v112
	v_add_f32_e32 v112, 1.0, v118
	v_mul_f32_e32 v111, v111, v113
	v_rcp_f32_e32 v112, v112
	v_mul_f32_e32 v113, 0xbfb8aa3b, v101
	v_exp_f32_e32 v113, v113
	v_mul_f32_e32 v110, v110, v114
	v_mul_f32_e32 v100, v100, v112
	v_mul_f32_e32 v104, v100, v104
	v_add_f32_e32 v100, 1.0, v113
	v_mul_f32_e32 v112, 0xbfb8aa3b, v102
	v_rcp_f32_e32 v100, v100
	v_exp_f32_e32 v112, v112
	v_mul_f32_e32 v113, 0xbfb8aa3b, v103
	v_exp_f32_e32 v113, v113
	v_mul_f32_e32 v100, v101, v100
	v_add_f32_e32 v101, 1.0, v112
	v_rcp_f32_e32 v101, v101
	v_add_f32_e32 v112, 1.0, v113
	v_rcp_f32_e32 v112, v112
	v_mul_f32_e32 v105, v100, v105
	v_mul_f32_e32 v100, v102, v101
	v_mul_f32_e32 v106, v100, v106
	v_mul_f32_e32 v100, v103, v112
	v_mul_f32_e32 v103, v100, v107
	v_mul_f32_e32 v111, v111, v115
	v_cvt_pk_bf16_f32 v100, v108, v109
	v_cvt_pk_bf16_f32 v101, v110, v111
	v_cvt_pk_bf16_f32 v102, v104, v105
	v_cvt_pk_bf16_f32 v103, v106, v103
	v_mul_f32_e32 v106, 0xbfb8aa3b, v92
	v_exp_f32_e32 v106, v106
	v_mul_f32_e32 v107, 0xbfb8aa3b, v93
	v_exp_f32_e32 v107, v107
	v_or_b32_e32 v104, 16, v0
	v_add_f32_e32 v106, 1.0, v106
	v_rcp_f32_e32 v106, v106
	v_mad_i64_i32 v[104:105], s[18:19], v104, s3, v[2:3]
	v_lshl_add_u64 v[104:105], v[104:105], 0, v[116:117]
	v_add_f32_e32 v107, 1.0, v107
	v_mul_f32_e32 v92, v92, v106
	v_rcp_f32_e32 v107, v107
	flat_store_dwordx4 v[104:105], v[100:103]
	v_mul_f32_e32 v92, v92, v96
	v_mul_f32_e32 v96, 0xbfb8aa3b, v94
	v_mul_f32_e32 v100, 0xbfb8aa3b, v95
	v_exp_f32_e32 v96, v96
	v_exp_f32_e32 v100, v100
	v_mul_f32_e32 v93, v93, v107
	v_mul_f32_e32 v93, v93, v97
	v_add_f32_e32 v96, 1.0, v96
	v_add_f32_e32 v97, 1.0, v100
	v_mul_f32_e32 v100, 0xbfb8aa3b, v84
	v_rcp_f32_e32 v96, v96
	v_exp_f32_e32 v100, v100
	v_rcp_f32_e32 v97, v97
	s_and_b64 vcc, exec, s[4:5]
	v_mul_f32_e32 v94, v94, v96
	v_add_f32_e32 v96, 1.0, v100
	v_mul_f32_e32 v95, v95, v97
	v_rcp_f32_e32 v96, v96
	v_mul_f32_e32 v97, 0xbfb8aa3b, v85
	v_exp_f32_e32 v97, v97
	v_mul_f32_e32 v94, v94, v98
	v_mul_f32_e32 v84, v84, v96
	v_mul_f32_e32 v88, v84, v88
	v_add_f32_e32 v84, 1.0, v97
	v_mul_f32_e32 v96, 0xbfb8aa3b, v86
	v_rcp_f32_e32 v84, v84
	v_exp_f32_e32 v96, v96
	v_mul_f32_e32 v97, 0xbfb8aa3b, v87
	v_exp_f32_e32 v97, v97
	v_mul_f32_e32 v84, v85, v84
	v_add_f32_e32 v85, 1.0, v96
	v_rcp_f32_e32 v85, v85
	v_add_f32_e32 v96, 1.0, v97
	v_rcp_f32_e32 v96, v96
	v_mul_f32_e32 v89, v84, v89
	v_mul_f32_e32 v84, v86, v85
	v_mul_f32_e32 v90, v84, v90
	v_mul_f32_e32 v84, v87, v96
	v_mul_f32_e32 v87, v84, v91
	v_mul_f32_e32 v95, v95, v99
	v_cvt_pk_bf16_f32 v84, v92, v93
	v_cvt_pk_bf16_f32 v85, v94, v95
	v_cvt_pk_bf16_f32 v86, v88, v89
	v_cvt_pk_bf16_f32 v87, v90, v87
	v_mul_f32_e32 v90, 0xbfb8aa3b, v76
	v_exp_f32_e32 v90, v90
	v_mul_f32_e32 v91, 0xbfb8aa3b, v77
	v_exp_f32_e32 v91, v91
	v_or_b32_e32 v88, 32, v0
	v_add_f32_e32 v90, 1.0, v90
	v_rcp_f32_e32 v90, v90
	v_mad_i64_i32 v[88:89], s[18:19], v88, s3, v[2:3]
	v_lshl_add_u64 v[88:89], v[88:89], 0, v[116:117]
	v_add_f32_e32 v91, 1.0, v91
	v_mul_f32_e32 v76, v76, v90
	v_rcp_f32_e32 v91, v91
	flat_store_dwordx4 v[88:89], v[84:87]
	v_mul_f32_e32 v76, v76, v80
	v_mul_f32_e32 v80, 0xbfb8aa3b, v78
	v_mul_f32_e32 v84, 0xbfb8aa3b, v79
	v_exp_f32_e32 v80, v80
	v_exp_f32_e32 v84, v84
	v_mul_f32_e32 v77, v77, v91
	v_mul_f32_e32 v77, v77, v81
	v_add_f32_e32 v80, 1.0, v80
	v_add_f32_e32 v81, 1.0, v84
	v_mul_f32_e32 v84, 0xbfb8aa3b, v64
	v_rcp_f32_e32 v80, v80
	v_exp_f32_e32 v84, v84
	v_rcp_f32_e32 v81, v81
	s_mov_b32 s75, s6
	v_mul_f32_e32 v78, v78, v80
	v_add_f32_e32 v80, 1.0, v84
	v_mul_f32_e32 v79, v79, v81
	v_rcp_f32_e32 v80, v80
	v_mul_f32_e32 v81, 0xbfb8aa3b, v65
	v_exp_f32_e32 v81, v81
	v_mul_f32_e32 v78, v78, v82
	v_mul_f32_e32 v64, v64, v80
	v_mul_f32_e32 v72, v64, v72
	v_add_f32_e32 v64, 1.0, v81
	v_mul_f32_e32 v80, 0xbfb8aa3b, v66
	v_rcp_f32_e32 v64, v64
	v_exp_f32_e32 v80, v80
	v_mul_f32_e32 v81, 0xbfb8aa3b, v67
	v_exp_f32_e32 v81, v81
	v_mul_f32_e32 v64, v65, v64
	v_add_f32_e32 v65, 1.0, v80
	v_rcp_f32_e32 v65, v65
	v_add_f32_e32 v80, 1.0, v81
	v_rcp_f32_e32 v80, v80
	v_mul_f32_e32 v73, v64, v73
	v_mul_f32_e32 v64, v66, v65
	v_mul_f32_e32 v74, v64, v74
	v_mul_f32_e32 v64, v67, v80
	v_mul_f32_e32 v79, v79, v83
	v_mul_f32_e32 v67, v64, v75
	v_cvt_pk_bf16_f32 v64, v76, v77
	v_cvt_pk_bf16_f32 v65, v78, v79
	v_cvt_pk_bf16_f32 v66, v72, v73
	v_or_b32_e32 v72, 48, v0
	v_mad_i64_i32 v[72:73], s[18:19], v72, s3, v[2:3]
	v_lshl_add_u64 v[72:73], v[72:73], 0, v[116:117]
	v_cvt_pk_bf16_f32 v67, v74, v67
	flat_store_dwordx4 v[72:73], v[64:67]
	v_mul_f32_e32 v74, 0xbfb8aa3b, v60
	v_mul_f32_e32 v75, 0xbfb8aa3b, v61
	v_mul_f32_e32 v64, 0xbfb8aa3b, v62
	v_exp_f32_e32 v64, v64
	v_mul_f32_e32 v65, 0xbfb8aa3b, v63
	v_exp_f32_e32 v65, v65
	v_mul_f32_e32 v66, 0xbfb8aa3b, v52
	v_add_f32_e32 v64, 1.0, v64
	v_rcp_f32_e32 v64, v64
	v_add_f32_e32 v65, 1.0, v65
	v_exp_f32_e32 v66, v66
	v_rcp_f32_e32 v65, v65
	v_mul_f32_e32 v62, v62, v64
	v_exp_f32_e32 v74, v74
	v_add_f32_e32 v64, 1.0, v66
	v_mul_f32_e32 v63, v63, v65
	v_rcp_f32_e32 v64, v64
	v_mul_f32_e32 v65, 0xbfb8aa3b, v53
	v_exp_f32_e32 v65, v65
	v_exp_f32_e32 v75, v75
	v_mul_f32_e32 v52, v52, v64
; DEVI unsigned cvtpk(float lo, float hi) { unsigned r; asm volatile("v_cvt_pk_bf16_f32 %0, %1, %2" : "=v"(r) : "v"(lo), "v"(hi)); return r; }
; DEVI float sigmoidf_(float x) { return __builtin_amdgcn_rcpf(1.f + __expf(-x)); }
;     DEVI void operator()(AccRef acc, const pg8::Unit& u, int wr, int wc, int fr, int fq) const {
;     ...
;         for (int ai = 0; ai < 2; ++ai)
; #pragma unroll
;             for (int m = 0; m < 4; ++m) { bf16_t* rowp = Hm + (size_t)(row0 + ai * 128 + m * 16) * DFF + col; float h[8];
; #pragma unroll
;                 for (int j = 0; j < 8; ++j) { const float gt = acc[ai][0][m][j >> 2][j & 3], up = acc[ai][1][m][j >> 2][j & 3]; h[j] = gt * sigmoidf_(gt) * up; }
;                 u32x4 w; w.x = cvtpk(h[0], h[1]); w.y = cvtpk(h[2], h[3]); w.z = cvtpk(h[4], h[5]); w.w = cvtpk(h[6], h[7]);
;                 if (ai == 0 && m == 0) asm volatile("s_waitcnt vmcnt(0)" ::: "memory");
;                 __builtin_nontemporal_store(w, (u32x4*)rowp); }
	v_mul_f32_e32 v56, v52, v56
	v_add_f32_e32 v52, 1.0, v65
	v_mul_f32_e32 v64, 0xbfb8aa3b, v54
	v_rcp_f32_e32 v52, v52
	v_exp_f32_e32 v64, v64
	v_mul_f32_e32 v65, 0xbfb8aa3b, v55
	v_exp_f32_e32 v65, v65
	v_mul_f32_e32 v52, v53, v52
	v_add_f32_e32 v53, 1.0, v64
	v_rcp_f32_e32 v53, v53
	v_add_f32_e32 v64, 1.0, v65
	v_add_f32_e32 v74, 1.0, v74
	v_add_f32_e32 v75, 1.0, v75
	v_rcp_f32_e32 v64, v64
	v_rcp_f32_e32 v74, v74
	v_rcp_f32_e32 v75, v75
	v_mul_f32_e32 v57, v52, v57
	v_mul_f32_e32 v52, v54, v53
	v_mul_f32_e32 v58, v52, v58
	v_mul_f32_e32 v52, v55, v64
	v_mul_f32_e32 v60, v60, v74
	v_mul_f32_e32 v61, v61, v75
	v_mul_f32_e32 v55, v52, v59
	v_mul_f32_e32 v60, v60, v68
	v_mul_f32_e32 v61, v61, v69
	v_mul_f32_e32 v62, v62, v70
	v_mul_f32_e32 v63, v63, v71
	v_cvt_pk_bf16_f32 v52, v60, v61
	v_cvt_pk_bf16_f32 v53, v62, v63
	v_cvt_pk_bf16_f32 v54, v56, v57
	v_cvt_pk_bf16_f32 v55, v58, v55
	v_mul_f32_e32 v58, 0xbfb8aa3b, v44
	v_exp_f32_e32 v58, v58
	v_mul_f32_e32 v59, 0xbfb8aa3b, v45
	v_exp_f32_e32 v59, v59
	v_add_u32_e32 v56, 0x80, v0
	v_add_f32_e32 v58, 1.0, v58
	v_rcp_f32_e32 v58, v58
	v_mad_i64_i32 v[56:57], s[18:19], v56, s3, v[2:3]
	v_lshl_add_u64 v[56:57], v[56:57], 0, v[116:117]
	v_add_f32_e32 v59, 1.0, v59
	v_mul_f32_e32 v44, v44, v58
	v_rcp_f32_e32 v59, v59
	flat_store_dwordx4 v[56:57], v[52:55]
	v_mul_f32_e32 v44, v44, v48
	v_mul_f32_e32 v48, 0xbfb8aa3b, v46
	v_mul_f32_e32 v52, 0xbfb8aa3b, v47
	v_exp_f32_e32 v48, v48
	v_exp_f32_e32 v52, v52
	v_mul_f32_e32 v45, v45, v59
	v_mul_f32_e32 v45, v45, v49
	v_add_f32_e32 v48, 1.0, v48
	v_add_f32_e32 v49, 1.0, v52
	v_mul_f32_e32 v52, 0xbfb8aa3b, v36
	v_rcp_f32_e32 v48, v48
	v_exp_f32_e32 v52, v52
	v_rcp_f32_e32 v49, v49
	s_mov_b32 s10, s8
	v_mul_f32_e32 v46, v46, v48
	v_add_f32_e32 v48, 1.0, v52
	v_mul_f32_e32 v47, v47, v49
	v_rcp_f32_e32 v48, v48
	v_mul_f32_e32 v49, 0xbfb8aa3b, v37
	v_exp_f32_e32 v49, v49
	v_mul_f32_e32 v46, v46, v50
	v_mul_f32_e32 v36, v36, v48
	v_mul_f32_e32 v40, v36, v40
	v_add_f32_e32 v36, 1.0, v49
	v_mul_f32_e32 v48, 0xbfb8aa3b, v38
	v_rcp_f32_e32 v36, v36
	v_exp_f32_e32 v48, v48
	v_mul_f32_e32 v49, 0xbfb8aa3b, v39
	v_exp_f32_e32 v49, v49
	v_mul_f32_e32 v36, v37, v36
	v_add_f32_e32 v37, 1.0, v48
	v_rcp_f32_e32 v37, v37
	v_add_f32_e32 v48, 1.0, v49
	v_rcp_f32_e32 v48, v48
	v_mul_f32_e32 v41, v36, v41
	v_mul_f32_e32 v36, v38, v37
	v_mul_f32_e32 v42, v36, v42
	v_mul_f32_e32 v36, v39, v48
	v_mul_f32_e32 v39, v36, v43
	v_mul_f32_e32 v47, v47, v51
	v_cvt_pk_bf16_f32 v36, v44, v45
	v_cvt_pk_bf16_f32 v37, v46, v47
	v_cvt_pk_bf16_f32 v38, v40, v41
	v_cvt_pk_bf16_f32 v39, v42, v39
	v_mul_f32_e32 v42, 0xbfb8aa3b, v28
	v_exp_f32_e32 v42, v42
	v_mul_f32_e32 v43, 0xbfb8aa3b, v29
	v_exp_f32_e32 v43, v43
	v_add_u32_e32 v40, 0x90, v0
	v_add_f32_e32 v42, 1.0, v42
	v_rcp_f32_e32 v42, v42
	v_mad_i64_i32 v[40:41], s[18:19], v40, s3, v[2:3]
	v_lshl_add_u64 v[40:41], v[40:41], 0, v[116:117]
	v_add_f32_e32 v43, 1.0, v43
	v_mul_f32_e32 v28, v28, v42
	v_rcp_f32_e32 v43, v43
	flat_store_dwordx4 v[40:41], v[36:39]
	v_mul_f32_e32 v28, v28, v32
	v_mul_f32_e32 v32, 0xbfb8aa3b, v30
	v_mul_f32_e32 v36, 0xbfb8aa3b, v31
	v_exp_f32_e32 v32, v32
	v_exp_f32_e32 v36, v36
	v_mul_f32_e32 v29, v29, v43
	v_mul_f32_e32 v29, v29, v33
	v_add_f32_e32 v32, 1.0, v32
	v_add_f32_e32 v33, 1.0, v36
	v_mul_f32_e32 v36, 0xbfb8aa3b, v20
	v_rcp_f32_e32 v32, v32
	v_exp_f32_e32 v36, v36
	v_rcp_f32_e32 v33, v33
	s_mov_b64 s[20:21], s[12:13]
	v_mul_f32_e32 v30, v30, v32
	v_add_f32_e32 v32, 1.0, v36
	v_mul_f32_e32 v31, v31, v33
	v_rcp_f32_e32 v32, v32
	v_mul_f32_e32 v33, 0xbfb8aa3b, v21
	v_exp_f32_e32 v33, v33
	v_mul_f32_e32 v30, v30, v34
	v_mul_f32_e32 v20, v20, v32
	v_mul_f32_e32 v24, v20, v24
	v_add_f32_e32 v20, 1.0, v33
	v_mul_f32_e32 v32, 0xbfb8aa3b, v22
	v_rcp_f32_e32 v20, v20
	v_exp_f32_e32 v32, v32
	v_mul_f32_e32 v33, 0xbfb8aa3b, v23
	v_exp_f32_e32 v33, v33
	v_mul_f32_e32 v20, v21, v20
	v_add_f32_e32 v21, 1.0, v32
	v_rcp_f32_e32 v21, v21
	v_add_f32_e32 v32, 1.0, v33
	v_rcp_f32_e32 v32, v32
	v_mul_f32_e32 v25, v20, v25
	v_mul_f32_e32 v20, v22, v21
	v_mul_f32_e32 v26, v20, v26
	v_mul_f32_e32 v20, v23, v32
	v_mul_f32_e32 v23, v20, v27
	v_mul_f32_e32 v31, v31, v35
	v_cvt_pk_bf16_f32 v20, v28, v29
	v_cvt_pk_bf16_f32 v21, v30, v31
	v_cvt_pk_bf16_f32 v22, v24, v25
	v_cvt_pk_bf16_f32 v23, v26, v23
	v_mul_f32_e32 v26, 0xbfb8aa3b, v12
	v_exp_f32_e32 v26, v26
	v_mul_f32_e32 v27, 0xbfb8aa3b, v13
	v_exp_f32_e32 v27, v27
	v_add_u32_e32 v24, 0xa0, v0
	v_add_f32_e32 v26, 1.0, v26
	v_rcp_f32_e32 v26, v26
	v_mad_i64_i32 v[24:25], s[18:19], v24, s3, v[2:3]
	v_lshl_add_u64 v[24:25], v[24:25], 0, v[116:117]
	v_add_f32_e32 v27, 1.0, v27
	v_mul_f32_e32 v12, v12, v26
	v_rcp_f32_e32 v27, v27
	flat_store_dwordx4 v[24:25], v[20:23]
	v_mul_f32_e32 v12, v12, v16
	v_mul_f32_e32 v16, 0xbfb8aa3b, v14
	v_mul_f32_e32 v20, 0xbfb8aa3b, v15
	v_exp_f32_e32 v16, v16
	v_exp_f32_e32 v20, v20
	v_mul_f32_e32 v13, v13, v27
	v_mul_f32_e32 v13, v13, v17
	v_add_f32_e32 v16, 1.0, v16
	v_add_f32_e32 v17, 1.0, v20
	v_mul_f32_e32 v20, 0xbfb8aa3b, v4
	v_rcp_f32_e32 v16, v16
	v_exp_f32_e32 v20, v20
	v_rcp_f32_e32 v17, v17
	v_add_u32_e32 v0, 0xb0, v0
	v_mul_f32_e32 v14, v14, v16
	v_add_f32_e32 v16, 1.0, v20
	v_mul_f32_e32 v15, v15, v17
	v_rcp_f32_e32 v16, v16
	v_mul_f32_e32 v17, 0xbfb8aa3b, v5
	v_exp_f32_e32 v17, v17
	v_mad_i64_i32 v[2:3], s[18:19], v0, s3, v[2:3]
	v_mul_f32_e32 v4, v4, v16
	v_mul_f32_e32 v8, v4, v8
	v_add_f32_e32 v4, 1.0, v17
	v_mul_f32_e32 v16, 0xbfb8aa3b, v6
	v_rcp_f32_e32 v4, v4
	v_exp_f32_e32 v16, v16
	v_mul_f32_e32 v17, 0xbfb8aa3b, v7
	v_exp_f32_e32 v17, v17
	v_mul_f32_e32 v4, v5, v4
	v_add_f32_e32 v5, 1.0, v16
	v_rcp_f32_e32 v5, v5
	v_add_f32_e32 v16, 1.0, v17
	v_rcp_f32_e32 v16, v16
	v_mul_f32_e32 v9, v4, v9
	v_mul_f32_e32 v4, v6, v5
	v_mul_f32_e32 v10, v4, v10
	v_mul_f32_e32 v4, v7, v16
	v_mul_f32_e32 v7, v4, v11
	v_lshl_add_u64 v[2:3], v[2:3], 0, v[116:117]
	s_mov_b64 s[18:19], s[14:15]
	v_mul_f32_e32 v14, v14, v18
	v_mul_f32_e32 v15, v15, v19
	v_cvt_pk_bf16_f32 v4, v12, v13
	v_cvt_pk_bf16_f32 v5, v14, v15
	v_cvt_pk_bf16_f32 v6, v8, v9
	v_cvt_pk_bf16_f32 v7, v10, v7
	flat_store_dwordx4 v[2:3], v[4:7]
	s_cbranch_vccz .LBB0_522
	s_waitcnt vmcnt(0)
	s_cmpk_gt_u32 s24, 0xff
	s_cbranch_scc1 .LBB0_532
	s_barrier
